# 8-phase GEMM K-loops: first 4 MFMAs of every 32-MFMA block issued before the barrier that opens the block (matrix pipe handed over without waiting for the barrier release)
# baseline (speedup 1.0000x reference)
; #define PG8_STAGE(bufoff, gbase, voff) do { _Pragma("unroll") for (int _i = 0; _i < 2; ++_i) \
;         __builtin_amdgcn_global_load_lds((const unsigned*)((const char*)(gbase) + (voff)[_i]), (PG8_LAS unsigned*)(lds + (bufoff) + ldsw + _i * 8192), 16, 0, 0); } while (0)
; #define PG8_LDA(dst, b, h) do { _Pragma("unroll") for (int m = 0; m < 4; ++m) _Pragma("unroll") for (int k = 0; k < 2; ++k) dst[m][k] = *(const PG8_LAS bf16x8*)(lds + PG8_SA(b, h) + aoff + m * 2048 + k * 1024); } while (0)
; #define PG8_LDB(dst, b, h) do { _Pragma("unroll") for (int n = 0; n < 2; ++n) _Pragma("unroll") for (int k = 0; k < 2; ++k) dst[n][k] = *(const PG8_LAS bf16x8*)(lds + PG8_SB(b, h) + boff + n * 2048 + k * 1024); } while (0)
; #define PG8_MMA(ai, bj, At, Bt) do { __builtin_amdgcn_s_setprio(1); _Pragma("unroll") for (int m = 0; m < 4; ++m) _Pragma("unroll") for (int n = 0; n < 2; ++n) _Pragma("unroll") for (int k = 0; k < 2; ++k) \
;         acc[ai][bj][m][n] = __builtin_amdgcn_mfma_f32_16x16x32_bf16(Bt[n][k], At[m][k], acc[ai][bj][m][n], 0, 0, 0); __builtin_amdgcn_s_setprio(0); } while (0)
; #define PG8_WAIT_V(n) asm volatile("s_waitcnt vmcnt(" #n ")" ::: "memory")
; #define PG8_WAIT_L(n) asm volatile("s_waitcnt lgkmcnt(" #n ")" ::: "memory")
; #define PG8_BAR __builtin_amdgcn_s_barrier()
; #define PG8_SCHED __builtin_amdgcn_sched_barrier(0)
; template <class Epi, class Sched, bool ALIGN_EPI = false, bool SP2 = false>
; __device__ __forceinline__ void gemm_phase(PG8_LAS unsigned char* lds, const Gemm g, const Sched& S, const Epi& E, const int tid) {
;     ...
;             if constexpr (SP2) {
;             PG8_LDB(B0, 0, 0); PG8_LDB(B1, 0, 1); PG8_SCHED; PG8_LDA(At, 0, 0); PG8_STAGE(PG8_SA(1, 1), a1 + hstepA, voffA);
;             PG8_WAIT_V(8); PG8_WAIT_L(0); PG8_BAR; PG8_MMA(0, 0, At, B0); PG8_MMA(0, 1, At, B1); PG8_BAR; PG8_SCHED;
;             PG8_LDA(At, 0, 1); PG8_STAGE(PG8_SB(0, 0), b2, voffB); PG8_STAGE(PG8_SB(0, 1), b2 + hstepB, voffB); PG8_STAGE(PG8_SA(0, 0), a2, voffA);
;             PG8_WAIT_V(8); PG8_WAIT_L(0); PG8_BAR; PG8_MMA(1, 0, At, B0); PG8_MMA(1, 1, At, B1); PG8_BAR; PG8_SCHED;
.LBB0_389:
	s_add_u32 s63, s50, s62
	s_addc_u32 s68, s51, 0
	s_add_u32 s66, s63, 0x100
	s_addc_u32 s67, s68, 0
	s_and_b64 s[64:65], s[58:59], exec
	s_cselect_b32 s65, s43, s67
	s_cselect_b32 s64, s42, s66
	s_add_u32 s62, s48, s62
	s_addc_u32 s66, s49, 0
	s_add_u32 s62, s62, 0x100
	s_addc_u32 s66, s66, 0
	s_and_b64 s[58:59], s[58:59], exec
	s_cselect_b32 s67, s35, s66
	s_cselect_b32 s66, s39, s62
	s_add_u32 s70, s63, 0x40080
	ds_read_b128 v[128:131], v163
	ds_read_b128 v[132:135], v163 offset:1024
	ds_read_b128 v[136:139], v163 offset:2048
	ds_read_b128 v[140:143], v163 offset:3072
	ds_read_b128 v[156:159], v164
	ds_read_b128 v[166:169], v164 offset:1024
	ds_read_b128 v[170:173], v164 offset:2048
	ds_read_b128 v[174:177], v164 offset:3072
	s_addc_u32 s71, s68, 0
	s_add_i32 s83, s60, s3
	s_add_i32 m0, s4, 0xc000
	s_add_i32 s86, s4, 0xe000
	s_add_i32 s80, s83, 0x2000
	s_add_u32 s68, s66, 0x10000
	s_addc_u32 s69, s67, 0
	s_add_i32 s82, s61, s3
	s_add_i32 s81, s82, 0x2000
	s_add_i32 s79, 0, 0x18000
	s_add_i32 s78, 0, 0x1c000
	s_add_u32 s62, s64, 0x40000
	s_addc_u32 s63, s65, 0
	s_add_i32 s77, s79, s3
	s_add_i32 s76, s77, 0x2000
	s_add_u32 s58, s66, 0x10080
	s_addc_u32 s59, s67, 0
	s_add_i32 s85, s78, s3
	s_add_i32 s84, s85, 0x2000
	v_lshl_add_u64 v[206:207], s[70:71], 0, v[144:145]
	ds_read_b128 v[178:181], v165
	ds_read_b128 v[182:185], v165 offset:1024
	ds_read_b128 v[186:189], v165 offset:2048
	ds_read_b128 v[190:193], v165 offset:3072
	ds_read_b128 v[194:197], v165 offset:4096
	ds_read_b128 v[198:201], v165 offset:5120
	ds_read_b128 v[202:205], v165 offset:6144
	ds_read_b128 v[210:213], v165 offset:7168
	global_load_lds_dwordx4 v[206:207], off
	v_lshl_add_u64 v[206:207], s[70:71], 0, v[148:149]
	s_mov_b32 m0, s86
	s_nop 0
	global_load_lds_dwordx4 v[206:207], off
	s_waitcnt vmcnt(8)
	s_waitcnt lgkmcnt(0)
	v_mfma_f32_16x16x32_bf16 v[124:127], v[128:131], v[178:181], v[124:127]
	v_mfma_f32_16x16x32_bf16 v[120:123], v[136:139], v[178:181], v[120:123]
	v_mfma_f32_16x16x32_bf16 v[112:115], v[128:131], v[186:189], v[112:115]
	v_mfma_f32_16x16x32_bf16 v[108:111], v[136:139], v[186:189], v[108:111]
	s_barrier
	s_setprio 1
	s_waitcnt lgkmcnt(0)
	v_mfma_f32_16x16x32_bf16 v[100:103], v[128:131], v[194:197], v[100:103]
	v_mfma_f32_16x16x32_bf16 v[92:95], v[136:139], v[194:197], v[92:95]
	v_mfma_f32_16x16x32_bf16 v[84:87], v[128:131], v[202:205], v[84:87]
	v_mfma_f32_16x16x32_bf16 v[76:79], v[136:139], v[202:205], v[76:79]
	v_mfma_f32_16x16x32_bf16 v[124:127], v[132:135], v[182:185], v[124:127]
	v_mfma_f32_16x16x32_bf16 v[120:123], v[140:143], v[182:185], v[120:123]
	v_mfma_f32_16x16x32_bf16 v[112:115], v[132:135], v[190:193], v[112:115]
	v_mfma_f32_16x16x32_bf16 v[108:111], v[140:143], v[190:193], v[108:111]
	v_mfma_f32_16x16x32_bf16 v[100:103], v[132:135], v[198:201], v[100:103]
	v_mfma_f32_16x16x32_bf16 v[92:95], v[140:143], v[198:201], v[92:95]
	v_mfma_f32_16x16x32_bf16 v[84:87], v[132:135], v[210:213], v[84:87]
	v_mfma_f32_16x16x32_bf16 v[76:79], v[140:143], v[210:213], v[76:79]
	s_setprio 0
	s_setprio 1
	v_mfma_f32_16x16x32_bf16 v[116:119], v[156:159], v[178:181], v[116:119]
	v_mfma_f32_16x16x32_bf16 v[104:107], v[170:173], v[178:181], v[104:107]
	v_mfma_f32_16x16x32_bf16 v[96:99], v[156:159], v[186:189], v[96:99]
	v_mfma_f32_16x16x32_bf16 v[88:91], v[170:173], v[186:189], v[88:91]
	v_mfma_f32_16x16x32_bf16 v[80:83], v[156:159], v[194:197], v[80:83]
	v_mfma_f32_16x16x32_bf16 v[72:75], v[170:173], v[194:197], v[72:75]
	v_mfma_f32_16x16x32_bf16 v[68:71], v[156:159], v[202:205], v[68:71]
	v_mfma_f32_16x16x32_bf16 v[64:67], v[170:173], v[202:205], v[64:67]
	v_mfma_f32_16x16x32_bf16 v[116:119], v[166:169], v[182:185], v[116:119]
	v_mfma_f32_16x16x32_bf16 v[104:107], v[174:177], v[182:185], v[104:107]
	v_mfma_f32_16x16x32_bf16 v[96:99], v[166:169], v[190:193], v[96:99]
	v_mfma_f32_16x16x32_bf16 v[88:91], v[174:177], v[190:193], v[88:91]
	v_mfma_f32_16x16x32_bf16 v[80:83], v[166:169], v[198:201], v[80:83]
	v_mfma_f32_16x16x32_bf16 v[72:75], v[174:177], v[198:201], v[72:75]
	v_mfma_f32_16x16x32_bf16 v[68:71], v[166:169], v[210:213], v[68:71]
	v_mfma_f32_16x16x32_bf16 v[64:67], v[174:177], v[210:213], v[64:67]
	s_setprio 0
	s_barrier
	s_mov_b32 m0, s83
	v_lshl_add_u64 v[206:207], s[66:67], 0, v[146:147]
	ds_read_b128 v[178:181], v165 offset:16384
	ds_read_b128 v[182:185], v165 offset:17408
	ds_read_b128 v[186:189], v165 offset:18432
	ds_read_b128 v[190:193], v165 offset:19456
	ds_read_b128 v[194:197], v165 offset:20480
	ds_read_b128 v[198:201], v165 offset:21504
	ds_read_b128 v[202:205], v165 offset:22528
	ds_read_b128 v[210:213], v165 offset:23552
	global_load_lds_dwordx4 v[206:207], off
	v_lshl_add_u64 v[214:215], s[66:67], 0, v[150:151]
	s_mov_b32 m0, s80
	v_lshl_add_u64 v[216:217], s[68:69], 0, v[146:147]
	global_load_lds_dwordx4 v[214:215], off
	s_mov_b32 m0, s82
	v_lshl_add_u64 v[218:219], s[64:65], 0, v[148:149]
	global_load_lds_dwordx4 v[216:217], off
	v_lshl_add_u64 v[216:217], s[68:69], 0, v[150:151]
	s_mov_b32 m0, s81
	s_nop 0
	global_load_lds_dwordx4 v[216:217], off
	v_lshl_add_u64 v[216:217], s[64:65], 0, v[144:145]
	s_mov_b32 m0, s4
	s_nop 0
	global_load_lds_dwordx4 v[216:217], off
	s_mov_b32 m0, s5
	s_nop 0
	global_load_lds_dwordx4 v[218:219], off
	s_waitcnt vmcnt(8)
	s_waitcnt lgkmcnt(0)
	v_mfma_f32_16x16x32_bf16 v[60:63], v[128:131], v[178:181], v[60:63]
	v_mfma_f32_16x16x32_bf16 v[56:59], v[136:139], v[178:181], v[56:59]
	v_mfma_f32_16x16x32_bf16 v[52:55], v[128:131], v[186:189], v[52:55]
	v_mfma_f32_16x16x32_bf16 v[44:47], v[136:139], v[186:189], v[44:47]
	s_barrier
; #define PG8_STAGE(bufoff, gbase, voff) do { _Pragma("unroll") for (int _i = 0; _i < 2; ++_i) \
;         __builtin_amdgcn_global_load_lds((const unsigned*)((const char*)(gbase) + (voff)[_i]), (PG8_LAS unsigned*)(lds + (bufoff) + ldsw + _i * 8192), 16, 0, 0); } while (0)
; #define PG8_LDA(dst, b, h) do { _Pragma("unroll") for (int m = 0; m < 4; ++m) _Pragma("unroll") for (int k = 0; k < 2; ++k) dst[m][k] = *(const PG8_LAS bf16x8*)(lds + PG8_SA(b, h) + aoff + m * 2048 + k * 1024); } while (0)
; #define PG8_LDB(dst, b, h) do { _Pragma("unroll") for (int n = 0; n < 2; ++n) _Pragma("unroll") for (int k = 0; k < 2; ++k) dst[n][k] = *(const PG8_LAS bf16x8*)(lds + PG8_SB(b, h) + boff + n * 2048 + k * 1024); } while (0)
; #define PG8_MMA(ai, bj, At, Bt) do { __builtin_amdgcn_s_setprio(1); _Pragma("unroll") for (int m = 0; m < 4; ++m) _Pragma("unroll") for (int n = 0; n < 2; ++n) _Pragma("unroll") for (int k = 0; k < 2; ++k) \
;         acc[ai][bj][m][n] = __builtin_amdgcn_mfma_f32_16x16x32_bf16(Bt[n][k], At[m][k], acc[ai][bj][m][n], 0, 0, 0); __builtin_amdgcn_s_setprio(0); } while (0)
; #define PG8_WAIT_V(n) asm volatile("s_waitcnt vmcnt(" #n ")" ::: "memory")
; #define PG8_WAIT_L(n) asm volatile("s_waitcnt lgkmcnt(" #n ")" ::: "memory")
; #define PG8_BAR __builtin_amdgcn_s_barrier()
; #define PG8_SCHED __builtin_amdgcn_sched_barrier(0)
; template <class Epi, class Sched, bool ALIGN_EPI = false, bool SP2 = false>
; __device__ __forceinline__ void gemm_phase(PG8_LAS unsigned char* lds, const Gemm g, const Sched& S, const Epi& E, const int tid) {
;     ...
;             PG8_LDA(At, 0, 1); PG8_STAGE(PG8_SB(0, 0), b2, voffB); PG8_STAGE(PG8_SB(0, 1), b2 + hstepB, voffB); PG8_STAGE(PG8_SA(0, 0), a2, voffA);
;             PG8_WAIT_V(8); PG8_WAIT_L(0); PG8_BAR; PG8_MMA(1, 0, At, B0); PG8_MMA(1, 1, At, B1); PG8_BAR; PG8_SCHED;
;             PG8_LDB(B0, 1, 0); PG8_LDB(B1, 1, 1); PG8_SCHED; PG8_LDA(At, 1, 0); PG8_STAGE(PG8_SA(0, 1), a2 + hstepA, voffA);
;             PG8_WAIT_V(8); PG8_WAIT_L(0); PG8_BAR; PG8_MMA(0, 0, At, B0); PG8_MMA(0, 1, At, B1); PG8_BAR; PG8_SCHED;
	s_setprio 1
	s_waitcnt lgkmcnt(0)
	v_mfma_f32_16x16x32_bf16 v[36:39], v[128:131], v[194:197], v[36:39]
	v_mfma_f32_16x16x32_bf16 v[28:31], v[136:139], v[194:197], v[28:31]
	v_mfma_f32_16x16x32_bf16 v[20:23], v[128:131], v[202:205], v[20:23]
	v_mfma_f32_16x16x32_bf16 v[12:15], v[136:139], v[202:205], v[12:15]
	v_mfma_f32_16x16x32_bf16 v[60:63], v[132:135], v[182:185], v[60:63]
	v_mfma_f32_16x16x32_bf16 v[56:59], v[140:143], v[182:185], v[56:59]
	v_mfma_f32_16x16x32_bf16 v[52:55], v[132:135], v[190:193], v[52:55]
	v_mfma_f32_16x16x32_bf16 v[44:47], v[140:143], v[190:193], v[44:47]
	v_mfma_f32_16x16x32_bf16 v[36:39], v[132:135], v[198:201], v[36:39]
	v_mfma_f32_16x16x32_bf16 v[28:31], v[140:143], v[198:201], v[28:31]
	v_mfma_f32_16x16x32_bf16 v[20:23], v[132:135], v[210:213], v[20:23]
	v_mfma_f32_16x16x32_bf16 v[12:15], v[140:143], v[210:213], v[12:15]
	s_setprio 0
	s_setprio 1
	v_mfma_f32_16x16x32_bf16 v[48:51], v[156:159], v[178:181], v[48:51]
	v_mfma_f32_16x16x32_bf16 v[40:43], v[170:173], v[178:181], v[40:43]
	v_mfma_f32_16x16x32_bf16 v[32:35], v[156:159], v[186:189], v[32:35]
	v_mfma_f32_16x16x32_bf16 v[24:27], v[170:173], v[186:189], v[24:27]
	v_mfma_f32_16x16x32_bf16 v[16:19], v[156:159], v[194:197], v[16:19]
	v_mfma_f32_16x16x32_bf16 v[8:11], v[170:173], v[194:197], v[8:11]
	v_mfma_f32_16x16x32_bf16 v[4:7], v[156:159], v[202:205], v[4:7]
	v_mfma_f32_16x16x32_bf16 v[0:3], v[170:173], v[202:205], v[0:3]
	v_mfma_f32_16x16x32_bf16 v[48:51], v[166:169], v[182:185], v[48:51]
	v_mfma_f32_16x16x32_bf16 v[40:43], v[174:177], v[182:185], v[40:43]
	v_mfma_f32_16x16x32_bf16 v[32:35], v[166:169], v[190:193], v[32:35]
	v_mfma_f32_16x16x32_bf16 v[24:27], v[174:177], v[190:193], v[24:27]
	v_mfma_f32_16x16x32_bf16 v[16:19], v[166:169], v[198:201], v[16:19]
	v_mfma_f32_16x16x32_bf16 v[8:11], v[174:177], v[198:201], v[8:11]
	v_mfma_f32_16x16x32_bf16 v[4:7], v[166:169], v[210:213], v[4:7]
	v_mfma_f32_16x16x32_bf16 v[0:3], v[174:177], v[210:213], v[0:3]
	s_setprio 0
	s_barrier
	v_add_u32_e32 v140, s79, v161
	v_add_u32_e32 v174, s78, v161
	ds_read_b128 v[128:131], v140
	ds_read_b128 v[132:135], v140 offset:1024
	ds_read_b128 v[136:139], v140 offset:2048
	ds_read_b128 v[140:143], v140 offset:3072
	ds_read_b128 v[156:159], v174
	ds_read_b128 v[166:169], v174 offset:1024
	ds_read_b128 v[170:173], v174 offset:2048
	ds_read_b128 v[174:177], v174 offset:3072
	s_mov_b32 m0, s33
	v_lshl_add_u64 v[220:221], s[62:63], 0, v[144:145]
	ds_read_b128 v[178:181], v165 offset:32768
	ds_read_b128 v[182:185], v165 offset:33792
	ds_read_b128 v[186:189], v165 offset:34816
	ds_read_b128 v[190:193], v165 offset:35840
	ds_read_b128 v[194:197], v165 offset:36864
	ds_read_b128 v[198:201], v165 offset:37888
	ds_read_b128 v[202:205], v165 offset:38912
	ds_read_b128 v[210:213], v165 offset:39936
	global_load_lds_dwordx4 v[220:221], off
	v_lshl_add_u64 v[220:221], s[62:63], 0, v[148:149]
	s_mov_b32 m0, s36
	s_nop 0
	global_load_lds_dwordx4 v[220:221], off
	s_waitcnt vmcnt(8)
	s_waitcnt lgkmcnt(0)
	v_mfma_f32_16x16x32_bf16 v[124:127], v[128:131], v[178:181], v[124:127]
	v_mfma_f32_16x16x32_bf16 v[120:123], v[136:139], v[178:181], v[120:123]
	v_mfma_f32_16x16x32_bf16 v[112:115], v[128:131], v[186:189], v[112:115]
	v_mfma_f32_16x16x32_bf16 v[108:111], v[136:139], v[186:189], v[108:111]
	s_barrier
	s_setprio 1
	s_waitcnt lgkmcnt(0)
	v_mfma_f32_16x16x32_bf16 v[100:103], v[128:131], v[194:197], v[100:103]
	v_mfma_f32_16x16x32_bf16 v[92:95], v[136:139], v[194:197], v[92:95]
	v_mfma_f32_16x16x32_bf16 v[84:87], v[128:131], v[202:205], v[84:87]
	v_mfma_f32_16x16x32_bf16 v[76:79], v[136:139], v[202:205], v[76:79]
	v_mfma_f32_16x16x32_bf16 v[124:127], v[132:135], v[182:185], v[124:127]
	v_mfma_f32_16x16x32_bf16 v[120:123], v[140:143], v[182:185], v[120:123]
	v_mfma_f32_16x16x32_bf16 v[112:115], v[132:135], v[190:193], v[112:115]
	v_mfma_f32_16x16x32_bf16 v[108:111], v[140:143], v[190:193], v[108:111]
	v_mfma_f32_16x16x32_bf16 v[100:103], v[132:135], v[198:201], v[100:103]
	v_mfma_f32_16x16x32_bf16 v[92:95], v[140:143], v[198:201], v[92:95]
	v_mfma_f32_16x16x32_bf16 v[84:87], v[132:135], v[210:213], v[84:87]
	v_mfma_f32_16x16x32_bf16 v[76:79], v[140:143], v[210:213], v[76:79]
	s_setprio 0
	s_setprio 1
	v_mfma_f32_16x16x32_bf16 v[116:119], v[156:159], v[178:181], v[116:119]
	v_mfma_f32_16x16x32_bf16 v[104:107], v[170:173], v[178:181], v[104:107]
	v_mfma_f32_16x16x32_bf16 v[96:99], v[156:159], v[186:189], v[96:99]
	v_mfma_f32_16x16x32_bf16 v[88:91], v[170:173], v[186:189], v[88:91]
	v_mfma_f32_16x16x32_bf16 v[80:83], v[156:159], v[194:197], v[80:83]
	v_mfma_f32_16x16x32_bf16 v[72:75], v[170:173], v[194:197], v[72:75]
	v_mfma_f32_16x16x32_bf16 v[68:71], v[156:159], v[202:205], v[68:71]
	v_mfma_f32_16x16x32_bf16 v[64:67], v[170:173], v[202:205], v[64:67]
	v_mfma_f32_16x16x32_bf16 v[116:119], v[166:169], v[182:185], v[116:119]
	v_mfma_f32_16x16x32_bf16 v[104:107], v[174:177], v[182:185], v[104:107]
	v_mfma_f32_16x16x32_bf16 v[96:99], v[166:169], v[190:193], v[96:99]
	v_mfma_f32_16x16x32_bf16 v[88:91], v[174:177], v[190:193], v[88:91]
	v_mfma_f32_16x16x32_bf16 v[80:83], v[166:169], v[198:201], v[80:83]
	v_mfma_f32_16x16x32_bf16 v[72:75], v[174:177], v[198:201], v[72:75]
	v_mfma_f32_16x16x32_bf16 v[68:71], v[166:169], v[210:213], v[68:71]
	v_mfma_f32_16x16x32_bf16 v[64:67], v[174:177], v[210:213], v[64:67]
	s_setprio 0
	s_barrier
; #define PG8_STAGE(bufoff, gbase, voff) do { _Pragma("unroll") for (int _i = 0; _i < 2; ++_i) \
;         __builtin_amdgcn_global_load_lds((const unsigned*)((const char*)(gbase) + (voff)[_i]), (PG8_LAS unsigned*)(lds + (bufoff) + ldsw + _i * 8192), 16, 0, 0); } while (0)
; #define PG8_LDA(dst, b, h) do { _Pragma("unroll") for (int m = 0; m < 4; ++m) _Pragma("unroll") for (int k = 0; k < 2; ++k) dst[m][k] = *(const PG8_LAS bf16x8*)(lds + PG8_SA(b, h) + aoff + m * 2048 + k * 1024); } while (0)
; #define PG8_MMA(ai, bj, At, Bt) do { __builtin_amdgcn_s_setprio(1); _Pragma("unroll") for (int m = 0; m < 4; ++m) _Pragma("unroll") for (int n = 0; n < 2; ++n) _Pragma("unroll") for (int k = 0; k < 2; ++k) \
;         acc[ai][bj][m][n] = __builtin_amdgcn_mfma_f32_16x16x32_bf16(Bt[n][k], At[m][k], acc[ai][bj][m][n], 0, 0, 0); __builtin_amdgcn_s_setprio(0); } while (0)
; #define PG8_WAIT_V(n) asm volatile("s_waitcnt vmcnt(" #n ")" ::: "memory")
; #define PG8_WAIT_L(n) asm volatile("s_waitcnt lgkmcnt(" #n ")" ::: "memory")
; #define PG8_BAR __builtin_amdgcn_s_barrier()
; #define PG8_SCHED __builtin_amdgcn_sched_barrier(0)
; template <class Epi, class Sched, bool ALIGN_EPI = false, bool SP2 = false>
; __device__ __forceinline__ void gemm_phase(PG8_LAS unsigned char* lds, const Gemm g, const Sched& S, const Epi& E, const int tid) {
;     ...
;             PG8_LDA(At, 1, 1); PG8_STAGE(PG8_SB(1, 0), b3, voffB); PG8_STAGE(PG8_SB(1, 1), b3 + hstepB, voffB); PG8_STAGE(PG8_SA(1, 0), a3, voffA);
;             PG8_WAIT_V(8); PG8_WAIT_L(0); PG8_BAR; PG8_MMA(1, 0, At, B0); PG8_MMA(1, 1, At, B1); PG8_BAR; PG8_SCHED;
;     ...
;         if constexpr (ALIGN_EPI) { if (wr == 0) PG8_BAR; }
	s_mov_b32 m0, s77
	v_lshl_add_u64 v[206:207], v[206:207], 0, s[20:21]
	ds_read_b128 v[178:181], v165 offset:49152
	ds_read_b128 v[182:185], v165 offset:50176
	ds_read_b128 v[186:189], v165 offset:51200
	ds_read_b128 v[190:193], v165 offset:52224
	ds_read_b128 v[194:197], v165 offset:53248
	ds_read_b128 v[198:201], v165 offset:54272
	ds_read_b128 v[202:205], v165 offset:55296
	ds_read_b128 v[210:213], v165 offset:56320
	global_load_lds_dwordx4 v[206:207], off
	v_lshl_add_u64 v[206:207], v[214:215], 0, s[20:21]
	s_mov_b32 m0, s76
	s_nop 0
	global_load_lds_dwordx4 v[206:207], off
	v_lshl_add_u64 v[206:207], s[58:59], 0, v[146:147]
	s_mov_b32 m0, s85
	s_nop 0
	global_load_lds_dwordx4 v[206:207], off
	v_lshl_add_u64 v[206:207], s[58:59], 0, v[150:151]
	s_mov_b32 m0, s84
	s_nop 0
	global_load_lds_dwordx4 v[206:207], off
	v_lshl_add_u64 v[206:207], v[216:217], 0, s[20:21]
	s_mov_b32 m0, s41
	s_nop 0
	global_load_lds_dwordx4 v[206:207], off
	v_lshl_add_u64 v[206:207], v[218:219], 0, s[20:21]
	s_mov_b32 m0, s47
	s_nop 0
	global_load_lds_dwordx4 v[206:207], off
	s_waitcnt vmcnt(8)
	s_waitcnt lgkmcnt(0)
	v_mfma_f32_16x16x32_bf16 v[60:63], v[128:131], v[178:181], v[60:63]
	v_mfma_f32_16x16x32_bf16 v[56:59], v[136:139], v[178:181], v[56:59]
	v_mfma_f32_16x16x32_bf16 v[52:55], v[128:131], v[186:189], v[52:55]
	v_mfma_f32_16x16x32_bf16 v[44:47], v[136:139], v[186:189], v[44:47]
	s_barrier
	s_setprio 1
	s_waitcnt lgkmcnt(0)
	v_mfma_f32_16x16x32_bf16 v[36:39], v[128:131], v[194:197], v[36:39]
	v_mfma_f32_16x16x32_bf16 v[28:31], v[136:139], v[194:197], v[28:31]
	v_mfma_f32_16x16x32_bf16 v[20:23], v[128:131], v[202:205], v[20:23]
	v_mfma_f32_16x16x32_bf16 v[12:15], v[136:139], v[202:205], v[12:15]
	v_mfma_f32_16x16x32_bf16 v[60:63], v[132:135], v[182:185], v[60:63]
	v_mfma_f32_16x16x32_bf16 v[56:59], v[140:143], v[182:185], v[56:59]
	v_mfma_f32_16x16x32_bf16 v[52:55], v[132:135], v[190:193], v[52:55]
	v_mfma_f32_16x16x32_bf16 v[44:47], v[140:143], v[190:193], v[44:47]
	v_mfma_f32_16x16x32_bf16 v[36:39], v[132:135], v[198:201], v[36:39]
	v_mfma_f32_16x16x32_bf16 v[28:31], v[140:143], v[198:201], v[28:31]
	v_mfma_f32_16x16x32_bf16 v[20:23], v[132:135], v[210:213], v[20:23]
	v_mfma_f32_16x16x32_bf16 v[12:15], v[140:143], v[210:213], v[12:15]
	s_setprio 0
	s_setprio 1
	v_mfma_f32_16x16x32_bf16 v[48:51], v[156:159], v[178:181], v[48:51]
	v_mfma_f32_16x16x32_bf16 v[40:43], v[170:173], v[178:181], v[40:43]
	v_mfma_f32_16x16x32_bf16 v[32:35], v[156:159], v[186:189], v[32:35]
	v_mfma_f32_16x16x32_bf16 v[24:27], v[170:173], v[186:189], v[24:27]
	v_mfma_f32_16x16x32_bf16 v[16:19], v[156:159], v[194:197], v[16:19]
	v_mfma_f32_16x16x32_bf16 v[8:11], v[170:173], v[194:197], v[8:11]
	v_mfma_f32_16x16x32_bf16 v[4:7], v[156:159], v[202:205], v[4:7]
	v_mfma_f32_16x16x32_bf16 v[0:3], v[170:173], v[202:205], v[0:3]
	v_mfma_f32_16x16x32_bf16 v[48:51], v[166:169], v[182:185], v[48:51]
	v_mfma_f32_16x16x32_bf16 v[40:43], v[174:177], v[182:185], v[40:43]
	v_mfma_f32_16x16x32_bf16 v[32:35], v[166:169], v[190:193], v[32:35]
	v_mfma_f32_16x16x32_bf16 v[24:27], v[174:177], v[190:193], v[24:27]
	v_mfma_f32_16x16x32_bf16 v[16:19], v[166:169], v[198:201], v[16:19]
	v_mfma_f32_16x16x32_bf16 v[8:11], v[174:177], v[198:201], v[8:11]
	v_mfma_f32_16x16x32_bf16 v[4:7], v[166:169], v[210:213], v[4:7]
	v_mfma_f32_16x16x32_bf16 v[0:3], v[174:177], v[210:213], v[0:3]
	s_setprio 0
	s_barrier
	s_movk_i32 s62, 0x100
	s_andn2_b64 vcc, exec, s[10:11]
	s_mov_b64 s[58:59], -1
	s_mov_b64 s[10:11], 0
	s_cbranch_vccz .LBB0_389
	s_and_b64 vcc, exec, s[22:23]
	s_cbranch_vccz .LBB0_392
	s_barrier

; #define PG8_STAGE(bufoff, gbase, voff) do { _Pragma("unroll") for (int _i = 0; _i < 2; ++_i) \
;         __builtin_amdgcn_global_load_lds((const unsigned*)((const char*)(gbase) + (voff)[_i]), (PG8_LAS unsigned*)(lds + (bufoff) + ldsw + _i * 8192), 16, 0, 0); } while (0)
; #define PG8_LDA(dst, b, h) do { _Pragma("unroll") for (int m = 0; m < 4; ++m) _Pragma("unroll") for (int k = 0; k < 2; ++k) dst[m][k] = *(const PG8_LAS bf16x8*)(lds + PG8_SA(b, h) + aoff + m * 2048 + k * 1024); } while (0)
; #define PG8_LDB(dst, b, h) do { _Pragma("unroll") for (int n = 0; n < 2; ++n) _Pragma("unroll") for (int k = 0; k < 2; ++k) dst[n][k] = *(const PG8_LAS bf16x8*)(lds + PG8_SB(b, h) + boff + n * 2048 + k * 1024); } while (0)
; #define PG8_MMA(ai, bj, At, Bt) do { __builtin_amdgcn_s_setprio(1); _Pragma("unroll") for (int m = 0; m < 4; ++m) _Pragma("unroll") for (int n = 0; n < 2; ++n) _Pragma("unroll") for (int k = 0; k < 2; ++k) \
;         acc[ai][bj][m][n] = __builtin_amdgcn_mfma_f32_16x16x32_bf16(Bt[n][k], At[m][k], acc[ai][bj][m][n], 0, 0, 0); __builtin_amdgcn_s_setprio(0); } while (0)
; #define PG8_WAIT_V(n) asm volatile("s_waitcnt vmcnt(" #n ")" ::: "memory")
; #define PG8_WAIT_L(n) asm volatile("s_waitcnt lgkmcnt(" #n ")" ::: "memory")
; #define PG8_BAR __builtin_amdgcn_s_barrier()
; #define PG8_SCHED __builtin_amdgcn_sched_barrier(0)
; template <class Epi, class Sched, bool ALIGN_EPI = false, bool SP2 = false>
; __device__ __forceinline__ void gemm_phase(PG8_LAS unsigned char* lds, const Gemm g, const Sched& S, const Epi& E, const int tid) {
;     ...
;             if constexpr (SP2) {
;             PG8_LDB(B0, 0, 0); PG8_LDB(B1, 0, 1); PG8_SCHED; PG8_LDA(At, 0, 0); PG8_STAGE(PG8_SA(1, 1), a1 + hstepA, voffA);
;             PG8_WAIT_V(8); PG8_WAIT_L(0); PG8_BAR; PG8_MMA(0, 0, At, B0); PG8_MMA(0, 1, At, B1); PG8_BAR; PG8_SCHED;
;             PG8_LDA(At, 0, 1); PG8_STAGE(PG8_SB(0, 0), b2, voffB); PG8_STAGE(PG8_SB(0, 1), b2 + hstepB, voffB); PG8_STAGE(PG8_SA(0, 0), a2, voffA);
;             PG8_WAIT_V(8); PG8_WAIT_L(0); PG8_BAR; PG8_MMA(1, 0, At, B0); PG8_MMA(1, 1, At, B1); PG8_BAR; PG8_SCHED;
.LBB0_550:
	ds_read_b128 v[92:95], v217
	ds_read_b128 v[96:99], v217 offset:1024
	ds_read_b128 v[100:103], v217 offset:2048
	ds_read_b128 v[104:107], v217 offset:3072
	ds_read_b128 v[108:111], v218
	ds_read_b128 v[112:115], v218 offset:1024
	ds_read_b128 v[116:119], v218 offset:2048
	ds_read_b128 v[120:123], v218 offset:3072
	s_add_u32 s22, s10, 0xfffc0080
	s_addc_u32 s23, s11, -1
	s_cmp_eq_u32 s87, 12
	s_cselect_b32 s35, s7, s23
	s_cselect_b32 s34, s58, s22
	s_cselect_b32 s23, s59, s79
	s_cselect_b32 s22, s73, s78
	v_lshl_add_u64 v[224:225], s[10:11], 0, v[190:191]
	s_add_i32 m0, s43, 0xc000
	ds_read_b128 v[160:163], v219
	ds_read_b128 v[164:167], v219 offset:1024
	ds_read_b128 v[168:171], v219 offset:2048
	ds_read_b128 v[172:175], v219 offset:3072
	ds_read_b128 v[176:179], v219 offset:4096
	ds_read_b128 v[196:199], v219 offset:5120
	ds_read_b128 v[200:203], v219 offset:6144
	ds_read_b128 v[204:207], v219 offset:7168
	global_load_lds_dwordx4 v[224:225], off
	v_lshl_add_u64 v[224:225], s[10:11], 0, v[188:189]
	s_add_i32 m0, s43, 0xe000
	s_nop 0
	global_load_lds_dwordx4 v[224:225], off
	s_waitcnt vmcnt(8)
	s_waitcnt lgkmcnt(0)
	v_mfma_f32_16x16x32_bf16 v[156:159], v[92:95], v[160:163], v[156:159]
	v_mfma_f32_16x16x32_bf16 v[68:71], v[100:103], v[160:163], v[68:71]
	v_mfma_f32_16x16x32_bf16 v[148:151], v[92:95], v[168:171], v[148:151]
	v_mfma_f32_16x16x32_bf16 v[60:63], v[100:103], v[168:171], v[60:63]
	s_barrier
	s_setprio 1
	s_waitcnt lgkmcnt(0)
	v_mfma_f32_16x16x32_bf16 v[140:143], v[92:95], v[176:179], v[140:143]
	v_mfma_f32_16x16x32_bf16 v[52:55], v[100:103], v[176:179], v[52:55]
	v_mfma_f32_16x16x32_bf16 v[132:135], v[92:95], v[200:203], v[132:135]
	v_mfma_f32_16x16x32_bf16 v[44:47], v[100:103], v[200:203], v[44:47]
	v_mfma_f32_16x16x32_bf16 v[156:159], v[96:99], v[164:167], v[156:159]
	v_mfma_f32_16x16x32_bf16 v[68:71], v[104:107], v[164:167], v[68:71]
	v_mfma_f32_16x16x32_bf16 v[148:151], v[96:99], v[172:175], v[148:151]
	v_mfma_f32_16x16x32_bf16 v[60:63], v[104:107], v[172:175], v[60:63]
	v_mfma_f32_16x16x32_bf16 v[140:143], v[96:99], v[196:199], v[140:143]
	v_mfma_f32_16x16x32_bf16 v[52:55], v[104:107], v[196:199], v[52:55]
	v_mfma_f32_16x16x32_bf16 v[132:135], v[96:99], v[204:207], v[132:135]
	v_mfma_f32_16x16x32_bf16 v[44:47], v[104:107], v[204:207], v[44:47]
	s_setprio 0
	s_setprio 1
	v_mfma_f32_16x16x32_bf16 v[152:155], v[108:111], v[160:163], v[152:155]
	v_mfma_f32_16x16x32_bf16 v[64:67], v[116:119], v[160:163], v[64:67]
	v_mfma_f32_16x16x32_bf16 v[144:147], v[108:111], v[168:171], v[144:147]
	v_mfma_f32_16x16x32_bf16 v[56:59], v[116:119], v[168:171], v[56:59]
	v_mfma_f32_16x16x32_bf16 v[136:139], v[108:111], v[176:179], v[136:139]
	v_mfma_f32_16x16x32_bf16 v[48:51], v[116:119], v[176:179], v[48:51]
	v_mfma_f32_16x16x32_bf16 v[128:131], v[108:111], v[200:203], v[128:131]
	v_mfma_f32_16x16x32_bf16 v[40:43], v[116:119], v[200:203], v[40:43]
	v_mfma_f32_16x16x32_bf16 v[152:155], v[112:115], v[164:167], v[152:155]
	v_mfma_f32_16x16x32_bf16 v[64:67], v[120:123], v[164:167], v[64:67]
	v_mfma_f32_16x16x32_bf16 v[144:147], v[112:115], v[172:175], v[144:147]
	v_mfma_f32_16x16x32_bf16 v[56:59], v[120:123], v[172:175], v[56:59]
	v_mfma_f32_16x16x32_bf16 v[136:139], v[112:115], v[196:199], v[136:139]
	v_mfma_f32_16x16x32_bf16 v[48:51], v[120:123], v[196:199], v[48:51]
	v_mfma_f32_16x16x32_bf16 v[128:131], v[112:115], v[204:207], v[128:131]
	v_mfma_f32_16x16x32_bf16 v[40:43], v[120:123], v[204:207], v[40:43]
	s_setprio 0
	s_barrier
	s_add_i32 s89, s80, s33
	v_lshl_add_u64 v[224:225], s[22:23], 0, v[182:183]
	s_mov_b32 m0, s89
	ds_read_b128 v[160:163], v219 offset:16384
	ds_read_b128 v[164:167], v219 offset:17408
	ds_read_b128 v[168:171], v219 offset:18432
	ds_read_b128 v[172:175], v219 offset:19456
	ds_read_b128 v[176:179], v219 offset:20480
	ds_read_b128 v[196:199], v219 offset:21504
	ds_read_b128 v[200:203], v219 offset:22528
	ds_read_b128 v[204:207], v219 offset:23552
	global_load_lds_dwordx4 v[224:225], off
	s_add_i32 m0, s89, 0x2000
	s_add_u32 s96, s22, 0x40000
	v_lshl_add_u64 v[226:227], s[22:23], 0, v[186:187]
	s_addc_u32 s97, s23, 0
	s_add_i32 s89, s81, s33
	global_load_lds_dwordx4 v[226:227], off
	v_lshl_add_u64 v[228:229], s[96:97], 0, v[182:183]
	s_mov_b32 m0, s89
	v_lshl_add_u64 v[230:231], s[34:35], 0, v[184:185]
	global_load_lds_dwordx4 v[228:229], off
	v_lshl_add_u64 v[228:229], s[96:97], 0, v[186:187]
	s_add_i32 m0, s89, 0x2000
	s_nop 0
	global_load_lds_dwordx4 v[228:229], off
	v_lshl_add_u64 v[228:229], s[34:35], 0, v[180:181]
	s_mov_b32 m0, s43
	s_nop 0
	global_load_lds_dwordx4 v[228:229], off
	s_mov_b32 m0, s53
	s_nop 0
	global_load_lds_dwordx4 v[230:231], off
	s_waitcnt vmcnt(8)
	s_waitcnt lgkmcnt(0)
	v_mfma_f32_16x16x32_bf16 v[124:127], v[92:95], v[160:163], v[124:127]
	v_mfma_f32_16x16x32_bf16 v[36:39], v[100:103], v[160:163], v[36:39]
	v_mfma_f32_16x16x32_bf16 v[84:87], v[92:95], v[168:171], v[84:87]
	v_mfma_f32_16x16x32_bf16 v[28:31], v[100:103], v[168:171], v[28:31]
	s_barrier
; #define PG8_STAGE(bufoff, gbase, voff) do { _Pragma("unroll") for (int _i = 0; _i < 2; ++_i) \
;         __builtin_amdgcn_global_load_lds((const unsigned*)((const char*)(gbase) + (voff)[_i]), (PG8_LAS unsigned*)(lds + (bufoff) + ldsw + _i * 8192), 16, 0, 0); } while (0)
; #define PG8_LDA(dst, b, h) do { _Pragma("unroll") for (int m = 0; m < 4; ++m) _Pragma("unroll") for (int k = 0; k < 2; ++k) dst[m][k] = *(const PG8_LAS bf16x8*)(lds + PG8_SA(b, h) + aoff + m * 2048 + k * 1024); } while (0)
; #define PG8_LDB(dst, b, h) do { _Pragma("unroll") for (int n = 0; n < 2; ++n) _Pragma("unroll") for (int k = 0; k < 2; ++k) dst[n][k] = *(const PG8_LAS bf16x8*)(lds + PG8_SB(b, h) + boff + n * 2048 + k * 1024); } while (0)
; #define PG8_MMA(ai, bj, At, Bt) do { __builtin_amdgcn_s_setprio(1); _Pragma("unroll") for (int m = 0; m < 4; ++m) _Pragma("unroll") for (int n = 0; n < 2; ++n) _Pragma("unroll") for (int k = 0; k < 2; ++k) \
;         acc[ai][bj][m][n] = __builtin_amdgcn_mfma_f32_16x16x32_bf16(Bt[n][k], At[m][k], acc[ai][bj][m][n], 0, 0, 0); __builtin_amdgcn_s_setprio(0); } while (0)
; #define PG8_WAIT_V(n) asm volatile("s_waitcnt vmcnt(" #n ")" ::: "memory")
; #define PG8_WAIT_L(n) asm volatile("s_waitcnt lgkmcnt(" #n ")" ::: "memory")
; #define PG8_BAR __builtin_amdgcn_s_barrier()
; #define PG8_SCHED __builtin_amdgcn_sched_barrier(0)
; template <class Epi, class Sched, bool ALIGN_EPI = false, bool SP2 = false>
; __device__ __forceinline__ void gemm_phase(PG8_LAS unsigned char* lds, const Gemm g, const Sched& S, const Epi& E, const int tid) {
;     ...
;             PG8_WAIT_V(8); PG8_WAIT_L(0); PG8_BAR; PG8_MMA(1, 0, At, B0); PG8_MMA(1, 1, At, B1); PG8_BAR; PG8_SCHED;
;             PG8_LDB(B0, 1, 0); PG8_LDB(B1, 1, 1); PG8_SCHED; PG8_LDA(At, 1, 0); PG8_STAGE(PG8_SA(0, 1), a2 + hstepA, voffA);
;             PG8_WAIT_V(8); PG8_WAIT_L(0); PG8_BAR; PG8_MMA(0, 0, At, B0); PG8_MMA(0, 1, At, B1); PG8_BAR; PG8_SCHED;
	s_setprio 1
	s_waitcnt lgkmcnt(0)
	v_mfma_f32_16x16x32_bf16 v[76:79], v[92:95], v[176:179], v[76:79]
	v_mfma_f32_16x16x32_bf16 v[20:23], v[100:103], v[176:179], v[20:23]
	v_mfma_f32_16x16x32_bf16 v[12:15], v[92:95], v[200:203], v[12:15]
	v_mfma_f32_16x16x32_bf16 v[8:11], v[100:103], v[200:203], v[8:11]
	v_mfma_f32_16x16x32_bf16 v[124:127], v[96:99], v[164:167], v[124:127]
	v_mfma_f32_16x16x32_bf16 v[36:39], v[104:107], v[164:167], v[36:39]
	v_mfma_f32_16x16x32_bf16 v[84:87], v[96:99], v[172:175], v[84:87]
	v_mfma_f32_16x16x32_bf16 v[28:31], v[104:107], v[172:175], v[28:31]
	v_mfma_f32_16x16x32_bf16 v[76:79], v[96:99], v[196:199], v[76:79]
	v_mfma_f32_16x16x32_bf16 v[20:23], v[104:107], v[196:199], v[20:23]
	v_mfma_f32_16x16x32_bf16 v[12:15], v[96:99], v[204:207], v[12:15]
	v_mfma_f32_16x16x32_bf16 v[8:11], v[104:107], v[204:207], v[8:11]
	s_setprio 0
	s_setprio 1
	v_mfma_f32_16x16x32_bf16 v[88:91], v[108:111], v[160:163], v[88:91]
	v_mfma_f32_16x16x32_bf16 v[32:35], v[116:119], v[160:163], v[32:35]
	v_mfma_f32_16x16x32_bf16 v[80:83], v[108:111], v[168:171], v[80:83]
	v_mfma_f32_16x16x32_bf16 v[24:27], v[116:119], v[168:171], v[24:27]
	v_mfma_f32_16x16x32_bf16 v[72:75], v[108:111], v[176:179], v[72:75]
	v_mfma_f32_16x16x32_bf16 v[16:19], v[116:119], v[176:179], v[16:19]
	v_mfma_f32_16x16x32_bf16 v[4:7], v[108:111], v[200:203], v[4:7]
	v_mfma_f32_16x16x32_bf16 v[0:3], v[116:119], v[200:203], v[0:3]
	v_mfma_f32_16x16x32_bf16 v[88:91], v[112:115], v[164:167], v[88:91]
	v_mfma_f32_16x16x32_bf16 v[32:35], v[120:123], v[164:167], v[32:35]
	v_mfma_f32_16x16x32_bf16 v[80:83], v[112:115], v[172:175], v[80:83]
	v_mfma_f32_16x16x32_bf16 v[24:27], v[120:123], v[172:175], v[24:27]
	v_mfma_f32_16x16x32_bf16 v[72:75], v[112:115], v[196:199], v[72:75]
	v_mfma_f32_16x16x32_bf16 v[16:19], v[120:123], v[196:199], v[16:19]
	v_mfma_f32_16x16x32_bf16 v[4:7], v[112:115], v[204:207], v[4:7]
	v_mfma_f32_16x16x32_bf16 v[0:3], v[120:123], v[204:207], v[0:3]
	s_setprio 0
	s_barrier
	s_add_i32 s89, 0, 0x18000
	s_add_i32 s96, 0, 0x1c000
	v_add_u32_e32 v104, s89, v213
	v_add_u32_e32 v120, s96, v213
	ds_read_b128 v[92:95], v104
	ds_read_b128 v[96:99], v104 offset:1024
	ds_read_b128 v[100:103], v104 offset:2048
	ds_read_b128 v[104:107], v104 offset:3072
	ds_read_b128 v[108:111], v120
	ds_read_b128 v[112:115], v120 offset:1024
	ds_read_b128 v[116:119], v120 offset:2048
	ds_read_b128 v[120:123], v120 offset:3072
	s_add_u32 s34, s34, 0x40000
	s_addc_u32 s35, s35, 0
	s_mov_b32 m0, s57
	v_lshl_add_u64 v[232:233], s[34:35], 0, v[180:181]
	ds_read_b128 v[160:163], v219 offset:32768
	ds_read_b128 v[164:167], v219 offset:33792
	ds_read_b128 v[168:171], v219 offset:34816
	ds_read_b128 v[172:175], v219 offset:35840
	ds_read_b128 v[176:179], v219 offset:36864
	ds_read_b128 v[196:199], v219 offset:37888
	ds_read_b128 v[200:203], v219 offset:38912
	ds_read_b128 v[204:207], v219 offset:39936
	global_load_lds_dwordx4 v[232:233], off
	v_lshl_add_u64 v[232:233], s[34:35], 0, v[184:185]
	s_mov_b32 m0, s60
	s_nop 0
	global_load_lds_dwordx4 v[232:233], off
	s_waitcnt vmcnt(8)
	s_waitcnt lgkmcnt(0)
	v_mfma_f32_16x16x32_bf16 v[156:159], v[92:95], v[160:163], v[156:159]
	v_mfma_f32_16x16x32_bf16 v[68:71], v[100:103], v[160:163], v[68:71]
	v_mfma_f32_16x16x32_bf16 v[148:151], v[92:95], v[168:171], v[148:151]
	v_mfma_f32_16x16x32_bf16 v[60:63], v[100:103], v[168:171], v[60:63]
	s_barrier
	s_setprio 1
	s_waitcnt lgkmcnt(0)
	v_mfma_f32_16x16x32_bf16 v[140:143], v[92:95], v[176:179], v[140:143]
	v_mfma_f32_16x16x32_bf16 v[52:55], v[100:103], v[176:179], v[52:55]
	v_mfma_f32_16x16x32_bf16 v[132:135], v[92:95], v[200:203], v[132:135]
	v_mfma_f32_16x16x32_bf16 v[44:47], v[100:103], v[200:203], v[44:47]
	v_mfma_f32_16x16x32_bf16 v[156:159], v[96:99], v[164:167], v[156:159]
	v_mfma_f32_16x16x32_bf16 v[68:71], v[104:107], v[164:167], v[68:71]
	v_mfma_f32_16x16x32_bf16 v[148:151], v[96:99], v[172:175], v[148:151]
	v_mfma_f32_16x16x32_bf16 v[60:63], v[104:107], v[172:175], v[60:63]
	v_mfma_f32_16x16x32_bf16 v[140:143], v[96:99], v[196:199], v[140:143]
	v_mfma_f32_16x16x32_bf16 v[52:55], v[104:107], v[196:199], v[52:55]
	v_mfma_f32_16x16x32_bf16 v[132:135], v[96:99], v[204:207], v[132:135]
	v_mfma_f32_16x16x32_bf16 v[44:47], v[104:107], v[204:207], v[44:47]
	s_setprio 0
	s_setprio 1
	v_mfma_f32_16x16x32_bf16 v[152:155], v[108:111], v[160:163], v[152:155]
	v_mfma_f32_16x16x32_bf16 v[64:67], v[116:119], v[160:163], v[64:67]
	v_mfma_f32_16x16x32_bf16 v[144:147], v[108:111], v[168:171], v[144:147]
	v_mfma_f32_16x16x32_bf16 v[56:59], v[116:119], v[168:171], v[56:59]
	v_mfma_f32_16x16x32_bf16 v[136:139], v[108:111], v[176:179], v[136:139]
	v_mfma_f32_16x16x32_bf16 v[48:51], v[116:119], v[176:179], v[48:51]
	v_mfma_f32_16x16x32_bf16 v[128:131], v[108:111], v[200:203], v[128:131]
	v_mfma_f32_16x16x32_bf16 v[40:43], v[116:119], v[200:203], v[40:43]
	v_mfma_f32_16x16x32_bf16 v[152:155], v[112:115], v[164:167], v[152:155]
	v_mfma_f32_16x16x32_bf16 v[64:67], v[120:123], v[164:167], v[64:67]
	v_mfma_f32_16x16x32_bf16 v[144:147], v[112:115], v[172:175], v[144:147]
	v_mfma_f32_16x16x32_bf16 v[56:59], v[120:123], v[172:175], v[56:59]
	v_mfma_f32_16x16x32_bf16 v[136:139], v[112:115], v[196:199], v[136:139]
	v_mfma_f32_16x16x32_bf16 v[48:51], v[120:123], v[196:199], v[48:51]
	v_mfma_f32_16x16x32_bf16 v[128:131], v[112:115], v[204:207], v[128:131]
	v_mfma_f32_16x16x32_bf16 v[40:43], v[120:123], v[204:207], v[40:43]
	s_setprio 0
	s_barrier
; #define PG8_STAGE(bufoff, gbase, voff) do { _Pragma("unroll") for (int _i = 0; _i < 2; ++_i) \
;         __builtin_amdgcn_global_load_lds((const unsigned*)((const char*)(gbase) + (voff)[_i]), (PG8_LAS unsigned*)(lds + (bufoff) + ldsw + _i * 8192), 16, 0, 0); } while (0)
; #define PG8_LDA(dst, b, h) do { _Pragma("unroll") for (int m = 0; m < 4; ++m) _Pragma("unroll") for (int k = 0; k < 2; ++k) dst[m][k] = *(const PG8_LAS bf16x8*)(lds + PG8_SA(b, h) + aoff + m * 2048 + k * 1024); } while (0)
; #define PG8_MMA(ai, bj, At, Bt) do { __builtin_amdgcn_s_setprio(1); _Pragma("unroll") for (int m = 0; m < 4; ++m) _Pragma("unroll") for (int n = 0; n < 2; ++n) _Pragma("unroll") for (int k = 0; k < 2; ++k) \
;         acc[ai][bj][m][n] = __builtin_amdgcn_mfma_f32_16x16x32_bf16(Bt[n][k], At[m][k], acc[ai][bj][m][n], 0, 0, 0); __builtin_amdgcn_s_setprio(0); } while (0)
; #define PG8_WAIT_V(n) asm volatile("s_waitcnt vmcnt(" #n ")" ::: "memory")
; #define PG8_WAIT_L(n) asm volatile("s_waitcnt lgkmcnt(" #n ")" ::: "memory")
; #define PG8_BAR __builtin_amdgcn_s_barrier()
; #define PG8_SCHED __builtin_amdgcn_sched_barrier(0)
; template <class Epi, class Sched, bool ALIGN_EPI = false, bool SP2 = false>
; __device__ __forceinline__ void gemm_phase(PG8_LAS unsigned char* lds, const Gemm g, const Sched& S, const Epi& E, const int tid) {
;     ...
;             PG8_LDA(At, 1, 1); PG8_STAGE(PG8_SB(1, 0), b3, voffB); PG8_STAGE(PG8_SB(1, 1), b3 + hstepB, voffB); PG8_STAGE(PG8_SA(1, 0), a3, voffA);
;             PG8_WAIT_V(8); PG8_WAIT_L(0); PG8_BAR; PG8_MMA(1, 0, At, B0); PG8_MMA(1, 1, At, B1); PG8_BAR; PG8_SCHED;
;     ...
;         if constexpr (ALIGN_EPI) { if (wr == 0) PG8_BAR; }
	s_add_i32 s34, s89, s33
	v_lshl_add_u64 v[224:225], v[224:225], 0, s[64:65]
	s_mov_b32 m0, s34
	ds_read_b128 v[160:163], v219 offset:49152
	ds_read_b128 v[164:167], v219 offset:50176
	ds_read_b128 v[168:171], v219 offset:51200
	ds_read_b128 v[172:175], v219 offset:52224
	ds_read_b128 v[176:179], v219 offset:53248
	ds_read_b128 v[196:199], v219 offset:54272
	ds_read_b128 v[200:203], v219 offset:55296
	ds_read_b128 v[204:207], v219 offset:56320
	global_load_lds_dwordx4 v[224:225], off
	s_add_i32 m0, s34, 0x2000
	s_add_u32 s22, s22, 0x40080
	v_lshl_add_u64 v[224:225], v[226:227], 0, s[64:65]
	s_addc_u32 s23, s23, 0
	s_add_i32 s34, s96, s33
	global_load_lds_dwordx4 v[224:225], off
	v_lshl_add_u64 v[224:225], s[22:23], 0, v[182:183]
	s_mov_b32 m0, s34
	s_nop 0
	global_load_lds_dwordx4 v[224:225], off
	v_lshl_add_u64 v[224:225], s[22:23], 0, v[186:187]
	s_add_i32 m0, s34, 0x2000
	s_nop 0
	global_load_lds_dwordx4 v[224:225], off
	v_lshl_add_u64 v[224:225], v[228:229], 0, s[64:65]
	s_mov_b32 m0, s61
	s_nop 0
	global_load_lds_dwordx4 v[224:225], off
	v_lshl_add_u64 v[224:225], v[230:231], 0, s[64:65]
	s_mov_b32 m0, s83
	s_nop 0
	global_load_lds_dwordx4 v[224:225], off
	s_waitcnt vmcnt(8)
	s_waitcnt lgkmcnt(0)
	v_mfma_f32_16x16x32_bf16 v[124:127], v[92:95], v[160:163], v[124:127]
	v_mfma_f32_16x16x32_bf16 v[36:39], v[100:103], v[160:163], v[36:39]
	v_mfma_f32_16x16x32_bf16 v[84:87], v[92:95], v[168:171], v[84:87]
	v_mfma_f32_16x16x32_bf16 v[28:31], v[100:103], v[168:171], v[28:31]
	s_barrier
	s_setprio 1
	s_waitcnt lgkmcnt(0)
	v_mfma_f32_16x16x32_bf16 v[76:79], v[92:95], v[176:179], v[76:79]
	v_mfma_f32_16x16x32_bf16 v[20:23], v[100:103], v[176:179], v[20:23]
	v_mfma_f32_16x16x32_bf16 v[12:15], v[92:95], v[200:203], v[12:15]
	v_mfma_f32_16x16x32_bf16 v[8:11], v[100:103], v[200:203], v[8:11]
	v_mfma_f32_16x16x32_bf16 v[124:127], v[96:99], v[164:167], v[124:127]
	v_mfma_f32_16x16x32_bf16 v[36:39], v[104:107], v[164:167], v[36:39]
	v_mfma_f32_16x16x32_bf16 v[84:87], v[96:99], v[172:175], v[84:87]
	v_mfma_f32_16x16x32_bf16 v[28:31], v[104:107], v[172:175], v[28:31]
	v_mfma_f32_16x16x32_bf16 v[76:79], v[96:99], v[196:199], v[76:79]
	v_mfma_f32_16x16x32_bf16 v[20:23], v[104:107], v[196:199], v[20:23]
	v_mfma_f32_16x16x32_bf16 v[12:15], v[96:99], v[204:207], v[12:15]
	v_mfma_f32_16x16x32_bf16 v[8:11], v[104:107], v[204:207], v[8:11]
	s_setprio 0
	s_setprio 1
	v_mfma_f32_16x16x32_bf16 v[88:91], v[108:111], v[160:163], v[88:91]
	v_mfma_f32_16x16x32_bf16 v[32:35], v[116:119], v[160:163], v[32:35]
	v_mfma_f32_16x16x32_bf16 v[80:83], v[108:111], v[168:171], v[80:83]
	v_mfma_f32_16x16x32_bf16 v[24:27], v[116:119], v[168:171], v[24:27]
	v_mfma_f32_16x16x32_bf16 v[72:75], v[108:111], v[176:179], v[72:75]
	v_mfma_f32_16x16x32_bf16 v[16:19], v[116:119], v[176:179], v[16:19]
	v_mfma_f32_16x16x32_bf16 v[4:7], v[108:111], v[200:203], v[4:7]
	v_mfma_f32_16x16x32_bf16 v[0:3], v[116:119], v[200:203], v[0:3]
	v_mfma_f32_16x16x32_bf16 v[88:91], v[112:115], v[164:167], v[88:91]
	v_mfma_f32_16x16x32_bf16 v[32:35], v[120:123], v[164:167], v[32:35]
	v_mfma_f32_16x16x32_bf16 v[80:83], v[112:115], v[172:175], v[80:83]
	v_mfma_f32_16x16x32_bf16 v[24:27], v[120:123], v[172:175], v[24:27]
	v_mfma_f32_16x16x32_bf16 v[72:75], v[112:115], v[196:199], v[72:75]
	v_mfma_f32_16x16x32_bf16 v[16:19], v[120:123], v[196:199], v[16:19]
	v_mfma_f32_16x16x32_bf16 v[4:7], v[112:115], v[204:207], v[4:7]
	v_mfma_f32_16x16x32_bf16 v[0:3], v[120:123], v[204:207], v[0:3]
	s_setprio 0
	s_barrier
	s_add_i32 s87, s87, 2
	s_add_u32 s78, s78, 0x100
	s_addc_u32 s79, s79, 0
	s_add_u32 s10, s10, 0x100
	s_addc_u32 s11, s11, 0
	s_cmp_gt_u32 s87, 13
	s_cbranch_scc0 .LBB0_550
	s_and_b64 vcc, exec, s[66:67]
	s_cbranch_vccz .LBB0_553
	s_barrier

; #define PG8_STAGE(bufoff, gbase, voff) do { _Pragma("unroll") for (int _i = 0; _i < 2; ++_i) \
;         __builtin_amdgcn_global_load_lds((const unsigned*)((const char*)(gbase) + (voff)[_i]), (PG8_LAS unsigned*)(lds + (bufoff) + ldsw + _i * 8192), 16, 0, 0); } while (0)
; #define PG8_LDA(dst, b, h) do { _Pragma("unroll") for (int m = 0; m < 4; ++m) _Pragma("unroll") for (int k = 0; k < 2; ++k) dst[m][k] = *(const PG8_LAS bf16x8*)(lds + PG8_SA(b, h) + aoff + m * 2048 + k * 1024); } while (0)
; #define PG8_LDB(dst, b, h) do { _Pragma("unroll") for (int n = 0; n < 2; ++n) _Pragma("unroll") for (int k = 0; k < 2; ++k) dst[n][k] = *(const PG8_LAS bf16x8*)(lds + PG8_SB(b, h) + boff + n * 2048 + k * 1024); } while (0)
; #define PG8_MMA(ai, bj, At, Bt) do { __builtin_amdgcn_s_setprio(1); _Pragma("unroll") for (int m = 0; m < 4; ++m) _Pragma("unroll") for (int n = 0; n < 2; ++n) _Pragma("unroll") for (int k = 0; k < 2; ++k) \
;         acc[ai][bj][m][n] = __builtin_amdgcn_mfma_f32_16x16x32_bf16(Bt[n][k], At[m][k], acc[ai][bj][m][n], 0, 0, 0); __builtin_amdgcn_s_setprio(0); } while (0)
; #define PG8_WAIT_V(n) asm volatile("s_waitcnt vmcnt(" #n ")" ::: "memory")
; #define PG8_WAIT_L(n) asm volatile("s_waitcnt lgkmcnt(" #n ")" ::: "memory")
; #define PG8_BAR __builtin_amdgcn_s_barrier()
; #define PG8_SCHED __builtin_amdgcn_sched_barrier(0)
; template <class Epi, class Sched, bool ALIGN_EPI = false, bool SP2 = false>
; __device__ __forceinline__ void gemm_phase(PG8_LAS unsigned char* lds, const Gemm g, const Sched& S, const Epi& E, const int tid) {
;     ...
;             if constexpr (SP2) {
;             PG8_LDB(B0, 0, 0); PG8_LDB(B1, 0, 1); PG8_SCHED; PG8_LDA(At, 0, 0); PG8_STAGE(PG8_SA(1, 1), a1 + hstepA, voffA);
;             PG8_WAIT_V(8); PG8_WAIT_L(0); PG8_BAR; PG8_MMA(0, 0, At, B0); PG8_MMA(0, 1, At, B1); PG8_BAR; PG8_SCHED;
;             PG8_LDA(At, 0, 1); PG8_STAGE(PG8_SB(0, 0), b2, voffB); PG8_STAGE(PG8_SB(0, 1), b2 + hstepB, voffB); PG8_STAGE(PG8_SA(0, 0), a2, voffA);
;             PG8_WAIT_V(8); PG8_WAIT_L(0); PG8_BAR; PG8_MMA(1, 0, At, B0); PG8_MMA(1, 1, At, B1); PG8_BAR; PG8_SCHED;
.LBB0_914:
	ds_read_b128 v[150:153], v147
	ds_read_b128 v[154:157], v147 offset:1024
	ds_read_b128 v[158:161], v147 offset:2048
	ds_read_b128 v[162:165], v147 offset:3072
	ds_read_b128 v[166:169], v148
	ds_read_b128 v[170:173], v148 offset:1024
	ds_read_b128 v[174:177], v148 offset:2048
	ds_read_b128 v[178:181], v148 offset:3072
	s_add_u32 s30, s28, 0x100
	s_addc_u32 s31, s29, 0
	s_cmp_eq_u32 s62, 40
	s_cselect_b32 s37, s15, s31
	s_cselect_b32 s36, s14, s30
	s_cselect_b32 s35, s27, s61
	s_cselect_b32 s34, s26, s60
	v_lshl_add_u64 v[206:207], s[28:29], 0, v[138:139]
	s_add_i32 m0, s38, 0xc000
	ds_read_b128 v[182:185], v149
	ds_read_b128 v[186:189], v149 offset:1024
	ds_read_b128 v[190:193], v149 offset:2048
	ds_read_b128 v[194:197], v149 offset:3072
	ds_read_b128 v[198:201], v149 offset:4096
	ds_read_b128 v[202:205], v149 offset:5120
	ds_read_b128 v[210:213], v149 offset:6144
	ds_read_b128 v[214:217], v149 offset:7168
	global_load_lds_dwordx4 v[206:207], off
	v_lshl_add_u64 v[206:207], s[28:29], 0, v[136:137]
	s_add_i32 m0, s38, 0xe000
	s_nop 0
	global_load_lds_dwordx4 v[206:207], off
	s_waitcnt vmcnt(8)
	s_waitcnt lgkmcnt(0)
	v_mfma_f32_16x16x32_bf16 v[124:127], v[150:153], v[182:185], v[124:127]
	v_mfma_f32_16x16x32_bf16 v[120:123], v[158:161], v[182:185], v[120:123]
	v_mfma_f32_16x16x32_bf16 v[116:119], v[150:153], v[190:193], v[116:119]
	v_mfma_f32_16x16x32_bf16 v[112:115], v[158:161], v[190:193], v[112:115]
	s_barrier
	s_setprio 1
	s_waitcnt lgkmcnt(0)
	v_mfma_f32_16x16x32_bf16 v[100:103], v[150:153], v[198:201], v[100:103]
	v_mfma_f32_16x16x32_bf16 v[96:99], v[158:161], v[198:201], v[96:99]
	v_mfma_f32_16x16x32_bf16 v[84:87], v[150:153], v[210:213], v[84:87]
	v_mfma_f32_16x16x32_bf16 v[80:83], v[158:161], v[210:213], v[80:83]
	v_mfma_f32_16x16x32_bf16 v[124:127], v[154:157], v[186:189], v[124:127]
	v_mfma_f32_16x16x32_bf16 v[120:123], v[162:165], v[186:189], v[120:123]
	v_mfma_f32_16x16x32_bf16 v[116:119], v[154:157], v[194:197], v[116:119]
	v_mfma_f32_16x16x32_bf16 v[112:115], v[162:165], v[194:197], v[112:115]
	v_mfma_f32_16x16x32_bf16 v[100:103], v[154:157], v[202:205], v[100:103]
	v_mfma_f32_16x16x32_bf16 v[96:99], v[162:165], v[202:205], v[96:99]
	v_mfma_f32_16x16x32_bf16 v[84:87], v[154:157], v[214:217], v[84:87]
	v_mfma_f32_16x16x32_bf16 v[80:83], v[162:165], v[214:217], v[80:83]
	s_setprio 0
	s_setprio 1
	v_mfma_f32_16x16x32_bf16 v[108:111], v[166:169], v[182:185], v[108:111]
	v_mfma_f32_16x16x32_bf16 v[104:107], v[174:177], v[182:185], v[104:107]
	v_mfma_f32_16x16x32_bf16 v[92:95], v[166:169], v[190:193], v[92:95]
	v_mfma_f32_16x16x32_bf16 v[88:91], v[174:177], v[190:193], v[88:91]
	v_mfma_f32_16x16x32_bf16 v[76:79], v[166:169], v[198:201], v[76:79]
	v_mfma_f32_16x16x32_bf16 v[72:75], v[174:177], v[198:201], v[72:75]
	v_mfma_f32_16x16x32_bf16 v[68:71], v[166:169], v[210:213], v[68:71]
	v_mfma_f32_16x16x32_bf16 v[64:67], v[174:177], v[210:213], v[64:67]
	v_mfma_f32_16x16x32_bf16 v[108:111], v[170:173], v[186:189], v[108:111]
	v_mfma_f32_16x16x32_bf16 v[104:107], v[178:181], v[186:189], v[104:107]
	v_mfma_f32_16x16x32_bf16 v[92:95], v[170:173], v[194:197], v[92:95]
	v_mfma_f32_16x16x32_bf16 v[88:91], v[178:181], v[194:197], v[88:91]
	v_mfma_f32_16x16x32_bf16 v[76:79], v[170:173], v[202:205], v[76:79]
	v_mfma_f32_16x16x32_bf16 v[72:75], v[178:181], v[202:205], v[72:75]
	v_mfma_f32_16x16x32_bf16 v[68:71], v[170:173], v[214:217], v[68:71]
	v_mfma_f32_16x16x32_bf16 v[64:67], v[178:181], v[214:217], v[64:67]
	s_setprio 0
	s_barrier
	s_add_i32 s28, s46, s33
	v_lshl_add_u64 v[206:207], s[34:35], 0, v[130:131]
	s_mov_b32 m0, s28
	ds_read_b128 v[182:185], v149 offset:16384
	ds_read_b128 v[186:189], v149 offset:17408
	ds_read_b128 v[190:193], v149 offset:18432
	ds_read_b128 v[194:197], v149 offset:19456
	ds_read_b128 v[198:201], v149 offset:20480
	ds_read_b128 v[202:205], v149 offset:21504
	ds_read_b128 v[210:213], v149 offset:22528
	ds_read_b128 v[214:217], v149 offset:23552
	global_load_lds_dwordx4 v[206:207], off
	s_add_i32 m0, s28, 0x2000
	s_add_u32 s28, s34, 0xb0000
	v_lshl_add_u64 v[218:219], s[34:35], 0, v[134:135]
	s_addc_u32 s29, s35, 0
	s_add_i32 s63, s47, s33
	global_load_lds_dwordx4 v[218:219], off
	v_lshl_add_u64 v[220:221], s[28:29], 0, v[130:131]
	s_mov_b32 m0, s63
	v_lshl_add_u64 v[222:223], s[36:37], 0, v[132:133]
	global_load_lds_dwordx4 v[220:221], off
	v_lshl_add_u64 v[220:221], s[28:29], 0, v[134:135]
	s_add_i32 m0, s63, 0x2000
	s_nop 0
	global_load_lds_dwordx4 v[220:221], off
	v_lshl_add_u64 v[220:221], s[36:37], 0, v[128:129]
	s_mov_b32 m0, s38
	s_nop 0
	global_load_lds_dwordx4 v[220:221], off
	s_mov_b32 m0, s39
	s_nop 0
	global_load_lds_dwordx4 v[222:223], off
	s_waitcnt vmcnt(8)
	s_waitcnt lgkmcnt(0)
	v_mfma_f32_16x16x32_bf16 v[60:63], v[150:153], v[182:185], v[60:63]
	v_mfma_f32_16x16x32_bf16 v[56:59], v[158:161], v[182:185], v[56:59]
	v_mfma_f32_16x16x32_bf16 v[52:55], v[150:153], v[190:193], v[52:55]
	v_mfma_f32_16x16x32_bf16 v[48:51], v[158:161], v[190:193], v[48:51]
	s_barrier
; #define PG8_STAGE(bufoff, gbase, voff) do { _Pragma("unroll") for (int _i = 0; _i < 2; ++_i) \
;         __builtin_amdgcn_global_load_lds((const unsigned*)((const char*)(gbase) + (voff)[_i]), (PG8_LAS unsigned*)(lds + (bufoff) + ldsw + _i * 8192), 16, 0, 0); } while (0)
; #define PG8_LDA(dst, b, h) do { _Pragma("unroll") for (int m = 0; m < 4; ++m) _Pragma("unroll") for (int k = 0; k < 2; ++k) dst[m][k] = *(const PG8_LAS bf16x8*)(lds + PG8_SA(b, h) + aoff + m * 2048 + k * 1024); } while (0)
; #define PG8_LDB(dst, b, h) do { _Pragma("unroll") for (int n = 0; n < 2; ++n) _Pragma("unroll") for (int k = 0; k < 2; ++k) dst[n][k] = *(const PG8_LAS bf16x8*)(lds + PG8_SB(b, h) + boff + n * 2048 + k * 1024); } while (0)
; #define PG8_MMA(ai, bj, At, Bt) do { __builtin_amdgcn_s_setprio(1); _Pragma("unroll") for (int m = 0; m < 4; ++m) _Pragma("unroll") for (int n = 0; n < 2; ++n) _Pragma("unroll") for (int k = 0; k < 2; ++k) \
;         acc[ai][bj][m][n] = __builtin_amdgcn_mfma_f32_16x16x32_bf16(Bt[n][k], At[m][k], acc[ai][bj][m][n], 0, 0, 0); __builtin_amdgcn_s_setprio(0); } while (0)
; #define PG8_WAIT_V(n) asm volatile("s_waitcnt vmcnt(" #n ")" ::: "memory")
; #define PG8_WAIT_L(n) asm volatile("s_waitcnt lgkmcnt(" #n ")" ::: "memory")
; #define PG8_BAR __builtin_amdgcn_s_barrier()
; #define PG8_SCHED __builtin_amdgcn_sched_barrier(0)
; template <class Epi, class Sched, bool ALIGN_EPI = false, bool SP2 = false>
; __device__ __forceinline__ void gemm_phase(PG8_LAS unsigned char* lds, const Gemm g, const Sched& S, const Epi& E, const int tid) {
;     ...
;             PG8_WAIT_V(8); PG8_WAIT_L(0); PG8_BAR; PG8_MMA(1, 0, At, B0); PG8_MMA(1, 1, At, B1); PG8_BAR; PG8_SCHED;
;             PG8_LDB(B0, 1, 0); PG8_LDB(B1, 1, 1); PG8_SCHED; PG8_LDA(At, 1, 0); PG8_STAGE(PG8_SA(0, 1), a2 + hstepA, voffA);
;             PG8_WAIT_V(8); PG8_WAIT_L(0); PG8_BAR; PG8_MMA(0, 0, At, B0); PG8_MMA(0, 1, At, B1); PG8_BAR; PG8_SCHED;
	s_setprio 1
	s_waitcnt lgkmcnt(0)
	v_mfma_f32_16x16x32_bf16 v[36:39], v[150:153], v[198:201], v[36:39]
	v_mfma_f32_16x16x32_bf16 v[32:35], v[158:161], v[198:201], v[32:35]
	v_mfma_f32_16x16x32_bf16 v[20:23], v[150:153], v[210:213], v[20:23]
	v_mfma_f32_16x16x32_bf16 v[16:19], v[158:161], v[210:213], v[16:19]
	v_mfma_f32_16x16x32_bf16 v[60:63], v[154:157], v[186:189], v[60:63]
	v_mfma_f32_16x16x32_bf16 v[56:59], v[162:165], v[186:189], v[56:59]
	v_mfma_f32_16x16x32_bf16 v[52:55], v[154:157], v[194:197], v[52:55]
	v_mfma_f32_16x16x32_bf16 v[48:51], v[162:165], v[194:197], v[48:51]
	v_mfma_f32_16x16x32_bf16 v[36:39], v[154:157], v[202:205], v[36:39]
	v_mfma_f32_16x16x32_bf16 v[32:35], v[162:165], v[202:205], v[32:35]
	v_mfma_f32_16x16x32_bf16 v[20:23], v[154:157], v[214:217], v[20:23]
	v_mfma_f32_16x16x32_bf16 v[16:19], v[162:165], v[214:217], v[16:19]
	s_setprio 0
	s_setprio 1
	v_mfma_f32_16x16x32_bf16 v[44:47], v[166:169], v[182:185], v[44:47]
	v_mfma_f32_16x16x32_bf16 v[40:43], v[174:177], v[182:185], v[40:43]
	v_mfma_f32_16x16x32_bf16 v[28:31], v[166:169], v[190:193], v[28:31]
	v_mfma_f32_16x16x32_bf16 v[24:27], v[174:177], v[190:193], v[24:27]
	v_mfma_f32_16x16x32_bf16 v[12:15], v[166:169], v[198:201], v[12:15]
	v_mfma_f32_16x16x32_bf16 v[8:11], v[174:177], v[198:201], v[8:11]
	v_mfma_f32_16x16x32_bf16 v[4:7], v[166:169], v[210:213], v[4:7]
	v_mfma_f32_16x16x32_bf16 v[0:3], v[174:177], v[210:213], v[0:3]
	v_mfma_f32_16x16x32_bf16 v[44:47], v[170:173], v[186:189], v[44:47]
	v_mfma_f32_16x16x32_bf16 v[40:43], v[178:181], v[186:189], v[40:43]
	v_mfma_f32_16x16x32_bf16 v[28:31], v[170:173], v[194:197], v[28:31]
	v_mfma_f32_16x16x32_bf16 v[24:27], v[178:181], v[194:197], v[24:27]
	v_mfma_f32_16x16x32_bf16 v[12:15], v[170:173], v[202:205], v[12:15]
	v_mfma_f32_16x16x32_bf16 v[8:11], v[178:181], v[202:205], v[8:11]
	v_mfma_f32_16x16x32_bf16 v[4:7], v[170:173], v[214:217], v[4:7]
	v_mfma_f32_16x16x32_bf16 v[0:3], v[178:181], v[214:217], v[0:3]
	s_setprio 0
	s_barrier
	s_add_i32 s63, 0, 0x18000
	s_add_i32 s64, 0, 0x1c000
	v_add_u32_e32 v162, s63, v145
	v_add_u32_e32 v178, s64, v145
	ds_read_b128 v[150:153], v162
	ds_read_b128 v[154:157], v162 offset:1024
	ds_read_b128 v[158:161], v162 offset:2048
	ds_read_b128 v[162:165], v162 offset:3072
	ds_read_b128 v[166:169], v178
	ds_read_b128 v[170:173], v178 offset:1024
	ds_read_b128 v[174:177], v178 offset:2048
	ds_read_b128 v[178:181], v178 offset:3072
	s_add_u32 s28, s36, 0xb0000
	s_addc_u32 s29, s37, 0
	s_mov_b32 m0, s40
	v_lshl_add_u64 v[224:225], s[28:29], 0, v[128:129]
	ds_read_b128 v[182:185], v149 offset:32768
	ds_read_b128 v[186:189], v149 offset:33792
	ds_read_b128 v[190:193], v149 offset:34816
	ds_read_b128 v[194:197], v149 offset:35840
	ds_read_b128 v[198:201], v149 offset:36864
	ds_read_b128 v[202:205], v149 offset:37888
	ds_read_b128 v[210:213], v149 offset:38912
	ds_read_b128 v[214:217], v149 offset:39936
	global_load_lds_dwordx4 v[224:225], off
	v_lshl_add_u64 v[224:225], s[28:29], 0, v[132:133]
	s_mov_b32 m0, s41
	s_nop 0
	global_load_lds_dwordx4 v[224:225], off
	s_waitcnt vmcnt(8)
	s_waitcnt lgkmcnt(0)
	v_mfma_f32_16x16x32_bf16 v[124:127], v[150:153], v[182:185], v[124:127]
	v_mfma_f32_16x16x32_bf16 v[120:123], v[158:161], v[182:185], v[120:123]
	v_mfma_f32_16x16x32_bf16 v[116:119], v[150:153], v[190:193], v[116:119]
	v_mfma_f32_16x16x32_bf16 v[112:115], v[158:161], v[190:193], v[112:115]
	s_barrier
	s_setprio 1
	s_waitcnt lgkmcnt(0)
	v_mfma_f32_16x16x32_bf16 v[100:103], v[150:153], v[198:201], v[100:103]
	v_mfma_f32_16x16x32_bf16 v[96:99], v[158:161], v[198:201], v[96:99]
	v_mfma_f32_16x16x32_bf16 v[84:87], v[150:153], v[210:213], v[84:87]
	v_mfma_f32_16x16x32_bf16 v[80:83], v[158:161], v[210:213], v[80:83]
	v_mfma_f32_16x16x32_bf16 v[124:127], v[154:157], v[186:189], v[124:127]
	v_mfma_f32_16x16x32_bf16 v[120:123], v[162:165], v[186:189], v[120:123]
	v_mfma_f32_16x16x32_bf16 v[116:119], v[154:157], v[194:197], v[116:119]
	v_mfma_f32_16x16x32_bf16 v[112:115], v[162:165], v[194:197], v[112:115]
	v_mfma_f32_16x16x32_bf16 v[100:103], v[154:157], v[202:205], v[100:103]
	v_mfma_f32_16x16x32_bf16 v[96:99], v[162:165], v[202:205], v[96:99]
	v_mfma_f32_16x16x32_bf16 v[84:87], v[154:157], v[214:217], v[84:87]
	v_mfma_f32_16x16x32_bf16 v[80:83], v[162:165], v[214:217], v[80:83]
	s_setprio 0
	s_setprio 1
	v_mfma_f32_16x16x32_bf16 v[108:111], v[166:169], v[182:185], v[108:111]
	v_mfma_f32_16x16x32_bf16 v[104:107], v[174:177], v[182:185], v[104:107]
	v_mfma_f32_16x16x32_bf16 v[92:95], v[166:169], v[190:193], v[92:95]
	v_mfma_f32_16x16x32_bf16 v[88:91], v[174:177], v[190:193], v[88:91]
	v_mfma_f32_16x16x32_bf16 v[76:79], v[166:169], v[198:201], v[76:79]
	v_mfma_f32_16x16x32_bf16 v[72:75], v[174:177], v[198:201], v[72:75]
	v_mfma_f32_16x16x32_bf16 v[68:71], v[166:169], v[210:213], v[68:71]
	v_mfma_f32_16x16x32_bf16 v[64:67], v[174:177], v[210:213], v[64:67]
	v_mfma_f32_16x16x32_bf16 v[108:111], v[170:173], v[186:189], v[108:111]
	v_mfma_f32_16x16x32_bf16 v[104:107], v[178:181], v[186:189], v[104:107]
	v_mfma_f32_16x16x32_bf16 v[92:95], v[170:173], v[194:197], v[92:95]
	v_mfma_f32_16x16x32_bf16 v[88:91], v[178:181], v[194:197], v[88:91]
	v_mfma_f32_16x16x32_bf16 v[76:79], v[170:173], v[202:205], v[76:79]
	v_mfma_f32_16x16x32_bf16 v[72:75], v[178:181], v[202:205], v[72:75]
	v_mfma_f32_16x16x32_bf16 v[68:71], v[170:173], v[214:217], v[68:71]
	v_mfma_f32_16x16x32_bf16 v[64:67], v[178:181], v[214:217], v[64:67]
	s_setprio 0
	s_barrier
; #define PG8_STAGE(bufoff, gbase, voff) do { _Pragma("unroll") for (int _i = 0; _i < 2; ++_i) \
;         __builtin_amdgcn_global_load_lds((const unsigned*)((const char*)(gbase) + (voff)[_i]), (PG8_LAS unsigned*)(lds + (bufoff) + ldsw + _i * 8192), 16, 0, 0); } while (0)
; #define PG8_LDA(dst, b, h) do { _Pragma("unroll") for (int m = 0; m < 4; ++m) _Pragma("unroll") for (int k = 0; k < 2; ++k) dst[m][k] = *(const PG8_LAS bf16x8*)(lds + PG8_SA(b, h) + aoff + m * 2048 + k * 1024); } while (0)
; #define PG8_MMA(ai, bj, At, Bt) do { __builtin_amdgcn_s_setprio(1); _Pragma("unroll") for (int m = 0; m < 4; ++m) _Pragma("unroll") for (int n = 0; n < 2; ++n) _Pragma("unroll") for (int k = 0; k < 2; ++k) \
;         acc[ai][bj][m][n] = __builtin_amdgcn_mfma_f32_16x16x32_bf16(Bt[n][k], At[m][k], acc[ai][bj][m][n], 0, 0, 0); __builtin_amdgcn_s_setprio(0); } while (0)
; #define PG8_WAIT_V(n) asm volatile("s_waitcnt vmcnt(" #n ")" ::: "memory")
; #define PG8_WAIT_L(n) asm volatile("s_waitcnt lgkmcnt(" #n ")" ::: "memory")
; #define PG8_BAR __builtin_amdgcn_s_barrier()
; #define PG8_SCHED __builtin_amdgcn_sched_barrier(0)
; template <class Epi, class Sched, bool ALIGN_EPI = false, bool SP2 = false>
; __device__ __forceinline__ void gemm_phase(PG8_LAS unsigned char* lds, const Gemm g, const Sched& S, const Epi& E, const int tid) {
;     ...
;             PG8_LDA(At, 1, 1); PG8_STAGE(PG8_SB(1, 0), b3, voffB); PG8_STAGE(PG8_SB(1, 1), b3 + hstepB, voffB); PG8_STAGE(PG8_SA(1, 0), a3, voffA);
;             PG8_WAIT_V(8); PG8_WAIT_L(0); PG8_BAR; PG8_MMA(1, 0, At, B0); PG8_MMA(1, 1, At, B1); PG8_BAR; PG8_SCHED;
;     ...
;         if constexpr (ALIGN_EPI) { if (wr == 0) PG8_BAR; }
	s_add_i32 s28, s63, s33
	v_lshl_add_u64 v[206:207], v[206:207], 0, s[10:11]
	s_mov_b32 m0, s28
	ds_read_b128 v[182:185], v149 offset:49152
	ds_read_b128 v[186:189], v149 offset:50176
	ds_read_b128 v[190:193], v149 offset:51200
	ds_read_b128 v[194:197], v149 offset:52224
	ds_read_b128 v[198:201], v149 offset:53248
	ds_read_b128 v[202:205], v149 offset:54272
	ds_read_b128 v[210:213], v149 offset:55296
	ds_read_b128 v[214:217], v149 offset:56320
	global_load_lds_dwordx4 v[206:207], off
	s_add_i32 m0, s28, 0x2000
	s_add_u32 s28, s34, 0xb0080
	v_lshl_add_u64 v[206:207], v[218:219], 0, s[10:11]
	s_addc_u32 s29, s35, 0
	s_add_i32 s34, s64, s33
	global_load_lds_dwordx4 v[206:207], off
	v_lshl_add_u64 v[206:207], s[28:29], 0, v[130:131]
	s_mov_b32 m0, s34
	s_nop 0
	global_load_lds_dwordx4 v[206:207], off
	v_lshl_add_u64 v[206:207], s[28:29], 0, v[134:135]
	s_add_i32 m0, s34, 0x2000
	s_nop 0
	global_load_lds_dwordx4 v[206:207], off
	v_lshl_add_u64 v[206:207], v[220:221], 0, s[10:11]
	s_mov_b32 m0, s43
	s_nop 0
	global_load_lds_dwordx4 v[206:207], off
	v_lshl_add_u64 v[206:207], v[222:223], 0, s[10:11]
	s_mov_b32 m0, s44
	s_nop 0
	global_load_lds_dwordx4 v[206:207], off
	s_waitcnt vmcnt(8)
	s_waitcnt lgkmcnt(0)
	v_mfma_f32_16x16x32_bf16 v[60:63], v[150:153], v[182:185], v[60:63]
	v_mfma_f32_16x16x32_bf16 v[56:59], v[158:161], v[182:185], v[56:59]
	v_mfma_f32_16x16x32_bf16 v[52:55], v[150:153], v[190:193], v[52:55]
	v_mfma_f32_16x16x32_bf16 v[48:51], v[158:161], v[190:193], v[48:51]
	s_barrier
	s_setprio 1
	s_waitcnt lgkmcnt(0)
	v_mfma_f32_16x16x32_bf16 v[36:39], v[150:153], v[198:201], v[36:39]
	v_mfma_f32_16x16x32_bf16 v[32:35], v[158:161], v[198:201], v[32:35]
	v_mfma_f32_16x16x32_bf16 v[20:23], v[150:153], v[210:213], v[20:23]
	v_mfma_f32_16x16x32_bf16 v[16:19], v[158:161], v[210:213], v[16:19]
	v_mfma_f32_16x16x32_bf16 v[60:63], v[154:157], v[186:189], v[60:63]
	v_mfma_f32_16x16x32_bf16 v[56:59], v[162:165], v[186:189], v[56:59]
	v_mfma_f32_16x16x32_bf16 v[52:55], v[154:157], v[194:197], v[52:55]
	v_mfma_f32_16x16x32_bf16 v[48:51], v[162:165], v[194:197], v[48:51]
	v_mfma_f32_16x16x32_bf16 v[36:39], v[154:157], v[202:205], v[36:39]
	v_mfma_f32_16x16x32_bf16 v[32:35], v[162:165], v[202:205], v[32:35]
	v_mfma_f32_16x16x32_bf16 v[20:23], v[154:157], v[214:217], v[20:23]
	v_mfma_f32_16x16x32_bf16 v[16:19], v[162:165], v[214:217], v[16:19]
	s_setprio 0
	s_setprio 1
	v_mfma_f32_16x16x32_bf16 v[44:47], v[166:169], v[182:185], v[44:47]
	v_mfma_f32_16x16x32_bf16 v[40:43], v[174:177], v[182:185], v[40:43]
	v_mfma_f32_16x16x32_bf16 v[28:31], v[166:169], v[190:193], v[28:31]
	v_mfma_f32_16x16x32_bf16 v[24:27], v[174:177], v[190:193], v[24:27]
	v_mfma_f32_16x16x32_bf16 v[12:15], v[166:169], v[198:201], v[12:15]
	v_mfma_f32_16x16x32_bf16 v[8:11], v[174:177], v[198:201], v[8:11]
	v_mfma_f32_16x16x32_bf16 v[4:7], v[166:169], v[210:213], v[4:7]
	v_mfma_f32_16x16x32_bf16 v[0:3], v[174:177], v[210:213], v[0:3]
	v_mfma_f32_16x16x32_bf16 v[44:47], v[170:173], v[186:189], v[44:47]
	v_mfma_f32_16x16x32_bf16 v[40:43], v[178:181], v[186:189], v[40:43]
	v_mfma_f32_16x16x32_bf16 v[28:31], v[170:173], v[194:197], v[28:31]
	v_mfma_f32_16x16x32_bf16 v[24:27], v[178:181], v[194:197], v[24:27]
	v_mfma_f32_16x16x32_bf16 v[12:15], v[170:173], v[202:205], v[12:15]
	v_mfma_f32_16x16x32_bf16 v[8:11], v[178:181], v[202:205], v[8:11]
	v_mfma_f32_16x16x32_bf16 v[4:7], v[170:173], v[214:217], v[4:7]
	v_mfma_f32_16x16x32_bf16 v[0:3], v[178:181], v[214:217], v[0:3]
	s_setprio 0
	s_barrier
	s_add_i32 s62, s62, 2
	s_add_u32 s60, s60, 0x100
	s_addc_u32 s61, s61, 0
	s_cmp_gt_u32 s62, 41
	s_mov_b64 s[28:29], s[30:31]
	s_cbranch_scc0 .LBB0_914
	s_and_b64 vcc, exec, s[16:17]
	s_cbranch_vccz .LBB0_917
	s_barrier

; #define PG8_STAGE(bufoff, gbase, voff) do { _Pragma("unroll") for (int _i = 0; _i < 2; ++_i) \
;         __builtin_amdgcn_global_load_lds((const unsigned*)((const char*)(gbase) + (voff)[_i]), (PG8_LAS unsigned*)(lds + (bufoff) + ldsw + _i * 8192), 16, 0, 0); } while (0)
; #define PG8_LDA(dst, b, h) do { _Pragma("unroll") for (int m = 0; m < 4; ++m) _Pragma("unroll") for (int k = 0; k < 2; ++k) dst[m][k] = *(const PG8_LAS bf16x8*)(lds + PG8_SA(b, h) + aoff + m * 2048 + k * 1024); } while (0)
; #define PG8_LDB(dst, b, h) do { _Pragma("unroll") for (int n = 0; n < 2; ++n) _Pragma("unroll") for (int k = 0; k < 2; ++k) dst[n][k] = *(const PG8_LAS bf16x8*)(lds + PG8_SB(b, h) + boff + n * 2048 + k * 1024); } while (0)
; #define PG8_MMA(ai, bj, At, Bt) do { __builtin_amdgcn_s_setprio(1); _Pragma("unroll") for (int m = 0; m < 4; ++m) _Pragma("unroll") for (int n = 0; n < 2; ++n) _Pragma("unroll") for (int k = 0; k < 2; ++k) \
;         acc[ai][bj][m][n] = __builtin_amdgcn_mfma_f32_16x16x32_bf16(Bt[n][k], At[m][k], acc[ai][bj][m][n], 0, 0, 0); __builtin_amdgcn_s_setprio(0); } while (0)
; #define PG8_WAIT_V(n) asm volatile("s_waitcnt vmcnt(" #n ")" ::: "memory")
; #define PG8_WAIT_L(n) asm volatile("s_waitcnt lgkmcnt(" #n ")" ::: "memory")
; #define PG8_BAR __builtin_amdgcn_s_barrier()
; #define PG8_SCHED __builtin_amdgcn_sched_barrier(0)
; template <class Epi, class Sched, bool ALIGN_EPI = false, bool SP2 = false>
; __device__ __forceinline__ void gemm_phase(PG8_LAS unsigned char* lds, const Gemm g, const Sched& S, const Epi& E, const int tid) {
;     ...
;             if constexpr (SP2) {
;             PG8_LDB(B0, 0, 0); PG8_LDB(B1, 0, 1); PG8_SCHED; PG8_LDA(At, 0, 0); PG8_STAGE(PG8_SA(1, 1), a1 + hstepA, voffA);
;             PG8_WAIT_V(8); PG8_WAIT_L(0); PG8_BAR; PG8_MMA(0, 0, At, B0); PG8_MMA(0, 1, At, B1); PG8_BAR; PG8_SCHED;
;             PG8_LDA(At, 0, 1); PG8_STAGE(PG8_SB(0, 0), b2, voffB); PG8_STAGE(PG8_SB(0, 1), b2 + hstepB, voffB); PG8_STAGE(PG8_SA(0, 0), a2, voffA);
;             PG8_WAIT_V(8); PG8_WAIT_L(0); PG8_BAR; PG8_MMA(1, 0, At, B0); PG8_MMA(1, 1, At, B1); PG8_BAR; PG8_SCHED;
.LBB0_1246:
	ds_read_b128 v[146:149], v173
	ds_read_b128 v[150:153], v173 offset:1024
	ds_read_b128 v[154:157], v173 offset:2048
	ds_read_b128 v[158:161], v173 offset:3072
	ds_read_b128 v[162:165], v174
	ds_read_b128 v[166:169], v174 offset:1024
	ds_read_b128 v[178:181], v174 offset:2048
	ds_read_b128 v[182:185], v174 offset:3072
	s_add_u32 s48, s6, 0xfffc0080
	s_addc_u32 s49, s7, -1
	s_cmp_eq_u32 s74, 12
	s_cselect_b32 s51, s43, s49
	s_cselect_b32 s50, s58, s48
	s_cselect_b32 s49, s41, s73
	s_cselect_b32 s48, s59, s72
	v_lshl_add_u64 v[206:207], s[6:7], 0, v[138:139]
	s_add_i32 m0, s53, 0xc000
	ds_read_b128 v[186:189], v175
	ds_read_b128 v[190:193], v175 offset:1024
	ds_read_b128 v[194:197], v175 offset:2048
	ds_read_b128 v[198:201], v175 offset:3072
	ds_read_b128 v[202:205], v175 offset:4096
	ds_read_b128 v[210:213], v175 offset:5120
	ds_read_b128 v[214:217], v175 offset:6144
	ds_read_b128 v[218:221], v175 offset:7168
	global_load_lds_dwordx4 v[206:207], off
	v_lshl_add_u64 v[206:207], s[6:7], 0, v[140:141]
	s_add_i32 m0, s53, 0xe000
	s_nop 0
	global_load_lds_dwordx4 v[206:207], off
	s_waitcnt vmcnt(8)
	s_waitcnt lgkmcnt(0)
	v_mfma_f32_16x16x32_bf16 v[124:127], v[146:149], v[186:189], v[124:127]
	v_mfma_f32_16x16x32_bf16 v[120:123], v[154:157], v[186:189], v[120:123]
	v_mfma_f32_16x16x32_bf16 v[108:111], v[146:149], v[194:197], v[108:111]
	v_mfma_f32_16x16x32_bf16 v[104:107], v[154:157], v[194:197], v[104:107]
	s_barrier
	s_setprio 1
	s_waitcnt lgkmcnt(0)
	v_mfma_f32_16x16x32_bf16 v[92:95], v[146:149], v[202:205], v[92:95]
	v_mfma_f32_16x16x32_bf16 v[88:91], v[154:157], v[202:205], v[88:91]
	v_mfma_f32_16x16x32_bf16 v[76:79], v[146:149], v[214:217], v[76:79]
	v_mfma_f32_16x16x32_bf16 v[72:75], v[154:157], v[214:217], v[72:75]
	v_mfma_f32_16x16x32_bf16 v[124:127], v[150:153], v[190:193], v[124:127]
	v_mfma_f32_16x16x32_bf16 v[120:123], v[158:161], v[190:193], v[120:123]
	v_mfma_f32_16x16x32_bf16 v[108:111], v[150:153], v[198:201], v[108:111]
	v_mfma_f32_16x16x32_bf16 v[104:107], v[158:161], v[198:201], v[104:107]
	v_mfma_f32_16x16x32_bf16 v[92:95], v[150:153], v[210:213], v[92:95]
	v_mfma_f32_16x16x32_bf16 v[88:91], v[158:161], v[210:213], v[88:91]
	v_mfma_f32_16x16x32_bf16 v[76:79], v[150:153], v[218:221], v[76:79]
	v_mfma_f32_16x16x32_bf16 v[72:75], v[158:161], v[218:221], v[72:75]
	s_setprio 0
	s_setprio 1
	v_mfma_f32_16x16x32_bf16 v[116:119], v[162:165], v[186:189], v[116:119]
	v_mfma_f32_16x16x32_bf16 v[112:115], v[178:181], v[186:189], v[112:115]
	v_mfma_f32_16x16x32_bf16 v[100:103], v[162:165], v[194:197], v[100:103]
	v_mfma_f32_16x16x32_bf16 v[96:99], v[178:181], v[194:197], v[96:99]
	v_mfma_f32_16x16x32_bf16 v[84:87], v[162:165], v[202:205], v[84:87]
	v_mfma_f32_16x16x32_bf16 v[80:83], v[178:181], v[202:205], v[80:83]
	v_mfma_f32_16x16x32_bf16 v[68:71], v[162:165], v[214:217], v[68:71]
	v_mfma_f32_16x16x32_bf16 v[64:67], v[178:181], v[214:217], v[64:67]
	v_mfma_f32_16x16x32_bf16 v[116:119], v[166:169], v[190:193], v[116:119]
	v_mfma_f32_16x16x32_bf16 v[112:115], v[182:185], v[190:193], v[112:115]
	v_mfma_f32_16x16x32_bf16 v[100:103], v[166:169], v[198:201], v[100:103]
	v_mfma_f32_16x16x32_bf16 v[96:99], v[182:185], v[198:201], v[96:99]
	v_mfma_f32_16x16x32_bf16 v[84:87], v[166:169], v[210:213], v[84:87]
	v_mfma_f32_16x16x32_bf16 v[80:83], v[182:185], v[210:213], v[80:83]
	v_mfma_f32_16x16x32_bf16 v[68:71], v[166:169], v[218:221], v[68:71]
	v_mfma_f32_16x16x32_bf16 v[64:67], v[182:185], v[218:221], v[64:67]
	s_setprio 0
	s_barrier
	s_add_i32 s75, s66, s1
	v_lshl_add_u64 v[206:207], s[48:49], 0, v[130:131]
	s_mov_b32 m0, s75
	ds_read_b128 v[186:189], v175 offset:16384
	ds_read_b128 v[190:193], v175 offset:17408
	ds_read_b128 v[194:197], v175 offset:18432
	ds_read_b128 v[198:201], v175 offset:19456
	ds_read_b128 v[202:205], v175 offset:20480
	ds_read_b128 v[210:213], v175 offset:21504
	ds_read_b128 v[214:217], v175 offset:22528
	ds_read_b128 v[218:221], v175 offset:23552
	global_load_lds_dwordx4 v[206:207], off
	s_add_i32 m0, s75, 0x2000
	s_add_u32 s76, s48, 0x40000
	v_lshl_add_u64 v[222:223], s[48:49], 0, v[134:135]
	s_addc_u32 s77, s49, 0
	s_add_i32 s75, s67, s1
	global_load_lds_dwordx4 v[222:223], off
	v_lshl_add_u64 v[224:225], s[76:77], 0, v[130:131]
	s_mov_b32 m0, s75
	v_lshl_add_u64 v[226:227], s[50:51], 0, v[132:133]
	global_load_lds_dwordx4 v[224:225], off
	v_lshl_add_u64 v[224:225], s[76:77], 0, v[134:135]
	s_add_i32 m0, s75, 0x2000
	s_nop 0
	global_load_lds_dwordx4 v[224:225], off
	v_lshl_add_u64 v[224:225], s[50:51], 0, v[128:129]
	s_mov_b32 m0, s53
	s_nop 0
	global_load_lds_dwordx4 v[224:225], off
	s_mov_b32 m0, s57
	s_nop 0
	global_load_lds_dwordx4 v[226:227], off
	s_waitcnt vmcnt(8)
	s_waitcnt lgkmcnt(0)
	v_mfma_f32_16x16x32_bf16 v[60:63], v[146:149], v[186:189], v[60:63]
	v_mfma_f32_16x16x32_bf16 v[56:59], v[154:157], v[186:189], v[56:59]
	v_mfma_f32_16x16x32_bf16 v[44:47], v[146:149], v[194:197], v[44:47]
	v_mfma_f32_16x16x32_bf16 v[40:43], v[154:157], v[194:197], v[40:43]
	s_barrier
; #define PG8_STAGE(bufoff, gbase, voff) do { _Pragma("unroll") for (int _i = 0; _i < 2; ++_i) \
;         __builtin_amdgcn_global_load_lds((const unsigned*)((const char*)(gbase) + (voff)[_i]), (PG8_LAS unsigned*)(lds + (bufoff) + ldsw + _i * 8192), 16, 0, 0); } while (0)
; #define PG8_LDA(dst, b, h) do { _Pragma("unroll") for (int m = 0; m < 4; ++m) _Pragma("unroll") for (int k = 0; k < 2; ++k) dst[m][k] = *(const PG8_LAS bf16x8*)(lds + PG8_SA(b, h) + aoff + m * 2048 + k * 1024); } while (0)
; #define PG8_LDB(dst, b, h) do { _Pragma("unroll") for (int n = 0; n < 2; ++n) _Pragma("unroll") for (int k = 0; k < 2; ++k) dst[n][k] = *(const PG8_LAS bf16x8*)(lds + PG8_SB(b, h) + boff + n * 2048 + k * 1024); } while (0)
; #define PG8_MMA(ai, bj, At, Bt) do { __builtin_amdgcn_s_setprio(1); _Pragma("unroll") for (int m = 0; m < 4; ++m) _Pragma("unroll") for (int n = 0; n < 2; ++n) _Pragma("unroll") for (int k = 0; k < 2; ++k) \
;         acc[ai][bj][m][n] = __builtin_amdgcn_mfma_f32_16x16x32_bf16(Bt[n][k], At[m][k], acc[ai][bj][m][n], 0, 0, 0); __builtin_amdgcn_s_setprio(0); } while (0)
; #define PG8_WAIT_V(n) asm volatile("s_waitcnt vmcnt(" #n ")" ::: "memory")
; #define PG8_WAIT_L(n) asm volatile("s_waitcnt lgkmcnt(" #n ")" ::: "memory")
; #define PG8_BAR __builtin_amdgcn_s_barrier()
; #define PG8_SCHED __builtin_amdgcn_sched_barrier(0)
; template <class Epi, class Sched, bool ALIGN_EPI = false, bool SP2 = false>
; __device__ __forceinline__ void gemm_phase(PG8_LAS unsigned char* lds, const Gemm g, const Sched& S, const Epi& E, const int tid) {
;     ...
;             PG8_WAIT_V(8); PG8_WAIT_L(0); PG8_BAR; PG8_MMA(1, 0, At, B0); PG8_MMA(1, 1, At, B1); PG8_BAR; PG8_SCHED;
;             PG8_LDB(B0, 1, 0); PG8_LDB(B1, 1, 1); PG8_SCHED; PG8_LDA(At, 1, 0); PG8_STAGE(PG8_SA(0, 1), a2 + hstepA, voffA);
;             PG8_WAIT_V(8); PG8_WAIT_L(0); PG8_BAR; PG8_MMA(0, 0, At, B0); PG8_MMA(0, 1, At, B1); PG8_BAR; PG8_SCHED;
	s_setprio 1
	s_waitcnt lgkmcnt(0)
	v_mfma_f32_16x16x32_bf16 v[28:31], v[146:149], v[202:205], v[28:31]
	v_mfma_f32_16x16x32_bf16 v[24:27], v[154:157], v[202:205], v[24:27]
	v_mfma_f32_16x16x32_bf16 v[12:15], v[146:149], v[214:217], v[12:15]
	v_mfma_f32_16x16x32_bf16 v[8:11], v[154:157], v[214:217], v[8:11]
	v_mfma_f32_16x16x32_bf16 v[60:63], v[150:153], v[190:193], v[60:63]
	v_mfma_f32_16x16x32_bf16 v[56:59], v[158:161], v[190:193], v[56:59]
	v_mfma_f32_16x16x32_bf16 v[44:47], v[150:153], v[198:201], v[44:47]
	v_mfma_f32_16x16x32_bf16 v[40:43], v[158:161], v[198:201], v[40:43]
	v_mfma_f32_16x16x32_bf16 v[28:31], v[150:153], v[210:213], v[28:31]
	v_mfma_f32_16x16x32_bf16 v[24:27], v[158:161], v[210:213], v[24:27]
	v_mfma_f32_16x16x32_bf16 v[12:15], v[150:153], v[218:221], v[12:15]
	v_mfma_f32_16x16x32_bf16 v[8:11], v[158:161], v[218:221], v[8:11]
	s_setprio 0
	s_setprio 1
	v_mfma_f32_16x16x32_bf16 v[52:55], v[162:165], v[186:189], v[52:55]
	v_mfma_f32_16x16x32_bf16 v[48:51], v[178:181], v[186:189], v[48:51]
	v_mfma_f32_16x16x32_bf16 v[36:39], v[162:165], v[194:197], v[36:39]
	v_mfma_f32_16x16x32_bf16 v[32:35], v[178:181], v[194:197], v[32:35]
	v_mfma_f32_16x16x32_bf16 v[20:23], v[162:165], v[202:205], v[20:23]
	v_mfma_f32_16x16x32_bf16 v[16:19], v[178:181], v[202:205], v[16:19]
	v_mfma_f32_16x16x32_bf16 v[4:7], v[162:165], v[214:217], v[4:7]
	v_mfma_f32_16x16x32_bf16 v[0:3], v[178:181], v[214:217], v[0:3]
	v_mfma_f32_16x16x32_bf16 v[52:55], v[166:169], v[190:193], v[52:55]
	v_mfma_f32_16x16x32_bf16 v[48:51], v[182:185], v[190:193], v[48:51]
	v_mfma_f32_16x16x32_bf16 v[36:39], v[166:169], v[198:201], v[36:39]
	v_mfma_f32_16x16x32_bf16 v[32:35], v[182:185], v[198:201], v[32:35]
	v_mfma_f32_16x16x32_bf16 v[20:23], v[166:169], v[210:213], v[20:23]
	v_mfma_f32_16x16x32_bf16 v[16:19], v[182:185], v[210:213], v[16:19]
	v_mfma_f32_16x16x32_bf16 v[4:7], v[166:169], v[218:221], v[4:7]
	v_mfma_f32_16x16x32_bf16 v[0:3], v[182:185], v[218:221], v[0:3]
	s_setprio 0
	s_barrier
	s_add_i32 s75, 0, 0x18000
	v_add_u32_e32 v136, s75, v171
	s_add_i32 s76, 0, 0x1c000
	ds_read_b128 v[146:149], v136
	ds_read_b128 v[150:153], v136 offset:1024
	ds_read_b128 v[154:157], v136 offset:2048
	ds_read_b128 v[158:161], v136 offset:3072
	v_add_u32_e32 v136, s76, v171
	ds_read_b128 v[162:165], v136
	ds_read_b128 v[166:169], v136 offset:1024
	ds_read_b128 v[178:181], v136 offset:2048
	ds_read_b128 v[182:185], v136 offset:3072
	s_add_u32 s50, s50, 0x40000
	s_addc_u32 s51, s51, 0
	s_mov_b32 m0, s60
	v_lshl_add_u64 v[228:229], s[50:51], 0, v[128:129]
	ds_read_b128 v[186:189], v175 offset:32768
	ds_read_b128 v[190:193], v175 offset:33792
	ds_read_b128 v[194:197], v175 offset:34816
	ds_read_b128 v[198:201], v175 offset:35840
	ds_read_b128 v[202:205], v175 offset:36864
	ds_read_b128 v[210:213], v175 offset:37888
	ds_read_b128 v[214:217], v175 offset:38912
	ds_read_b128 v[218:221], v175 offset:39936
	global_load_lds_dwordx4 v[228:229], off
	v_lshl_add_u64 v[228:229], s[50:51], 0, v[132:133]
	s_mov_b32 m0, s61
	s_nop 0
	global_load_lds_dwordx4 v[228:229], off
	s_waitcnt vmcnt(8)
	s_waitcnt lgkmcnt(0)
	v_mfma_f32_16x16x32_bf16 v[124:127], v[146:149], v[186:189], v[124:127]
	v_mfma_f32_16x16x32_bf16 v[120:123], v[154:157], v[186:189], v[120:123]
	v_mfma_f32_16x16x32_bf16 v[108:111], v[146:149], v[194:197], v[108:111]
	v_mfma_f32_16x16x32_bf16 v[104:107], v[154:157], v[194:197], v[104:107]
	s_barrier
	s_setprio 1
	s_waitcnt lgkmcnt(0)
	v_mfma_f32_16x16x32_bf16 v[92:95], v[146:149], v[202:205], v[92:95]
	v_mfma_f32_16x16x32_bf16 v[88:91], v[154:157], v[202:205], v[88:91]
	v_mfma_f32_16x16x32_bf16 v[76:79], v[146:149], v[214:217], v[76:79]
	v_mfma_f32_16x16x32_bf16 v[72:75], v[154:157], v[214:217], v[72:75]
	v_mfma_f32_16x16x32_bf16 v[124:127], v[150:153], v[190:193], v[124:127]
	v_mfma_f32_16x16x32_bf16 v[120:123], v[158:161], v[190:193], v[120:123]
	v_mfma_f32_16x16x32_bf16 v[108:111], v[150:153], v[198:201], v[108:111]
	v_mfma_f32_16x16x32_bf16 v[104:107], v[158:161], v[198:201], v[104:107]
	v_mfma_f32_16x16x32_bf16 v[92:95], v[150:153], v[210:213], v[92:95]
	v_mfma_f32_16x16x32_bf16 v[88:91], v[158:161], v[210:213], v[88:91]
	v_mfma_f32_16x16x32_bf16 v[76:79], v[150:153], v[218:221], v[76:79]
	v_mfma_f32_16x16x32_bf16 v[72:75], v[158:161], v[218:221], v[72:75]
	s_setprio 0
	s_setprio 1
	v_mfma_f32_16x16x32_bf16 v[116:119], v[162:165], v[186:189], v[116:119]
	v_mfma_f32_16x16x32_bf16 v[112:115], v[178:181], v[186:189], v[112:115]
	v_mfma_f32_16x16x32_bf16 v[100:103], v[162:165], v[194:197], v[100:103]
	v_mfma_f32_16x16x32_bf16 v[96:99], v[178:181], v[194:197], v[96:99]
	v_mfma_f32_16x16x32_bf16 v[84:87], v[162:165], v[202:205], v[84:87]
	v_mfma_f32_16x16x32_bf16 v[80:83], v[178:181], v[202:205], v[80:83]
	v_mfma_f32_16x16x32_bf16 v[68:71], v[162:165], v[214:217], v[68:71]
	v_mfma_f32_16x16x32_bf16 v[64:67], v[178:181], v[214:217], v[64:67]
	v_mfma_f32_16x16x32_bf16 v[116:119], v[166:169], v[190:193], v[116:119]
	v_mfma_f32_16x16x32_bf16 v[112:115], v[182:185], v[190:193], v[112:115]
	v_mfma_f32_16x16x32_bf16 v[100:103], v[166:169], v[198:201], v[100:103]
	v_mfma_f32_16x16x32_bf16 v[96:99], v[182:185], v[198:201], v[96:99]
	v_mfma_f32_16x16x32_bf16 v[84:87], v[166:169], v[210:213], v[84:87]
	v_mfma_f32_16x16x32_bf16 v[80:83], v[182:185], v[210:213], v[80:83]
	v_mfma_f32_16x16x32_bf16 v[68:71], v[166:169], v[218:221], v[68:71]
	v_mfma_f32_16x16x32_bf16 v[64:67], v[182:185], v[218:221], v[64:67]
	s_setprio 0
	s_barrier
; #define PG8_STAGE(bufoff, gbase, voff) do { _Pragma("unroll") for (int _i = 0; _i < 2; ++_i) \
;         __builtin_amdgcn_global_load_lds((const unsigned*)((const char*)(gbase) + (voff)[_i]), (PG8_LAS unsigned*)(lds + (bufoff) + ldsw + _i * 8192), 16, 0, 0); } while (0)
; #define PG8_LDA(dst, b, h) do { _Pragma("unroll") for (int m = 0; m < 4; ++m) _Pragma("unroll") for (int k = 0; k < 2; ++k) dst[m][k] = *(const PG8_LAS bf16x8*)(lds + PG8_SA(b, h) + aoff + m * 2048 + k * 1024); } while (0)
; #define PG8_MMA(ai, bj, At, Bt) do { __builtin_amdgcn_s_setprio(1); _Pragma("unroll") for (int m = 0; m < 4; ++m) _Pragma("unroll") for (int n = 0; n < 2; ++n) _Pragma("unroll") for (int k = 0; k < 2; ++k) \
;         acc[ai][bj][m][n] = __builtin_amdgcn_mfma_f32_16x16x32_bf16(Bt[n][k], At[m][k], acc[ai][bj][m][n], 0, 0, 0); __builtin_amdgcn_s_setprio(0); } while (0)
; #define PG8_WAIT_V(n) asm volatile("s_waitcnt vmcnt(" #n ")" ::: "memory")
; #define PG8_WAIT_L(n) asm volatile("s_waitcnt lgkmcnt(" #n ")" ::: "memory")
; #define PG8_BAR __builtin_amdgcn_s_barrier()
; #define PG8_SCHED __builtin_amdgcn_sched_barrier(0)
; template <class Epi, class Sched, bool ALIGN_EPI = false, bool SP2 = false>
; __device__ __forceinline__ void gemm_phase(PG8_LAS unsigned char* lds, const Gemm g, const Sched& S, const Epi& E, const int tid) {
;     ...
;             PG8_LDA(At, 1, 1); PG8_STAGE(PG8_SB(1, 0), b3, voffB); PG8_STAGE(PG8_SB(1, 1), b3 + hstepB, voffB); PG8_STAGE(PG8_SA(1, 0), a3, voffA);
;             PG8_WAIT_V(8); PG8_WAIT_L(0); PG8_BAR; PG8_MMA(1, 0, At, B0); PG8_MMA(1, 1, At, B1); PG8_BAR; PG8_SCHED;
	s_add_i32 s50, s75, s1
	v_lshl_add_u64 v[206:207], v[206:207], 0, s[24:25]
	s_mov_b32 m0, s50
	ds_read_b128 v[186:189], v175 offset:49152
	ds_read_b128 v[190:193], v175 offset:50176
	ds_read_b128 v[194:197], v175 offset:51200
	ds_read_b128 v[198:201], v175 offset:52224
	ds_read_b128 v[202:205], v175 offset:53248
	ds_read_b128 v[210:213], v175 offset:54272
	ds_read_b128 v[214:217], v175 offset:55296
	ds_read_b128 v[218:221], v175 offset:56320
	global_load_lds_dwordx4 v[206:207], off
	s_add_i32 m0, s50, 0x2000
	s_add_u32 s48, s48, 0x40080
	v_lshl_add_u64 v[206:207], v[222:223], 0, s[24:25]
	s_addc_u32 s49, s49, 0
	s_add_i32 s50, s76, s1
	global_load_lds_dwordx4 v[206:207], off
	v_lshl_add_u64 v[206:207], s[48:49], 0, v[130:131]
	s_mov_b32 m0, s50
	s_nop 0
	global_load_lds_dwordx4 v[206:207], off
	v_lshl_add_u64 v[206:207], s[48:49], 0, v[134:135]
	s_add_i32 m0, s50, 0x2000
	s_nop 0
	global_load_lds_dwordx4 v[206:207], off
	v_lshl_add_u64 v[206:207], v[224:225], 0, s[24:25]
	s_mov_b32 m0, s63
	s_nop 0
	global_load_lds_dwordx4 v[206:207], off
	v_lshl_add_u64 v[206:207], v[226:227], 0, s[24:25]
	s_mov_b32 m0, s64
	s_nop 0
	global_load_lds_dwordx4 v[206:207], off
	s_waitcnt vmcnt(8)
	s_waitcnt lgkmcnt(0)
	v_mfma_f32_16x16x32_bf16 v[60:63], v[146:149], v[186:189], v[60:63]
	v_mfma_f32_16x16x32_bf16 v[56:59], v[154:157], v[186:189], v[56:59]
	v_mfma_f32_16x16x32_bf16 v[44:47], v[146:149], v[194:197], v[44:47]
	v_mfma_f32_16x16x32_bf16 v[40:43], v[154:157], v[194:197], v[40:43]
	s_barrier
	s_setprio 1
	s_waitcnt lgkmcnt(0)
	v_mfma_f32_16x16x32_bf16 v[28:31], v[146:149], v[202:205], v[28:31]
	v_mfma_f32_16x16x32_bf16 v[24:27], v[154:157], v[202:205], v[24:27]
	v_mfma_f32_16x16x32_bf16 v[12:15], v[146:149], v[214:217], v[12:15]
	v_mfma_f32_16x16x32_bf16 v[8:11], v[154:157], v[214:217], v[8:11]
	v_mfma_f32_16x16x32_bf16 v[60:63], v[150:153], v[190:193], v[60:63]
	v_mfma_f32_16x16x32_bf16 v[56:59], v[158:161], v[190:193], v[56:59]
	v_mfma_f32_16x16x32_bf16 v[44:47], v[150:153], v[198:201], v[44:47]
	v_mfma_f32_16x16x32_bf16 v[40:43], v[158:161], v[198:201], v[40:43]
	v_mfma_f32_16x16x32_bf16 v[28:31], v[150:153], v[210:213], v[28:31]
	v_mfma_f32_16x16x32_bf16 v[24:27], v[158:161], v[210:213], v[24:27]
	v_mfma_f32_16x16x32_bf16 v[12:15], v[150:153], v[218:221], v[12:15]
	v_mfma_f32_16x16x32_bf16 v[8:11], v[158:161], v[218:221], v[8:11]
	s_setprio 0
	s_setprio 1
	v_mfma_f32_16x16x32_bf16 v[52:55], v[162:165], v[186:189], v[52:55]
	v_mfma_f32_16x16x32_bf16 v[48:51], v[178:181], v[186:189], v[48:51]
	v_mfma_f32_16x16x32_bf16 v[36:39], v[162:165], v[194:197], v[36:39]
	v_mfma_f32_16x16x32_bf16 v[32:35], v[178:181], v[194:197], v[32:35]
	v_mfma_f32_16x16x32_bf16 v[20:23], v[162:165], v[202:205], v[20:23]
	v_mfma_f32_16x16x32_bf16 v[16:19], v[178:181], v[202:205], v[16:19]
	v_mfma_f32_16x16x32_bf16 v[4:7], v[162:165], v[214:217], v[4:7]
	v_mfma_f32_16x16x32_bf16 v[0:3], v[178:181], v[214:217], v[0:3]
	v_mfma_f32_16x16x32_bf16 v[52:55], v[166:169], v[190:193], v[52:55]
	v_mfma_f32_16x16x32_bf16 v[48:51], v[182:185], v[190:193], v[48:51]
	v_mfma_f32_16x16x32_bf16 v[36:39], v[166:169], v[198:201], v[36:39]
	v_mfma_f32_16x16x32_bf16 v[32:35], v[182:185], v[198:201], v[32:35]
	v_mfma_f32_16x16x32_bf16 v[20:23], v[166:169], v[210:213], v[20:23]
	v_mfma_f32_16x16x32_bf16 v[16:19], v[182:185], v[210:213], v[16:19]
	v_mfma_f32_16x16x32_bf16 v[4:7], v[166:169], v[218:221], v[4:7]
	v_mfma_f32_16x16x32_bf16 v[0:3], v[182:185], v[218:221], v[0:3]
	s_setprio 0
	s_barrier
	s_add_i32 s74, s74, 2
	s_add_u32 s6, s6, 0x100
	s_addc_u32 s7, s7, 0
	s_add_u32 s72, s72, 0x100
	s_addc_u32 s73, s73, 0
	s_cmp_gt_u32 s74, 13
	s_cbranch_scc0 .LBB0_1246
	s_and_b64 vcc, exec, s[26:27]
	s_cbranch_vccz .LBB0_1249
	s_barrier

; #define PG8_STAGE(bufoff, gbase, voff) do { _Pragma("unroll") for (int _i = 0; _i < 2; ++_i) \
;         __builtin_amdgcn_global_load_lds((const unsigned*)((const char*)(gbase) + (voff)[_i]), (PG8_LAS unsigned*)(lds + (bufoff) + ldsw + _i * 8192), 16, 0, 0); } while (0)
; #define PG8_LDA(dst, b, h) do { _Pragma("unroll") for (int m = 0; m < 4; ++m) _Pragma("unroll") for (int k = 0; k < 2; ++k) dst[m][k] = *(const PG8_LAS bf16x8*)(lds + PG8_SA(b, h) + aoff + m * 2048 + k * 1024); } while (0)
; #define PG8_LDB(dst, b, h) do { _Pragma("unroll") for (int n = 0; n < 2; ++n) _Pragma("unroll") for (int k = 0; k < 2; ++k) dst[n][k] = *(const PG8_LAS bf16x8*)(lds + PG8_SB(b, h) + boff + n * 2048 + k * 1024); } while (0)
; #define PG8_MMA(ai, bj, At, Bt) do { __builtin_amdgcn_s_setprio(1); _Pragma("unroll") for (int m = 0; m < 4; ++m) _Pragma("unroll") for (int n = 0; n < 2; ++n) _Pragma("unroll") for (int k = 0; k < 2; ++k) \
;         acc[ai][bj][m][n] = __builtin_amdgcn_mfma_f32_16x16x32_bf16(Bt[n][k], At[m][k], acc[ai][bj][m][n], 0, 0, 0); __builtin_amdgcn_s_setprio(0); } while (0)
; #define PG8_WAIT_V(n) asm volatile("s_waitcnt vmcnt(" #n ")" ::: "memory")
; #define PG8_WAIT_L(n) asm volatile("s_waitcnt lgkmcnt(" #n ")" ::: "memory")
; template <class Epi, class Sched, bool ALIGN_EPI = false, bool SP2 = false>
; __device__ __forceinline__ void gemm_phase(PG8_LAS unsigned char* lds, const Gemm g, const Sched& S, const Epi& E, const int tid) {
;     ...
;             const bool last = (t == nt - 2);
;             const char* a1 = cA + (size_t)(t + 1) * kstep;
;             const char* a2 = last ? nA : cA + (size_t)(t + 2) * kstep; const char* b2 = last ? nB : cB + (size_t)(t + 2) * kstep;
;             const char* a3 = a2 + kstep; const char* b3 = b2 + kstep;
;             if (last && has_next) S.a_ready(nxt);
;             if constexpr (SP2) {
;             PG8_LDB(B0, 0, 0); PG8_LDB(B1, 0, 1); PG8_SCHED; PG8_LDA(At, 0, 0); PG8_STAGE(PG8_SA(1, 1), a1 + hstepA, voffA);
;             PG8_WAIT_V(8); PG8_WAIT_L(0); PG8_BAR; PG8_MMA(0, 0, At, B0); PG8_MMA(0, 1, At, B1); PG8_BAR; PG8_SCHED;
;             PG8_LDA(At, 0, 1); PG8_STAGE(PG8_SB(0, 0), b2, voffB); PG8_STAGE(PG8_SB(0, 1), b2 + hstepB, voffB); PG8_STAGE(PG8_SA(0, 0), a2, voffA);
;             PG8_WAIT_V(8); PG8_WAIT_L(0); PG8_BAR; PG8_MMA(1, 0, At, B0); PG8_MMA(1, 1, At, B1); PG8_BAR; PG8_SCHED;
.LBB0_1517:
	ds_read_b128 v[150:153], v147
	ds_read_b128 v[154:157], v147 offset:1024
	ds_read_b128 v[158:161], v147 offset:2048
	ds_read_b128 v[162:165], v147 offset:3072
	ds_read_b128 v[166:169], v148
	ds_read_b128 v[170:173], v148 offset:1024
	ds_read_b128 v[174:177], v148 offset:2048
	ds_read_b128 v[178:181], v148 offset:3072
	s_add_u32 s38, s36, 0xfffc0080
	s_addc_u32 s39, s37, -1
	s_cmp_eq_u32 s64, 12
	s_cselect_b32 s41, s29, s39
	s_cselect_b32 s40, s60, s38
	s_cselect_b32 s39, s27, s63
	s_cselect_b32 s38, s61, s62
	v_lshl_add_u64 v[206:207], s[36:37], 0, v[136:137]
	s_add_i32 m0, s25, 0xc000
	ds_read_b128 v[182:185], v149
	ds_read_b128 v[186:189], v149 offset:1024
	ds_read_b128 v[190:193], v149 offset:2048
	ds_read_b128 v[194:197], v149 offset:3072
	ds_read_b128 v[198:201], v149 offset:4096
	ds_read_b128 v[202:205], v149 offset:5120
	ds_read_b128 v[210:213], v149 offset:6144
	ds_read_b128 v[214:217], v149 offset:7168
	global_load_lds_dwordx4 v[206:207], off
	v_lshl_add_u64 v[206:207], s[36:37], 0, v[138:139]
	s_add_i32 m0, s25, 0xe000
	s_nop 0
	global_load_lds_dwordx4 v[206:207], off
	s_waitcnt vmcnt(8)
	s_waitcnt lgkmcnt(0)
	v_mfma_f32_16x16x32_bf16 v[124:127], v[150:153], v[182:185], v[124:127]
	v_mfma_f32_16x16x32_bf16 v[120:123], v[158:161], v[182:185], v[120:123]
	v_mfma_f32_16x16x32_bf16 v[116:119], v[150:153], v[190:193], v[116:119]
	v_mfma_f32_16x16x32_bf16 v[112:115], v[158:161], v[190:193], v[112:115]
	s_barrier
	s_setprio 1
	s_waitcnt lgkmcnt(0)
	v_mfma_f32_16x16x32_bf16 v[100:103], v[150:153], v[198:201], v[100:103]
	v_mfma_f32_16x16x32_bf16 v[96:99], v[158:161], v[198:201], v[96:99]
	v_mfma_f32_16x16x32_bf16 v[84:87], v[150:153], v[210:213], v[84:87]
	v_mfma_f32_16x16x32_bf16 v[80:83], v[158:161], v[210:213], v[80:83]
	v_mfma_f32_16x16x32_bf16 v[124:127], v[154:157], v[186:189], v[124:127]
	v_mfma_f32_16x16x32_bf16 v[120:123], v[162:165], v[186:189], v[120:123]
	v_mfma_f32_16x16x32_bf16 v[116:119], v[154:157], v[194:197], v[116:119]
	v_mfma_f32_16x16x32_bf16 v[112:115], v[162:165], v[194:197], v[112:115]
	v_mfma_f32_16x16x32_bf16 v[100:103], v[154:157], v[202:205], v[100:103]
	v_mfma_f32_16x16x32_bf16 v[96:99], v[162:165], v[202:205], v[96:99]
	v_mfma_f32_16x16x32_bf16 v[84:87], v[154:157], v[214:217], v[84:87]
	v_mfma_f32_16x16x32_bf16 v[80:83], v[162:165], v[214:217], v[80:83]
	s_setprio 0
	s_setprio 1
	v_mfma_f32_16x16x32_bf16 v[108:111], v[166:169], v[182:185], v[108:111]
	v_mfma_f32_16x16x32_bf16 v[104:107], v[174:177], v[182:185], v[104:107]
	v_mfma_f32_16x16x32_bf16 v[92:95], v[166:169], v[190:193], v[92:95]
	v_mfma_f32_16x16x32_bf16 v[88:91], v[174:177], v[190:193], v[88:91]
	v_mfma_f32_16x16x32_bf16 v[76:79], v[166:169], v[198:201], v[76:79]
	v_mfma_f32_16x16x32_bf16 v[72:75], v[174:177], v[198:201], v[72:75]
	v_mfma_f32_16x16x32_bf16 v[68:71], v[166:169], v[210:213], v[68:71]
	v_mfma_f32_16x16x32_bf16 v[64:67], v[174:177], v[210:213], v[64:67]
	v_mfma_f32_16x16x32_bf16 v[108:111], v[170:173], v[186:189], v[108:111]
	v_mfma_f32_16x16x32_bf16 v[104:107], v[178:181], v[186:189], v[104:107]
	v_mfma_f32_16x16x32_bf16 v[92:95], v[170:173], v[194:197], v[92:95]
	v_mfma_f32_16x16x32_bf16 v[88:91], v[178:181], v[194:197], v[88:91]
	v_mfma_f32_16x16x32_bf16 v[76:79], v[170:173], v[202:205], v[76:79]
	v_mfma_f32_16x16x32_bf16 v[72:75], v[178:181], v[202:205], v[72:75]
	v_mfma_f32_16x16x32_bf16 v[68:71], v[170:173], v[214:217], v[68:71]
	v_mfma_f32_16x16x32_bf16 v[64:67], v[178:181], v[214:217], v[64:67]
	s_setprio 0
	s_barrier
	s_add_i32 s65, s49, s1
	v_lshl_add_u64 v[206:207], s[38:39], 0, v[130:131]
	s_mov_b32 m0, s65
	ds_read_b128 v[182:185], v149 offset:16384
	ds_read_b128 v[186:189], v149 offset:17408
	ds_read_b128 v[190:193], v149 offset:18432
	ds_read_b128 v[194:197], v149 offset:19456
	ds_read_b128 v[198:201], v149 offset:20480
	ds_read_b128 v[202:205], v149 offset:21504
	ds_read_b128 v[210:213], v149 offset:22528
	ds_read_b128 v[214:217], v149 offset:23552
	global_load_lds_dwordx4 v[206:207], off
	s_add_i32 m0, s65, 0x2000
	s_add_u32 s66, s38, 0x40000
	v_lshl_add_u64 v[218:219], s[38:39], 0, v[134:135]
	s_addc_u32 s67, s39, 0
	s_add_i32 s65, s50, s1
	global_load_lds_dwordx4 v[218:219], off
	v_lshl_add_u64 v[220:221], s[66:67], 0, v[130:131]
	s_mov_b32 m0, s65
	v_lshl_add_u64 v[222:223], s[40:41], 0, v[132:133]
	global_load_lds_dwordx4 v[220:221], off
	v_lshl_add_u64 v[220:221], s[66:67], 0, v[134:135]
	s_add_i32 m0, s65, 0x2000
	s_nop 0
	global_load_lds_dwordx4 v[220:221], off
	v_lshl_add_u64 v[220:221], s[40:41], 0, v[128:129]
	s_mov_b32 m0, s25
	s_nop 0
	global_load_lds_dwordx4 v[220:221], off
	s_mov_b32 m0, s42
	s_nop 0
	global_load_lds_dwordx4 v[222:223], off
	s_waitcnt vmcnt(8)
	s_waitcnt lgkmcnt(0)
	v_mfma_f32_16x16x32_bf16 v[60:63], v[150:153], v[182:185], v[60:63]
	v_mfma_f32_16x16x32_bf16 v[56:59], v[158:161], v[182:185], v[56:59]
	v_mfma_f32_16x16x32_bf16 v[52:55], v[150:153], v[190:193], v[52:55]
	v_mfma_f32_16x16x32_bf16 v[48:51], v[158:161], v[190:193], v[48:51]
	s_barrier
; #define PG8_STAGE(bufoff, gbase, voff) do { _Pragma("unroll") for (int _i = 0; _i < 2; ++_i) \
;         __builtin_amdgcn_global_load_lds((const unsigned*)((const char*)(gbase) + (voff)[_i]), (PG8_LAS unsigned*)(lds + (bufoff) + ldsw + _i * 8192), 16, 0, 0); } while (0)
; #define PG8_LDA(dst, b, h) do { _Pragma("unroll") for (int m = 0; m < 4; ++m) _Pragma("unroll") for (int k = 0; k < 2; ++k) dst[m][k] = *(const PG8_LAS bf16x8*)(lds + PG8_SA(b, h) + aoff + m * 2048 + k * 1024); } while (0)
; #define PG8_LDB(dst, b, h) do { _Pragma("unroll") for (int n = 0; n < 2; ++n) _Pragma("unroll") for (int k = 0; k < 2; ++k) dst[n][k] = *(const PG8_LAS bf16x8*)(lds + PG8_SB(b, h) + boff + n * 2048 + k * 1024); } while (0)
; #define PG8_MMA(ai, bj, At, Bt) do { __builtin_amdgcn_s_setprio(1); _Pragma("unroll") for (int m = 0; m < 4; ++m) _Pragma("unroll") for (int n = 0; n < 2; ++n) _Pragma("unroll") for (int k = 0; k < 2; ++k) \
;         acc[ai][bj][m][n] = __builtin_amdgcn_mfma_f32_16x16x32_bf16(Bt[n][k], At[m][k], acc[ai][bj][m][n], 0, 0, 0); __builtin_amdgcn_s_setprio(0); } while (0)
; #define PG8_WAIT_V(n) asm volatile("s_waitcnt vmcnt(" #n ")" ::: "memory")
; #define PG8_WAIT_L(n) asm volatile("s_waitcnt lgkmcnt(" #n ")" ::: "memory")
; #define PG8_BAR __builtin_amdgcn_s_barrier()
; #define PG8_SCHED __builtin_amdgcn_sched_barrier(0)
; template <class Epi, class Sched, bool ALIGN_EPI = false, bool SP2 = false>
; __device__ __forceinline__ void gemm_phase(PG8_LAS unsigned char* lds, const Gemm g, const Sched& S, const Epi& E, const int tid) {
;     ...
;             PG8_WAIT_V(8); PG8_WAIT_L(0); PG8_BAR; PG8_MMA(1, 0, At, B0); PG8_MMA(1, 1, At, B1); PG8_BAR; PG8_SCHED;
;             PG8_LDB(B0, 1, 0); PG8_LDB(B1, 1, 1); PG8_SCHED; PG8_LDA(At, 1, 0); PG8_STAGE(PG8_SA(0, 1), a2 + hstepA, voffA);
;             PG8_WAIT_V(8); PG8_WAIT_L(0); PG8_BAR; PG8_MMA(0, 0, At, B0); PG8_MMA(0, 1, At, B1); PG8_BAR; PG8_SCHED;
	s_setprio 1
	s_waitcnt lgkmcnt(0)
	v_mfma_f32_16x16x32_bf16 v[36:39], v[150:153], v[198:201], v[36:39]
	v_mfma_f32_16x16x32_bf16 v[32:35], v[158:161], v[198:201], v[32:35]
	v_mfma_f32_16x16x32_bf16 v[20:23], v[150:153], v[210:213], v[20:23]
	v_mfma_f32_16x16x32_bf16 v[16:19], v[158:161], v[210:213], v[16:19]
	v_mfma_f32_16x16x32_bf16 v[60:63], v[154:157], v[186:189], v[60:63]
	v_mfma_f32_16x16x32_bf16 v[56:59], v[162:165], v[186:189], v[56:59]
	v_mfma_f32_16x16x32_bf16 v[52:55], v[154:157], v[194:197], v[52:55]
	v_mfma_f32_16x16x32_bf16 v[48:51], v[162:165], v[194:197], v[48:51]
	v_mfma_f32_16x16x32_bf16 v[36:39], v[154:157], v[202:205], v[36:39]
	v_mfma_f32_16x16x32_bf16 v[32:35], v[162:165], v[202:205], v[32:35]
	v_mfma_f32_16x16x32_bf16 v[20:23], v[154:157], v[214:217], v[20:23]
	v_mfma_f32_16x16x32_bf16 v[16:19], v[162:165], v[214:217], v[16:19]
	s_setprio 0
	s_setprio 1
	v_mfma_f32_16x16x32_bf16 v[44:47], v[166:169], v[182:185], v[44:47]
	v_mfma_f32_16x16x32_bf16 v[40:43], v[174:177], v[182:185], v[40:43]
	v_mfma_f32_16x16x32_bf16 v[28:31], v[166:169], v[190:193], v[28:31]
	v_mfma_f32_16x16x32_bf16 v[24:27], v[174:177], v[190:193], v[24:27]
	v_mfma_f32_16x16x32_bf16 v[12:15], v[166:169], v[198:201], v[12:15]
	v_mfma_f32_16x16x32_bf16 v[8:11], v[174:177], v[198:201], v[8:11]
	v_mfma_f32_16x16x32_bf16 v[4:7], v[166:169], v[210:213], v[4:7]
	v_mfma_f32_16x16x32_bf16 v[0:3], v[174:177], v[210:213], v[0:3]
	v_mfma_f32_16x16x32_bf16 v[44:47], v[170:173], v[186:189], v[44:47]
	v_mfma_f32_16x16x32_bf16 v[40:43], v[178:181], v[186:189], v[40:43]
	v_mfma_f32_16x16x32_bf16 v[28:31], v[170:173], v[194:197], v[28:31]
	v_mfma_f32_16x16x32_bf16 v[24:27], v[178:181], v[194:197], v[24:27]
	v_mfma_f32_16x16x32_bf16 v[12:15], v[170:173], v[202:205], v[12:15]
	v_mfma_f32_16x16x32_bf16 v[8:11], v[178:181], v[202:205], v[8:11]
	v_mfma_f32_16x16x32_bf16 v[4:7], v[170:173], v[214:217], v[4:7]
	v_mfma_f32_16x16x32_bf16 v[0:3], v[178:181], v[214:217], v[0:3]
	s_setprio 0
	s_barrier
	s_add_i32 s65, 0, 0x18000
	s_add_i32 s66, 0, 0x1c000
	v_add_u32_e32 v162, s65, v145
	v_add_u32_e32 v178, s66, v145
	ds_read_b128 v[150:153], v162
	ds_read_b128 v[154:157], v162 offset:1024
	ds_read_b128 v[158:161], v162 offset:2048
	ds_read_b128 v[162:165], v162 offset:3072
	ds_read_b128 v[166:169], v178
	ds_read_b128 v[170:173], v178 offset:1024
	ds_read_b128 v[174:177], v178 offset:2048
	ds_read_b128 v[178:181], v178 offset:3072
	s_add_u32 s40, s40, 0x40000
	s_addc_u32 s41, s41, 0
	s_mov_b32 m0, s43
	v_lshl_add_u64 v[224:225], s[40:41], 0, v[128:129]
	ds_read_b128 v[182:185], v149 offset:32768
	ds_read_b128 v[186:189], v149 offset:33792
	ds_read_b128 v[190:193], v149 offset:34816
	ds_read_b128 v[194:197], v149 offset:35840
	ds_read_b128 v[198:201], v149 offset:36864
	ds_read_b128 v[202:205], v149 offset:37888
	ds_read_b128 v[210:213], v149 offset:38912
	ds_read_b128 v[214:217], v149 offset:39936
	global_load_lds_dwordx4 v[224:225], off
	v_lshl_add_u64 v[224:225], s[40:41], 0, v[132:133]
	s_mov_b32 m0, s44
	s_nop 0
	global_load_lds_dwordx4 v[224:225], off
	s_waitcnt vmcnt(8)
	s_waitcnt lgkmcnt(0)
	v_mfma_f32_16x16x32_bf16 v[124:127], v[150:153], v[182:185], v[124:127]
	v_mfma_f32_16x16x32_bf16 v[120:123], v[158:161], v[182:185], v[120:123]
	v_mfma_f32_16x16x32_bf16 v[116:119], v[150:153], v[190:193], v[116:119]
	v_mfma_f32_16x16x32_bf16 v[112:115], v[158:161], v[190:193], v[112:115]
	s_barrier
	s_setprio 1
	s_waitcnt lgkmcnt(0)
	v_mfma_f32_16x16x32_bf16 v[100:103], v[150:153], v[198:201], v[100:103]
	v_mfma_f32_16x16x32_bf16 v[96:99], v[158:161], v[198:201], v[96:99]
	v_mfma_f32_16x16x32_bf16 v[84:87], v[150:153], v[210:213], v[84:87]
	v_mfma_f32_16x16x32_bf16 v[80:83], v[158:161], v[210:213], v[80:83]
	v_mfma_f32_16x16x32_bf16 v[124:127], v[154:157], v[186:189], v[124:127]
	v_mfma_f32_16x16x32_bf16 v[120:123], v[162:165], v[186:189], v[120:123]
	v_mfma_f32_16x16x32_bf16 v[116:119], v[154:157], v[194:197], v[116:119]
	v_mfma_f32_16x16x32_bf16 v[112:115], v[162:165], v[194:197], v[112:115]
	v_mfma_f32_16x16x32_bf16 v[100:103], v[154:157], v[202:205], v[100:103]
	v_mfma_f32_16x16x32_bf16 v[96:99], v[162:165], v[202:205], v[96:99]
	v_mfma_f32_16x16x32_bf16 v[84:87], v[154:157], v[214:217], v[84:87]
	v_mfma_f32_16x16x32_bf16 v[80:83], v[162:165], v[214:217], v[80:83]
	s_setprio 0
	s_setprio 1
	v_mfma_f32_16x16x32_bf16 v[108:111], v[166:169], v[182:185], v[108:111]
	v_mfma_f32_16x16x32_bf16 v[104:107], v[174:177], v[182:185], v[104:107]
	v_mfma_f32_16x16x32_bf16 v[92:95], v[166:169], v[190:193], v[92:95]
	v_mfma_f32_16x16x32_bf16 v[88:91], v[174:177], v[190:193], v[88:91]
	v_mfma_f32_16x16x32_bf16 v[76:79], v[166:169], v[198:201], v[76:79]
	v_mfma_f32_16x16x32_bf16 v[72:75], v[174:177], v[198:201], v[72:75]
	v_mfma_f32_16x16x32_bf16 v[68:71], v[166:169], v[210:213], v[68:71]
	v_mfma_f32_16x16x32_bf16 v[64:67], v[174:177], v[210:213], v[64:67]
	v_mfma_f32_16x16x32_bf16 v[108:111], v[170:173], v[186:189], v[108:111]
	v_mfma_f32_16x16x32_bf16 v[104:107], v[178:181], v[186:189], v[104:107]
	v_mfma_f32_16x16x32_bf16 v[92:95], v[170:173], v[194:197], v[92:95]
	v_mfma_f32_16x16x32_bf16 v[88:91], v[178:181], v[194:197], v[88:91]
	v_mfma_f32_16x16x32_bf16 v[76:79], v[170:173], v[202:205], v[76:79]
	v_mfma_f32_16x16x32_bf16 v[72:75], v[178:181], v[202:205], v[72:75]
	v_mfma_f32_16x16x32_bf16 v[68:71], v[170:173], v[214:217], v[68:71]
	v_mfma_f32_16x16x32_bf16 v[64:67], v[178:181], v[214:217], v[64:67]
	s_setprio 0
	s_barrier
; #define PG8_STAGE(bufoff, gbase, voff) do { _Pragma("unroll") for (int _i = 0; _i < 2; ++_i) \
;         __builtin_amdgcn_global_load_lds((const unsigned*)((const char*)(gbase) + (voff)[_i]), (PG8_LAS unsigned*)(lds + (bufoff) + ldsw + _i * 8192), 16, 0, 0); } while (0)
; #define PG8_LDA(dst, b, h) do { _Pragma("unroll") for (int m = 0; m < 4; ++m) _Pragma("unroll") for (int k = 0; k < 2; ++k) dst[m][k] = *(const PG8_LAS bf16x8*)(lds + PG8_SA(b, h) + aoff + m * 2048 + k * 1024); } while (0)
; #define PG8_MMA(ai, bj, At, Bt) do { __builtin_amdgcn_s_setprio(1); _Pragma("unroll") for (int m = 0; m < 4; ++m) _Pragma("unroll") for (int n = 0; n < 2; ++n) _Pragma("unroll") for (int k = 0; k < 2; ++k) \
;         acc[ai][bj][m][n] = __builtin_amdgcn_mfma_f32_16x16x32_bf16(Bt[n][k], At[m][k], acc[ai][bj][m][n], 0, 0, 0); __builtin_amdgcn_s_setprio(0); } while (0)
; #define PG8_WAIT_V(n) asm volatile("s_waitcnt vmcnt(" #n ")" ::: "memory")
; #define PG8_WAIT_L(n) asm volatile("s_waitcnt lgkmcnt(" #n ")" ::: "memory")
; #define PG8_BAR __builtin_amdgcn_s_barrier()
; #define PG8_SCHED __builtin_amdgcn_sched_barrier(0)
; template <class Epi, class Sched, bool ALIGN_EPI = false, bool SP2 = false>
; __device__ __forceinline__ void gemm_phase(PG8_LAS unsigned char* lds, const Gemm g, const Sched& S, const Epi& E, const int tid) {
;     ...
;             PG8_LDA(At, 1, 1); PG8_STAGE(PG8_SB(1, 0), b3, voffB); PG8_STAGE(PG8_SB(1, 1), b3 + hstepB, voffB); PG8_STAGE(PG8_SA(1, 0), a3, voffA);
;             PG8_WAIT_V(8); PG8_WAIT_L(0); PG8_BAR; PG8_MMA(1, 0, At, B0); PG8_MMA(1, 1, At, B1); PG8_BAR; PG8_SCHED;
	s_add_i32 s40, s65, s1
	v_lshl_add_u64 v[206:207], v[206:207], 0, s[14:15]
	s_mov_b32 m0, s40
	ds_read_b128 v[182:185], v149 offset:49152
	ds_read_b128 v[186:189], v149 offset:50176
	ds_read_b128 v[190:193], v149 offset:51200
	ds_read_b128 v[194:197], v149 offset:52224
	ds_read_b128 v[198:201], v149 offset:53248
	ds_read_b128 v[202:205], v149 offset:54272
	ds_read_b128 v[210:213], v149 offset:55296
	ds_read_b128 v[214:217], v149 offset:56320
	global_load_lds_dwordx4 v[206:207], off
	s_add_i32 m0, s40, 0x2000
	s_add_u32 s38, s38, 0x40080
	v_lshl_add_u64 v[206:207], v[218:219], 0, s[14:15]
	s_addc_u32 s39, s39, 0
	s_add_i32 s40, s66, s1
	global_load_lds_dwordx4 v[206:207], off
	v_lshl_add_u64 v[206:207], s[38:39], 0, v[130:131]
	s_mov_b32 m0, s40
	s_nop 0
	global_load_lds_dwordx4 v[206:207], off
	v_lshl_add_u64 v[206:207], s[38:39], 0, v[134:135]
	s_add_i32 m0, s40, 0x2000
	s_nop 0
	global_load_lds_dwordx4 v[206:207], off
	v_lshl_add_u64 v[206:207], v[220:221], 0, s[14:15]
	s_mov_b32 m0, s46
	s_nop 0
	global_load_lds_dwordx4 v[206:207], off
	v_lshl_add_u64 v[206:207], v[222:223], 0, s[14:15]
	s_mov_b32 m0, s47
	s_nop 0
	global_load_lds_dwordx4 v[206:207], off
	s_waitcnt vmcnt(8)
	s_waitcnt lgkmcnt(0)
	v_mfma_f32_16x16x32_bf16 v[60:63], v[150:153], v[182:185], v[60:63]
	v_mfma_f32_16x16x32_bf16 v[56:59], v[158:161], v[182:185], v[56:59]
	v_mfma_f32_16x16x32_bf16 v[52:55], v[150:153], v[190:193], v[52:55]
	v_mfma_f32_16x16x32_bf16 v[48:51], v[158:161], v[190:193], v[48:51]
	s_barrier
	s_setprio 1
	s_waitcnt lgkmcnt(0)
	v_mfma_f32_16x16x32_bf16 v[36:39], v[150:153], v[198:201], v[36:39]
	v_mfma_f32_16x16x32_bf16 v[32:35], v[158:161], v[198:201], v[32:35]
	v_mfma_f32_16x16x32_bf16 v[20:23], v[150:153], v[210:213], v[20:23]
	v_mfma_f32_16x16x32_bf16 v[16:19], v[158:161], v[210:213], v[16:19]
	v_mfma_f32_16x16x32_bf16 v[60:63], v[154:157], v[186:189], v[60:63]
	v_mfma_f32_16x16x32_bf16 v[56:59], v[162:165], v[186:189], v[56:59]
	v_mfma_f32_16x16x32_bf16 v[52:55], v[154:157], v[194:197], v[52:55]
	v_mfma_f32_16x16x32_bf16 v[48:51], v[162:165], v[194:197], v[48:51]
	v_mfma_f32_16x16x32_bf16 v[36:39], v[154:157], v[202:205], v[36:39]
	v_mfma_f32_16x16x32_bf16 v[32:35], v[162:165], v[202:205], v[32:35]
	v_mfma_f32_16x16x32_bf16 v[20:23], v[154:157], v[214:217], v[20:23]
	v_mfma_f32_16x16x32_bf16 v[16:19], v[162:165], v[214:217], v[16:19]
	s_setprio 0
	s_setprio 1
	v_mfma_f32_16x16x32_bf16 v[44:47], v[166:169], v[182:185], v[44:47]
	v_mfma_f32_16x16x32_bf16 v[40:43], v[174:177], v[182:185], v[40:43]
	v_mfma_f32_16x16x32_bf16 v[28:31], v[166:169], v[190:193], v[28:31]
	v_mfma_f32_16x16x32_bf16 v[24:27], v[174:177], v[190:193], v[24:27]
	v_mfma_f32_16x16x32_bf16 v[12:15], v[166:169], v[198:201], v[12:15]
	v_mfma_f32_16x16x32_bf16 v[8:11], v[174:177], v[198:201], v[8:11]
	v_mfma_f32_16x16x32_bf16 v[4:7], v[166:169], v[210:213], v[4:7]
	v_mfma_f32_16x16x32_bf16 v[0:3], v[174:177], v[210:213], v[0:3]
	v_mfma_f32_16x16x32_bf16 v[44:47], v[170:173], v[186:189], v[44:47]
	v_mfma_f32_16x16x32_bf16 v[40:43], v[178:181], v[186:189], v[40:43]
	v_mfma_f32_16x16x32_bf16 v[28:31], v[170:173], v[194:197], v[28:31]
	v_mfma_f32_16x16x32_bf16 v[24:27], v[178:181], v[194:197], v[24:27]
	v_mfma_f32_16x16x32_bf16 v[12:15], v[170:173], v[202:205], v[12:15]
	v_mfma_f32_16x16x32_bf16 v[8:11], v[178:181], v[202:205], v[8:11]
	v_mfma_f32_16x16x32_bf16 v[4:7], v[170:173], v[214:217], v[4:7]
	v_mfma_f32_16x16x32_bf16 v[0:3], v[178:181], v[214:217], v[0:3]
	s_setprio 0
	s_barrier
	s_add_i32 s64, s64, 2
	s_add_u32 s36, s36, 0x100
	s_addc_u32 s37, s37, 0
	s_add_u32 s62, s62, 0x100
	s_addc_u32 s63, s63, 0
	s_cmp_gt_u32 s64, 13
	s_cbranch_scc0 .LBB0_1517
	s_and_b64 vcc, exec, s[16:17]
	s_cbranch_vccz .LBB0_1520
	s_barrier

; #define PG8_STAGE(bufoff, gbase, voff) do { _Pragma("unroll") for (int _i = 0; _i < 2; ++_i) \
;         __builtin_amdgcn_global_load_lds((const unsigned*)((const char*)(gbase) + (voff)[_i]), (PG8_LAS unsigned*)(lds + (bufoff) + ldsw + _i * 8192), 16, 0, 0); } while (0)
; #define PG8_LDA(dst, b, h) do { _Pragma("unroll") for (int m = 0; m < 4; ++m) _Pragma("unroll") for (int k = 0; k < 2; ++k) dst[m][k] = *(const PG8_LAS bf16x8*)(lds + PG8_SA(b, h) + aoff + m * 2048 + k * 1024); } while (0)
; #define PG8_LDB(dst, b, h) do { _Pragma("unroll") for (int n = 0; n < 2; ++n) _Pragma("unroll") for (int k = 0; k < 2; ++k) dst[n][k] = *(const PG8_LAS bf16x8*)(lds + PG8_SB(b, h) + boff + n * 2048 + k * 1024); } while (0)
; #define PG8_MMA(ai, bj, At, Bt) do { __builtin_amdgcn_s_setprio(1); _Pragma("unroll") for (int m = 0; m < 4; ++m) _Pragma("unroll") for (int n = 0; n < 2; ++n) _Pragma("unroll") for (int k = 0; k < 2; ++k) \
;         acc[ai][bj][m][n] = __builtin_amdgcn_mfma_f32_16x16x32_bf16(Bt[n][k], At[m][k], acc[ai][bj][m][n], 0, 0, 0); __builtin_amdgcn_s_setprio(0); } while (0)
; #define PG8_WAIT_V(n) asm volatile("s_waitcnt vmcnt(" #n ")" ::: "memory")
; #define PG8_WAIT_L(n) asm volatile("s_waitcnt lgkmcnt(" #n ")" ::: "memory")
; template <class Epi, class Sched, bool ALIGN_EPI = false, bool SP2 = false>
; __device__ __forceinline__ void gemm_phase(PG8_LAS unsigned char* lds, const Gemm g, const Sched& S, const Epi& E, const int tid) {
;     ...
;             const bool last = (t == nt - 2);
;             const char* a1 = cA + (size_t)(t + 1) * kstep;
;             const char* a2 = last ? nA : cA + (size_t)(t + 2) * kstep; const char* b2 = last ? nB : cB + (size_t)(t + 2) * kstep;
;             const char* a3 = a2 + kstep; const char* b3 = b2 + kstep;
;             if (last && has_next) S.a_ready(nxt);
;             if constexpr (SP2) {
;             PG8_LDB(B0, 0, 0); PG8_LDB(B1, 0, 1); PG8_SCHED; PG8_LDA(At, 0, 0); PG8_STAGE(PG8_SA(1, 1), a1 + hstepA, voffA);
;             PG8_WAIT_V(8); PG8_WAIT_L(0); PG8_BAR; PG8_MMA(0, 0, At, B0); PG8_MMA(0, 1, At, B1); PG8_BAR; PG8_SCHED;
;             PG8_LDA(At, 0, 1); PG8_STAGE(PG8_SB(0, 0), b2, voffB); PG8_STAGE(PG8_SB(0, 1), b2 + hstepB, voffB); PG8_STAGE(PG8_SA(0, 0), a2, voffA);
;             PG8_WAIT_V(8); PG8_WAIT_L(0); PG8_BAR; PG8_MMA(1, 0, At, B0); PG8_MMA(1, 1, At, B1); PG8_BAR; PG8_SCHED;
.LBB0_1668:
	ds_read_b128 v[92:95], v213
	ds_read_b128 v[96:99], v213 offset:1024
	ds_read_b128 v[100:103], v213 offset:2048
	ds_read_b128 v[104:107], v213 offset:3072
	ds_read_b128 v[108:111], v214
	ds_read_b128 v[112:115], v214 offset:1024
	ds_read_b128 v[116:119], v214 offset:2048
	ds_read_b128 v[120:123], v214 offset:3072
	s_add_u32 s22, s8, 0xfffc0080
	s_addc_u32 s23, s9, -1
	s_cmp_eq_u32 s94, 12
	s_cselect_b32 s59, s7, s23
	s_cselect_b32 s58, s62, s22
	s_cselect_b32 s23, s63, s87
	s_cselect_b32 s22, s73, s85
	v_lshl_add_u64 v[224:225], s[8:9], 0, v[190:191]
	s_add_i32 m0, s37, 0xc000
	ds_read_b128 v[160:163], v215
	ds_read_b128 v[164:167], v215 offset:1024
	ds_read_b128 v[168:171], v215 offset:2048
	ds_read_b128 v[172:175], v215 offset:3072
	ds_read_b128 v[176:179], v215 offset:4096
	ds_read_b128 v[196:199], v215 offset:5120
	ds_read_b128 v[200:203], v215 offset:6144
	ds_read_b128 v[220:223], v215 offset:7168
	global_load_lds_dwordx4 v[224:225], off
	v_lshl_add_u64 v[224:225], s[8:9], 0, v[188:189]
	s_add_i32 m0, s37, 0xe000
	s_nop 0
	global_load_lds_dwordx4 v[224:225], off
	s_waitcnt vmcnt(8)
	s_waitcnt lgkmcnt(0)
	v_mfma_f32_16x16x32_bf16 v[156:159], v[92:95], v[160:163], v[156:159]
	v_mfma_f32_16x16x32_bf16 v[68:71], v[100:103], v[160:163], v[68:71]
	v_mfma_f32_16x16x32_bf16 v[148:151], v[92:95], v[168:171], v[148:151]
	v_mfma_f32_16x16x32_bf16 v[60:63], v[100:103], v[168:171], v[60:63]
	s_barrier
	s_setprio 1
	s_waitcnt lgkmcnt(0)
	v_mfma_f32_16x16x32_bf16 v[140:143], v[92:95], v[176:179], v[140:143]
	v_mfma_f32_16x16x32_bf16 v[52:55], v[100:103], v[176:179], v[52:55]
	v_mfma_f32_16x16x32_bf16 v[132:135], v[92:95], v[200:203], v[132:135]
	v_mfma_f32_16x16x32_bf16 v[44:47], v[100:103], v[200:203], v[44:47]
	v_mfma_f32_16x16x32_bf16 v[156:159], v[96:99], v[164:167], v[156:159]
	v_mfma_f32_16x16x32_bf16 v[68:71], v[104:107], v[164:167], v[68:71]
	v_mfma_f32_16x16x32_bf16 v[148:151], v[96:99], v[172:175], v[148:151]
	v_mfma_f32_16x16x32_bf16 v[60:63], v[104:107], v[172:175], v[60:63]
	v_mfma_f32_16x16x32_bf16 v[140:143], v[96:99], v[196:199], v[140:143]
	v_mfma_f32_16x16x32_bf16 v[52:55], v[104:107], v[196:199], v[52:55]
	v_mfma_f32_16x16x32_bf16 v[132:135], v[96:99], v[220:223], v[132:135]
	v_mfma_f32_16x16x32_bf16 v[44:47], v[104:107], v[220:223], v[44:47]
	s_setprio 0
	s_setprio 1
	v_mfma_f32_16x16x32_bf16 v[152:155], v[108:111], v[160:163], v[152:155]
	v_mfma_f32_16x16x32_bf16 v[64:67], v[116:119], v[160:163], v[64:67]
	v_mfma_f32_16x16x32_bf16 v[144:147], v[108:111], v[168:171], v[144:147]
	v_mfma_f32_16x16x32_bf16 v[56:59], v[116:119], v[168:171], v[56:59]
	v_mfma_f32_16x16x32_bf16 v[136:139], v[108:111], v[176:179], v[136:139]
	v_mfma_f32_16x16x32_bf16 v[48:51], v[116:119], v[176:179], v[48:51]
	v_mfma_f32_16x16x32_bf16 v[128:131], v[108:111], v[200:203], v[128:131]
	v_mfma_f32_16x16x32_bf16 v[40:43], v[116:119], v[200:203], v[40:43]
	v_mfma_f32_16x16x32_bf16 v[152:155], v[112:115], v[164:167], v[152:155]
	v_mfma_f32_16x16x32_bf16 v[64:67], v[120:123], v[164:167], v[64:67]
	v_mfma_f32_16x16x32_bf16 v[144:147], v[112:115], v[172:175], v[144:147]
	v_mfma_f32_16x16x32_bf16 v[56:59], v[120:123], v[172:175], v[56:59]
	v_mfma_f32_16x16x32_bf16 v[136:139], v[112:115], v[196:199], v[136:139]
	v_mfma_f32_16x16x32_bf16 v[48:51], v[120:123], v[196:199], v[48:51]
	v_mfma_f32_16x16x32_bf16 v[128:131], v[112:115], v[220:223], v[128:131]
	v_mfma_f32_16x16x32_bf16 v[40:43], v[120:123], v[220:223], v[40:43]
	s_setprio 0
	s_barrier
	s_add_i32 s95, s78, s33
	v_lshl_add_u64 v[224:225], s[22:23], 0, v[182:183]
	s_mov_b32 m0, s95
	ds_read_b128 v[160:163], v215 offset:16384
	ds_read_b128 v[164:167], v215 offset:17408
	ds_read_b128 v[168:171], v215 offset:18432
	ds_read_b128 v[172:175], v215 offset:19456
	ds_read_b128 v[176:179], v215 offset:20480
	ds_read_b128 v[196:199], v215 offset:21504
	ds_read_b128 v[200:203], v215 offset:22528
	ds_read_b128 v[220:223], v215 offset:23552
	global_load_lds_dwordx4 v[224:225], off
	s_add_i32 m0, s95, 0x2000
	s_add_u32 s96, s22, 0x40000
	v_lshl_add_u64 v[226:227], s[22:23], 0, v[186:187]
	s_addc_u32 s97, s23, 0
	s_add_i32 s95, s79, s33
	global_load_lds_dwordx4 v[226:227], off
	v_lshl_add_u64 v[228:229], s[96:97], 0, v[182:183]
	s_mov_b32 m0, s95
	v_lshl_add_u64 v[230:231], s[58:59], 0, v[184:185]
	global_load_lds_dwordx4 v[228:229], off
	v_lshl_add_u64 v[228:229], s[96:97], 0, v[186:187]
	s_add_i32 m0, s95, 0x2000
	s_nop 0
	global_load_lds_dwordx4 v[228:229], off
	v_lshl_add_u64 v[228:229], s[58:59], 0, v[180:181]
	s_mov_b32 m0, s37
	s_nop 0
	global_load_lds_dwordx4 v[228:229], off
	s_mov_b32 m0, s53
	s_nop 0
	global_load_lds_dwordx4 v[230:231], off
	s_waitcnt vmcnt(8)
	s_waitcnt lgkmcnt(0)
	v_mfma_f32_16x16x32_bf16 v[124:127], v[92:95], v[160:163], v[124:127]
	v_mfma_f32_16x16x32_bf16 v[36:39], v[100:103], v[160:163], v[36:39]
	v_mfma_f32_16x16x32_bf16 v[84:87], v[92:95], v[168:171], v[84:87]
	v_mfma_f32_16x16x32_bf16 v[28:31], v[100:103], v[168:171], v[28:31]
	s_barrier
; #define PG8_STAGE(bufoff, gbase, voff) do { _Pragma("unroll") for (int _i = 0; _i < 2; ++_i) \
;         __builtin_amdgcn_global_load_lds((const unsigned*)((const char*)(gbase) + (voff)[_i]), (PG8_LAS unsigned*)(lds + (bufoff) + ldsw + _i * 8192), 16, 0, 0); } while (0)
; #define PG8_LDA(dst, b, h) do { _Pragma("unroll") for (int m = 0; m < 4; ++m) _Pragma("unroll") for (int k = 0; k < 2; ++k) dst[m][k] = *(const PG8_LAS bf16x8*)(lds + PG8_SA(b, h) + aoff + m * 2048 + k * 1024); } while (0)
; #define PG8_LDB(dst, b, h) do { _Pragma("unroll") for (int n = 0; n < 2; ++n) _Pragma("unroll") for (int k = 0; k < 2; ++k) dst[n][k] = *(const PG8_LAS bf16x8*)(lds + PG8_SB(b, h) + boff + n * 2048 + k * 1024); } while (0)
; #define PG8_MMA(ai, bj, At, Bt) do { __builtin_amdgcn_s_setprio(1); _Pragma("unroll") for (int m = 0; m < 4; ++m) _Pragma("unroll") for (int n = 0; n < 2; ++n) _Pragma("unroll") for (int k = 0; k < 2; ++k) \
;         acc[ai][bj][m][n] = __builtin_amdgcn_mfma_f32_16x16x32_bf16(Bt[n][k], At[m][k], acc[ai][bj][m][n], 0, 0, 0); __builtin_amdgcn_s_setprio(0); } while (0)
; #define PG8_WAIT_V(n) asm volatile("s_waitcnt vmcnt(" #n ")" ::: "memory")
; #define PG8_WAIT_L(n) asm volatile("s_waitcnt lgkmcnt(" #n ")" ::: "memory")
; #define PG8_BAR __builtin_amdgcn_s_barrier()
; #define PG8_SCHED __builtin_amdgcn_sched_barrier(0)
; template <class Epi, class Sched, bool ALIGN_EPI = false, bool SP2 = false>
; __device__ __forceinline__ void gemm_phase(PG8_LAS unsigned char* lds, const Gemm g, const Sched& S, const Epi& E, const int tid) {
;     ...
;             PG8_WAIT_V(8); PG8_WAIT_L(0); PG8_BAR; PG8_MMA(1, 0, At, B0); PG8_MMA(1, 1, At, B1); PG8_BAR; PG8_SCHED;
;             PG8_LDB(B0, 1, 0); PG8_LDB(B1, 1, 1); PG8_SCHED; PG8_LDA(At, 1, 0); PG8_STAGE(PG8_SA(0, 1), a2 + hstepA, voffA);
;             PG8_WAIT_V(8); PG8_WAIT_L(0); PG8_BAR; PG8_MMA(0, 0, At, B0); PG8_MMA(0, 1, At, B1); PG8_BAR; PG8_SCHED;
	s_setprio 1
	s_waitcnt lgkmcnt(0)
	v_mfma_f32_16x16x32_bf16 v[76:79], v[92:95], v[176:179], v[76:79]
	v_mfma_f32_16x16x32_bf16 v[20:23], v[100:103], v[176:179], v[20:23]
	v_mfma_f32_16x16x32_bf16 v[12:15], v[92:95], v[200:203], v[12:15]
	v_mfma_f32_16x16x32_bf16 v[8:11], v[100:103], v[200:203], v[8:11]
	v_mfma_f32_16x16x32_bf16 v[124:127], v[96:99], v[164:167], v[124:127]
	v_mfma_f32_16x16x32_bf16 v[36:39], v[104:107], v[164:167], v[36:39]
	v_mfma_f32_16x16x32_bf16 v[84:87], v[96:99], v[172:175], v[84:87]
	v_mfma_f32_16x16x32_bf16 v[28:31], v[104:107], v[172:175], v[28:31]
	v_mfma_f32_16x16x32_bf16 v[76:79], v[96:99], v[196:199], v[76:79]
	v_mfma_f32_16x16x32_bf16 v[20:23], v[104:107], v[196:199], v[20:23]
	v_mfma_f32_16x16x32_bf16 v[12:15], v[96:99], v[220:223], v[12:15]
	v_mfma_f32_16x16x32_bf16 v[8:11], v[104:107], v[220:223], v[8:11]
	s_setprio 0
	s_setprio 1
	v_mfma_f32_16x16x32_bf16 v[88:91], v[108:111], v[160:163], v[88:91]
	v_mfma_f32_16x16x32_bf16 v[32:35], v[116:119], v[160:163], v[32:35]
	v_mfma_f32_16x16x32_bf16 v[80:83], v[108:111], v[168:171], v[80:83]
	v_mfma_f32_16x16x32_bf16 v[24:27], v[116:119], v[168:171], v[24:27]
	v_mfma_f32_16x16x32_bf16 v[72:75], v[108:111], v[176:179], v[72:75]
	v_mfma_f32_16x16x32_bf16 v[16:19], v[116:119], v[176:179], v[16:19]
	v_mfma_f32_16x16x32_bf16 v[4:7], v[108:111], v[200:203], v[4:7]
	v_mfma_f32_16x16x32_bf16 v[0:3], v[116:119], v[200:203], v[0:3]
	v_mfma_f32_16x16x32_bf16 v[88:91], v[112:115], v[164:167], v[88:91]
	v_mfma_f32_16x16x32_bf16 v[32:35], v[120:123], v[164:167], v[32:35]
	v_mfma_f32_16x16x32_bf16 v[80:83], v[112:115], v[172:175], v[80:83]
	v_mfma_f32_16x16x32_bf16 v[24:27], v[120:123], v[172:175], v[24:27]
	v_mfma_f32_16x16x32_bf16 v[72:75], v[112:115], v[196:199], v[72:75]
	v_mfma_f32_16x16x32_bf16 v[16:19], v[120:123], v[196:199], v[16:19]
	v_mfma_f32_16x16x32_bf16 v[4:7], v[112:115], v[220:223], v[4:7]
	v_mfma_f32_16x16x32_bf16 v[0:3], v[120:123], v[220:223], v[0:3]
	s_setprio 0
	s_barrier
	s_add_i32 s95, 0, 0x18000
	s_add_i32 s96, 0, 0x1c000
	v_add_u32_e32 v104, s95, v207
	v_add_u32_e32 v120, s96, v207
	ds_read_b128 v[92:95], v104
	ds_read_b128 v[96:99], v104 offset:1024
	ds_read_b128 v[100:103], v104 offset:2048
	ds_read_b128 v[104:107], v104 offset:3072
	ds_read_b128 v[108:111], v120
	ds_read_b128 v[112:115], v120 offset:1024
	ds_read_b128 v[116:119], v120 offset:2048
	ds_read_b128 v[120:123], v120 offset:3072
	s_add_u32 s58, s58, 0x40000
	s_addc_u32 s59, s59, 0
	s_mov_b32 m0, s57
	v_lshl_add_u64 v[232:233], s[58:59], 0, v[180:181]
	ds_read_b128 v[160:163], v215 offset:32768
	ds_read_b128 v[164:167], v215 offset:33792
	ds_read_b128 v[168:171], v215 offset:34816
	ds_read_b128 v[172:175], v215 offset:35840
	ds_read_b128 v[176:179], v215 offset:36864
	ds_read_b128 v[196:199], v215 offset:37888
	ds_read_b128 v[200:203], v215 offset:38912
	ds_read_b128 v[220:223], v215 offset:39936
	global_load_lds_dwordx4 v[232:233], off
	v_lshl_add_u64 v[232:233], s[58:59], 0, v[184:185]
	s_mov_b32 m0, s60
	s_nop 0
	global_load_lds_dwordx4 v[232:233], off
	s_waitcnt vmcnt(8)
	s_waitcnt lgkmcnt(0)
	v_mfma_f32_16x16x32_bf16 v[156:159], v[92:95], v[160:163], v[156:159]
	v_mfma_f32_16x16x32_bf16 v[68:71], v[100:103], v[160:163], v[68:71]
	v_mfma_f32_16x16x32_bf16 v[148:151], v[92:95], v[168:171], v[148:151]
	v_mfma_f32_16x16x32_bf16 v[60:63], v[100:103], v[168:171], v[60:63]
	s_barrier
	s_setprio 1
	s_waitcnt lgkmcnt(0)
	v_mfma_f32_16x16x32_bf16 v[140:143], v[92:95], v[176:179], v[140:143]
	v_mfma_f32_16x16x32_bf16 v[52:55], v[100:103], v[176:179], v[52:55]
	v_mfma_f32_16x16x32_bf16 v[132:135], v[92:95], v[200:203], v[132:135]
	v_mfma_f32_16x16x32_bf16 v[44:47], v[100:103], v[200:203], v[44:47]
	v_mfma_f32_16x16x32_bf16 v[156:159], v[96:99], v[164:167], v[156:159]
	v_mfma_f32_16x16x32_bf16 v[68:71], v[104:107], v[164:167], v[68:71]
	v_mfma_f32_16x16x32_bf16 v[148:151], v[96:99], v[172:175], v[148:151]
	v_mfma_f32_16x16x32_bf16 v[60:63], v[104:107], v[172:175], v[60:63]
	v_mfma_f32_16x16x32_bf16 v[140:143], v[96:99], v[196:199], v[140:143]
	v_mfma_f32_16x16x32_bf16 v[52:55], v[104:107], v[196:199], v[52:55]
	v_mfma_f32_16x16x32_bf16 v[132:135], v[96:99], v[220:223], v[132:135]
	v_mfma_f32_16x16x32_bf16 v[44:47], v[104:107], v[220:223], v[44:47]
	s_setprio 0
	s_setprio 1
	v_mfma_f32_16x16x32_bf16 v[152:155], v[108:111], v[160:163], v[152:155]
	v_mfma_f32_16x16x32_bf16 v[64:67], v[116:119], v[160:163], v[64:67]
	v_mfma_f32_16x16x32_bf16 v[144:147], v[108:111], v[168:171], v[144:147]
	v_mfma_f32_16x16x32_bf16 v[56:59], v[116:119], v[168:171], v[56:59]
	v_mfma_f32_16x16x32_bf16 v[136:139], v[108:111], v[176:179], v[136:139]
	v_mfma_f32_16x16x32_bf16 v[48:51], v[116:119], v[176:179], v[48:51]
	v_mfma_f32_16x16x32_bf16 v[128:131], v[108:111], v[200:203], v[128:131]
	v_mfma_f32_16x16x32_bf16 v[40:43], v[116:119], v[200:203], v[40:43]
	v_mfma_f32_16x16x32_bf16 v[152:155], v[112:115], v[164:167], v[152:155]
	v_mfma_f32_16x16x32_bf16 v[64:67], v[120:123], v[164:167], v[64:67]
	v_mfma_f32_16x16x32_bf16 v[144:147], v[112:115], v[172:175], v[144:147]
	v_mfma_f32_16x16x32_bf16 v[56:59], v[120:123], v[172:175], v[56:59]
	v_mfma_f32_16x16x32_bf16 v[136:139], v[112:115], v[196:199], v[136:139]
	v_mfma_f32_16x16x32_bf16 v[48:51], v[120:123], v[196:199], v[48:51]
	v_mfma_f32_16x16x32_bf16 v[128:131], v[112:115], v[220:223], v[128:131]
	v_mfma_f32_16x16x32_bf16 v[40:43], v[120:123], v[220:223], v[40:43]
	s_setprio 0
	s_barrier
; #define PG8_STAGE(bufoff, gbase, voff) do { _Pragma("unroll") for (int _i = 0; _i < 2; ++_i) \
;         __builtin_amdgcn_global_load_lds((const unsigned*)((const char*)(gbase) + (voff)[_i]), (PG8_LAS unsigned*)(lds + (bufoff) + ldsw + _i * 8192), 16, 0, 0); } while (0)
; #define PG8_LDA(dst, b, h) do { _Pragma("unroll") for (int m = 0; m < 4; ++m) _Pragma("unroll") for (int k = 0; k < 2; ++k) dst[m][k] = *(const PG8_LAS bf16x8*)(lds + PG8_SA(b, h) + aoff + m * 2048 + k * 1024); } while (0)
; #define PG8_MMA(ai, bj, At, Bt) do { __builtin_amdgcn_s_setprio(1); _Pragma("unroll") for (int m = 0; m < 4; ++m) _Pragma("unroll") for (int n = 0; n < 2; ++n) _Pragma("unroll") for (int k = 0; k < 2; ++k) \
;         acc[ai][bj][m][n] = __builtin_amdgcn_mfma_f32_16x16x32_bf16(Bt[n][k], At[m][k], acc[ai][bj][m][n], 0, 0, 0); __builtin_amdgcn_s_setprio(0); } while (0)
; #define PG8_WAIT_V(n) asm volatile("s_waitcnt vmcnt(" #n ")" ::: "memory")
; #define PG8_WAIT_L(n) asm volatile("s_waitcnt lgkmcnt(" #n ")" ::: "memory")
; #define PG8_BAR __builtin_amdgcn_s_barrier()
; #define PG8_SCHED __builtin_amdgcn_sched_barrier(0)
; template <class Epi, class Sched, bool ALIGN_EPI = false, bool SP2 = false>
; __device__ __forceinline__ void gemm_phase(PG8_LAS unsigned char* lds, const Gemm g, const Sched& S, const Epi& E, const int tid) {
;     ...
;             PG8_LDA(At, 1, 1); PG8_STAGE(PG8_SB(1, 0), b3, voffB); PG8_STAGE(PG8_SB(1, 1), b3 + hstepB, voffB); PG8_STAGE(PG8_SA(1, 0), a3, voffA);
;             PG8_WAIT_V(8); PG8_WAIT_L(0); PG8_BAR; PG8_MMA(1, 0, At, B0); PG8_MMA(1, 1, At, B1); PG8_BAR; PG8_SCHED;
	s_add_i32 s58, s95, s33
	v_lshl_add_u64 v[224:225], v[224:225], 0, s[64:65]
	s_mov_b32 m0, s58
	ds_read_b128 v[160:163], v215 offset:49152
	ds_read_b128 v[164:167], v215 offset:50176
	ds_read_b128 v[168:171], v215 offset:51200
	ds_read_b128 v[172:175], v215 offset:52224
	ds_read_b128 v[176:179], v215 offset:53248
	ds_read_b128 v[196:199], v215 offset:54272
	ds_read_b128 v[200:203], v215 offset:55296
	ds_read_b128 v[220:223], v215 offset:56320
	global_load_lds_dwordx4 v[224:225], off
	s_add_i32 m0, s58, 0x2000
	s_add_u32 s22, s22, 0x40080
	v_lshl_add_u64 v[224:225], v[226:227], 0, s[64:65]
	s_addc_u32 s23, s23, 0
	s_add_i32 s58, s96, s33
	global_load_lds_dwordx4 v[224:225], off
	v_lshl_add_u64 v[224:225], s[22:23], 0, v[182:183]
	s_mov_b32 m0, s58
	s_nop 0
	global_load_lds_dwordx4 v[224:225], off
	v_lshl_add_u64 v[224:225], s[22:23], 0, v[186:187]
	s_add_i32 m0, s58, 0x2000
	s_nop 0
	global_load_lds_dwordx4 v[224:225], off
	v_lshl_add_u64 v[224:225], v[228:229], 0, s[64:65]
	s_mov_b32 m0, s61
	s_nop 0
	global_load_lds_dwordx4 v[224:225], off
	v_lshl_add_u64 v[224:225], v[230:231], 0, s[64:65]
	s_mov_b32 m0, s81
	s_nop 0
	global_load_lds_dwordx4 v[224:225], off
	s_waitcnt vmcnt(8)
	s_waitcnt lgkmcnt(0)
	v_mfma_f32_16x16x32_bf16 v[124:127], v[92:95], v[160:163], v[124:127]
	v_mfma_f32_16x16x32_bf16 v[36:39], v[100:103], v[160:163], v[36:39]
	v_mfma_f32_16x16x32_bf16 v[84:87], v[92:95], v[168:171], v[84:87]
	v_mfma_f32_16x16x32_bf16 v[28:31], v[100:103], v[168:171], v[28:31]
	s_barrier
	s_setprio 1
	s_waitcnt lgkmcnt(0)
	v_mfma_f32_16x16x32_bf16 v[76:79], v[92:95], v[176:179], v[76:79]
	v_mfma_f32_16x16x32_bf16 v[20:23], v[100:103], v[176:179], v[20:23]
	v_mfma_f32_16x16x32_bf16 v[12:15], v[92:95], v[200:203], v[12:15]
	v_mfma_f32_16x16x32_bf16 v[8:11], v[100:103], v[200:203], v[8:11]
	v_mfma_f32_16x16x32_bf16 v[124:127], v[96:99], v[164:167], v[124:127]
	v_mfma_f32_16x16x32_bf16 v[36:39], v[104:107], v[164:167], v[36:39]
	v_mfma_f32_16x16x32_bf16 v[84:87], v[96:99], v[172:175], v[84:87]
	v_mfma_f32_16x16x32_bf16 v[28:31], v[104:107], v[172:175], v[28:31]
	v_mfma_f32_16x16x32_bf16 v[76:79], v[96:99], v[196:199], v[76:79]
	v_mfma_f32_16x16x32_bf16 v[20:23], v[104:107], v[196:199], v[20:23]
	v_mfma_f32_16x16x32_bf16 v[12:15], v[96:99], v[220:223], v[12:15]
	v_mfma_f32_16x16x32_bf16 v[8:11], v[104:107], v[220:223], v[8:11]
	s_setprio 0
	s_setprio 1
	v_mfma_f32_16x16x32_bf16 v[88:91], v[108:111], v[160:163], v[88:91]
	v_mfma_f32_16x16x32_bf16 v[32:35], v[116:119], v[160:163], v[32:35]
	v_mfma_f32_16x16x32_bf16 v[80:83], v[108:111], v[168:171], v[80:83]
	v_mfma_f32_16x16x32_bf16 v[24:27], v[116:119], v[168:171], v[24:27]
	v_mfma_f32_16x16x32_bf16 v[72:75], v[108:111], v[176:179], v[72:75]
	v_mfma_f32_16x16x32_bf16 v[16:19], v[116:119], v[176:179], v[16:19]
	v_mfma_f32_16x16x32_bf16 v[4:7], v[108:111], v[200:203], v[4:7]
	v_mfma_f32_16x16x32_bf16 v[0:3], v[116:119], v[200:203], v[0:3]
	v_mfma_f32_16x16x32_bf16 v[88:91], v[112:115], v[164:167], v[88:91]
	v_mfma_f32_16x16x32_bf16 v[32:35], v[120:123], v[164:167], v[32:35]
	v_mfma_f32_16x16x32_bf16 v[80:83], v[112:115], v[172:175], v[80:83]
	v_mfma_f32_16x16x32_bf16 v[24:27], v[120:123], v[172:175], v[24:27]
	v_mfma_f32_16x16x32_bf16 v[72:75], v[112:115], v[196:199], v[72:75]
	v_mfma_f32_16x16x32_bf16 v[16:19], v[120:123], v[196:199], v[16:19]
	v_mfma_f32_16x16x32_bf16 v[4:7], v[112:115], v[220:223], v[4:7]
	v_mfma_f32_16x16x32_bf16 v[0:3], v[120:123], v[220:223], v[0:3]
	s_setprio 0
	s_barrier
	s_add_i32 s94, s94, 2
	s_add_u32 s85, s85, 0x100
	s_addc_u32 s87, s87, 0
	s_add_u32 s8, s8, 0x100
	s_addc_u32 s9, s9, 0
	s_cmp_gt_u32 s94, 13
	s_cbranch_scc0 .LBB0_1668
	s_and_b64 vcc, exec, s[66:67]
	s_cbranch_vccz .LBB0_1671
	s_barrier

; #define PG8_STAGE(bufoff, gbase, voff) do { _Pragma("unroll") for (int _i = 0; _i < 2; ++_i) \
;         __builtin_amdgcn_global_load_lds((const unsigned*)((const char*)(gbase) + (voff)[_i]), (PG8_LAS unsigned*)(lds + (bufoff) + ldsw + _i * 8192), 16, 0, 0); } while (0)
; #define PG8_LDA(dst, b, h) do { _Pragma("unroll") for (int m = 0; m < 4; ++m) _Pragma("unroll") for (int k = 0; k < 2; ++k) dst[m][k] = *(const PG8_LAS bf16x8*)(lds + PG8_SA(b, h) + aoff + m * 2048 + k * 1024); } while (0)
; #define PG8_LDB(dst, b, h) do { _Pragma("unroll") for (int n = 0; n < 2; ++n) _Pragma("unroll") for (int k = 0; k < 2; ++k) dst[n][k] = *(const PG8_LAS bf16x8*)(lds + PG8_SB(b, h) + boff + n * 2048 + k * 1024); } while (0)
; #define PG8_MMA(ai, bj, At, Bt) do { __builtin_amdgcn_s_setprio(1); _Pragma("unroll") for (int m = 0; m < 4; ++m) _Pragma("unroll") for (int n = 0; n < 2; ++n) _Pragma("unroll") for (int k = 0; k < 2; ++k) \
;         acc[ai][bj][m][n] = __builtin_amdgcn_mfma_f32_16x16x32_bf16(Bt[n][k], At[m][k], acc[ai][bj][m][n], 0, 0, 0); __builtin_amdgcn_s_setprio(0); } while (0)
; #define PG8_WAIT_V(n) asm volatile("s_waitcnt vmcnt(" #n ")" ::: "memory")
; #define PG8_WAIT_L(n) asm volatile("s_waitcnt lgkmcnt(" #n ")" ::: "memory")
; template <class Epi, class Sched, bool ALIGN_EPI = false, bool SP2 = false>
; __device__ __forceinline__ void gemm_phase(PG8_LAS unsigned char* lds, const Gemm g, const Sched& S, const Epi& E, const int tid) {
;     ...
;             const bool last = (t == nt - 2);
;             const char* a1 = cA + (size_t)(t + 1) * kstep;
;             const char* a2 = last ? nA : cA + (size_t)(t + 2) * kstep; const char* b2 = last ? nB : cB + (size_t)(t + 2) * kstep;
;             const char* a3 = a2 + kstep; const char* b3 = b2 + kstep;
;             if (last && has_next) S.a_ready(nxt);
;             if constexpr (SP2) {
;             PG8_LDB(B0, 0, 0); PG8_LDB(B1, 0, 1); PG8_SCHED; PG8_LDA(At, 0, 0); PG8_STAGE(PG8_SA(1, 1), a1 + hstepA, voffA);
;             PG8_WAIT_V(8); PG8_WAIT_L(0); PG8_BAR; PG8_MMA(0, 0, At, B0); PG8_MMA(0, 1, At, B1); PG8_BAR; PG8_SCHED;
;             PG8_LDA(At, 0, 1); PG8_STAGE(PG8_SB(0, 0), b2, voffB); PG8_STAGE(PG8_SB(0, 1), b2 + hstepB, voffB); PG8_STAGE(PG8_SA(0, 0), a2, voffA);
;             PG8_WAIT_V(8); PG8_WAIT_L(0); PG8_BAR; PG8_MMA(1, 0, At, B0); PG8_MMA(1, 1, At, B1); PG8_BAR; PG8_SCHED;
.LBB0_2016:
	ds_read_b128 v[150:153], v147
	ds_read_b128 v[154:157], v147 offset:1024
	ds_read_b128 v[158:161], v147 offset:2048
	ds_read_b128 v[162:165], v147 offset:3072
	ds_read_b128 v[166:169], v148
	ds_read_b128 v[170:173], v148 offset:1024
	ds_read_b128 v[174:177], v148 offset:2048
	ds_read_b128 v[178:181], v148 offset:3072
	s_add_u32 s30, s28, 0x100
	s_addc_u32 s31, s29, 0
	s_cmp_eq_u32 s62, 40
	s_cselect_b32 s37, s9, s31
	s_cselect_b32 s36, s8, s30
	s_cselect_b32 s35, s27, s61
	s_cselect_b32 s34, s26, s60
	v_lshl_add_u64 v[206:207], s[28:29], 0, v[138:139]
	s_add_i32 m0, s38, 0xc000
	ds_read_b128 v[182:185], v149
	ds_read_b128 v[186:189], v149 offset:1024
	ds_read_b128 v[190:193], v149 offset:2048
	ds_read_b128 v[194:197], v149 offset:3072
	ds_read_b128 v[198:201], v149 offset:4096
	ds_read_b128 v[202:205], v149 offset:5120
	ds_read_b128 v[210:213], v149 offset:6144
	ds_read_b128 v[214:217], v149 offset:7168
	global_load_lds_dwordx4 v[206:207], off
	v_lshl_add_u64 v[206:207], s[28:29], 0, v[136:137]
	s_add_i32 m0, s38, 0xe000
	s_nop 0
	global_load_lds_dwordx4 v[206:207], off
	s_waitcnt vmcnt(8)
	s_waitcnt lgkmcnt(0)
	v_mfma_f32_16x16x32_bf16 v[124:127], v[150:153], v[182:185], v[124:127]
	v_mfma_f32_16x16x32_bf16 v[120:123], v[158:161], v[182:185], v[120:123]
	v_mfma_f32_16x16x32_bf16 v[116:119], v[150:153], v[190:193], v[116:119]
	v_mfma_f32_16x16x32_bf16 v[112:115], v[158:161], v[190:193], v[112:115]
	s_barrier
	s_setprio 1
	s_waitcnt lgkmcnt(0)
	v_mfma_f32_16x16x32_bf16 v[100:103], v[150:153], v[198:201], v[100:103]
	v_mfma_f32_16x16x32_bf16 v[96:99], v[158:161], v[198:201], v[96:99]
	v_mfma_f32_16x16x32_bf16 v[84:87], v[150:153], v[210:213], v[84:87]
	v_mfma_f32_16x16x32_bf16 v[80:83], v[158:161], v[210:213], v[80:83]
	v_mfma_f32_16x16x32_bf16 v[124:127], v[154:157], v[186:189], v[124:127]
	v_mfma_f32_16x16x32_bf16 v[120:123], v[162:165], v[186:189], v[120:123]
	v_mfma_f32_16x16x32_bf16 v[116:119], v[154:157], v[194:197], v[116:119]
	v_mfma_f32_16x16x32_bf16 v[112:115], v[162:165], v[194:197], v[112:115]
	v_mfma_f32_16x16x32_bf16 v[100:103], v[154:157], v[202:205], v[100:103]
	v_mfma_f32_16x16x32_bf16 v[96:99], v[162:165], v[202:205], v[96:99]
	v_mfma_f32_16x16x32_bf16 v[84:87], v[154:157], v[214:217], v[84:87]
	v_mfma_f32_16x16x32_bf16 v[80:83], v[162:165], v[214:217], v[80:83]
	s_setprio 0
	s_setprio 1
	v_mfma_f32_16x16x32_bf16 v[108:111], v[166:169], v[182:185], v[108:111]
	v_mfma_f32_16x16x32_bf16 v[104:107], v[174:177], v[182:185], v[104:107]
	v_mfma_f32_16x16x32_bf16 v[92:95], v[166:169], v[190:193], v[92:95]
	v_mfma_f32_16x16x32_bf16 v[88:91], v[174:177], v[190:193], v[88:91]
	v_mfma_f32_16x16x32_bf16 v[76:79], v[166:169], v[198:201], v[76:79]
	v_mfma_f32_16x16x32_bf16 v[72:75], v[174:177], v[198:201], v[72:75]
	v_mfma_f32_16x16x32_bf16 v[68:71], v[166:169], v[210:213], v[68:71]
	v_mfma_f32_16x16x32_bf16 v[64:67], v[174:177], v[210:213], v[64:67]
	v_mfma_f32_16x16x32_bf16 v[108:111], v[170:173], v[186:189], v[108:111]
	v_mfma_f32_16x16x32_bf16 v[104:107], v[178:181], v[186:189], v[104:107]
	v_mfma_f32_16x16x32_bf16 v[92:95], v[170:173], v[194:197], v[92:95]
	v_mfma_f32_16x16x32_bf16 v[88:91], v[178:181], v[194:197], v[88:91]
	v_mfma_f32_16x16x32_bf16 v[76:79], v[170:173], v[202:205], v[76:79]
	v_mfma_f32_16x16x32_bf16 v[72:75], v[178:181], v[202:205], v[72:75]
	v_mfma_f32_16x16x32_bf16 v[68:71], v[170:173], v[214:217], v[68:71]
	v_mfma_f32_16x16x32_bf16 v[64:67], v[178:181], v[214:217], v[64:67]
	s_setprio 0
	s_barrier
	s_add_i32 s28, s46, s33
	v_lshl_add_u64 v[206:207], s[34:35], 0, v[130:131]
	s_mov_b32 m0, s28
	ds_read_b128 v[182:185], v149 offset:16384
	ds_read_b128 v[186:189], v149 offset:17408
	ds_read_b128 v[190:193], v149 offset:18432
	ds_read_b128 v[194:197], v149 offset:19456
	ds_read_b128 v[198:201], v149 offset:20480
	ds_read_b128 v[202:205], v149 offset:21504
	ds_read_b128 v[210:213], v149 offset:22528
	ds_read_b128 v[214:217], v149 offset:23552
	global_load_lds_dwordx4 v[206:207], off
	s_add_i32 m0, s28, 0x2000
	s_add_u32 s28, s34, 0xb0000
	v_lshl_add_u64 v[218:219], s[34:35], 0, v[134:135]
	s_addc_u32 s29, s35, 0
	s_add_i32 s63, s47, s33
	global_load_lds_dwordx4 v[218:219], off
	v_lshl_add_u64 v[220:221], s[28:29], 0, v[130:131]
	s_mov_b32 m0, s63
	v_lshl_add_u64 v[222:223], s[36:37], 0, v[132:133]
	global_load_lds_dwordx4 v[220:221], off
	v_lshl_add_u64 v[220:221], s[28:29], 0, v[134:135]
	s_add_i32 m0, s63, 0x2000
	s_nop 0
	global_load_lds_dwordx4 v[220:221], off
	v_lshl_add_u64 v[220:221], s[36:37], 0, v[128:129]
	s_mov_b32 m0, s38
	s_nop 0
	global_load_lds_dwordx4 v[220:221], off
	s_mov_b32 m0, s39
	s_nop 0
	global_load_lds_dwordx4 v[222:223], off
	s_waitcnt vmcnt(8)
	s_waitcnt lgkmcnt(0)
	v_mfma_f32_16x16x32_bf16 v[60:63], v[150:153], v[182:185], v[60:63]
	v_mfma_f32_16x16x32_bf16 v[56:59], v[158:161], v[182:185], v[56:59]
	v_mfma_f32_16x16x32_bf16 v[52:55], v[150:153], v[190:193], v[52:55]
	v_mfma_f32_16x16x32_bf16 v[48:51], v[158:161], v[190:193], v[48:51]
	s_barrier
; #define PG8_STAGE(bufoff, gbase, voff) do { _Pragma("unroll") for (int _i = 0; _i < 2; ++_i) \
;         __builtin_amdgcn_global_load_lds((const unsigned*)((const char*)(gbase) + (voff)[_i]), (PG8_LAS unsigned*)(lds + (bufoff) + ldsw + _i * 8192), 16, 0, 0); } while (0)
; #define PG8_LDA(dst, b, h) do { _Pragma("unroll") for (int m = 0; m < 4; ++m) _Pragma("unroll") for (int k = 0; k < 2; ++k) dst[m][k] = *(const PG8_LAS bf16x8*)(lds + PG8_SA(b, h) + aoff + m * 2048 + k * 1024); } while (0)
; #define PG8_LDB(dst, b, h) do { _Pragma("unroll") for (int n = 0; n < 2; ++n) _Pragma("unroll") for (int k = 0; k < 2; ++k) dst[n][k] = *(const PG8_LAS bf16x8*)(lds + PG8_SB(b, h) + boff + n * 2048 + k * 1024); } while (0)
; #define PG8_MMA(ai, bj, At, Bt) do { __builtin_amdgcn_s_setprio(1); _Pragma("unroll") for (int m = 0; m < 4; ++m) _Pragma("unroll") for (int n = 0; n < 2; ++n) _Pragma("unroll") for (int k = 0; k < 2; ++k) \
;         acc[ai][bj][m][n] = __builtin_amdgcn_mfma_f32_16x16x32_bf16(Bt[n][k], At[m][k], acc[ai][bj][m][n], 0, 0, 0); __builtin_amdgcn_s_setprio(0); } while (0)
; #define PG8_WAIT_V(n) asm volatile("s_waitcnt vmcnt(" #n ")" ::: "memory")
; #define PG8_WAIT_L(n) asm volatile("s_waitcnt lgkmcnt(" #n ")" ::: "memory")
; #define PG8_BAR __builtin_amdgcn_s_barrier()
; #define PG8_SCHED __builtin_amdgcn_sched_barrier(0)
; template <class Epi, class Sched, bool ALIGN_EPI = false, bool SP2 = false>
; __device__ __forceinline__ void gemm_phase(PG8_LAS unsigned char* lds, const Gemm g, const Sched& S, const Epi& E, const int tid) {
;     ...
;             PG8_WAIT_V(8); PG8_WAIT_L(0); PG8_BAR; PG8_MMA(1, 0, At, B0); PG8_MMA(1, 1, At, B1); PG8_BAR; PG8_SCHED;
;             PG8_LDB(B0, 1, 0); PG8_LDB(B1, 1, 1); PG8_SCHED; PG8_LDA(At, 1, 0); PG8_STAGE(PG8_SA(0, 1), a2 + hstepA, voffA);
;             PG8_WAIT_V(8); PG8_WAIT_L(0); PG8_BAR; PG8_MMA(0, 0, At, B0); PG8_MMA(0, 1, At, B1); PG8_BAR; PG8_SCHED;
	s_setprio 1
	s_waitcnt lgkmcnt(0)
	v_mfma_f32_16x16x32_bf16 v[36:39], v[150:153], v[198:201], v[36:39]
	v_mfma_f32_16x16x32_bf16 v[32:35], v[158:161], v[198:201], v[32:35]
	v_mfma_f32_16x16x32_bf16 v[20:23], v[150:153], v[210:213], v[20:23]
	v_mfma_f32_16x16x32_bf16 v[16:19], v[158:161], v[210:213], v[16:19]
	v_mfma_f32_16x16x32_bf16 v[60:63], v[154:157], v[186:189], v[60:63]
	v_mfma_f32_16x16x32_bf16 v[56:59], v[162:165], v[186:189], v[56:59]
	v_mfma_f32_16x16x32_bf16 v[52:55], v[154:157], v[194:197], v[52:55]
	v_mfma_f32_16x16x32_bf16 v[48:51], v[162:165], v[194:197], v[48:51]
	v_mfma_f32_16x16x32_bf16 v[36:39], v[154:157], v[202:205], v[36:39]
	v_mfma_f32_16x16x32_bf16 v[32:35], v[162:165], v[202:205], v[32:35]
	v_mfma_f32_16x16x32_bf16 v[20:23], v[154:157], v[214:217], v[20:23]
	v_mfma_f32_16x16x32_bf16 v[16:19], v[162:165], v[214:217], v[16:19]
	s_setprio 0
	s_setprio 1
	v_mfma_f32_16x16x32_bf16 v[44:47], v[166:169], v[182:185], v[44:47]
	v_mfma_f32_16x16x32_bf16 v[40:43], v[174:177], v[182:185], v[40:43]
	v_mfma_f32_16x16x32_bf16 v[28:31], v[166:169], v[190:193], v[28:31]
	v_mfma_f32_16x16x32_bf16 v[24:27], v[174:177], v[190:193], v[24:27]
	v_mfma_f32_16x16x32_bf16 v[12:15], v[166:169], v[198:201], v[12:15]
	v_mfma_f32_16x16x32_bf16 v[8:11], v[174:177], v[198:201], v[8:11]
	v_mfma_f32_16x16x32_bf16 v[4:7], v[166:169], v[210:213], v[4:7]
	v_mfma_f32_16x16x32_bf16 v[0:3], v[174:177], v[210:213], v[0:3]
	v_mfma_f32_16x16x32_bf16 v[44:47], v[170:173], v[186:189], v[44:47]
	v_mfma_f32_16x16x32_bf16 v[40:43], v[178:181], v[186:189], v[40:43]
	v_mfma_f32_16x16x32_bf16 v[28:31], v[170:173], v[194:197], v[28:31]
	v_mfma_f32_16x16x32_bf16 v[24:27], v[178:181], v[194:197], v[24:27]
	v_mfma_f32_16x16x32_bf16 v[12:15], v[170:173], v[202:205], v[12:15]
	v_mfma_f32_16x16x32_bf16 v[8:11], v[178:181], v[202:205], v[8:11]
	v_mfma_f32_16x16x32_bf16 v[4:7], v[170:173], v[214:217], v[4:7]
	v_mfma_f32_16x16x32_bf16 v[0:3], v[178:181], v[214:217], v[0:3]
	s_setprio 0
	s_barrier
	s_add_i32 s63, 0, 0x18000
	s_add_i32 s64, 0, 0x1c000
	v_add_u32_e32 v162, s63, v145
	v_add_u32_e32 v178, s64, v145
	ds_read_b128 v[150:153], v162
	ds_read_b128 v[154:157], v162 offset:1024
	ds_read_b128 v[158:161], v162 offset:2048
	ds_read_b128 v[162:165], v162 offset:3072
	ds_read_b128 v[166:169], v178
	ds_read_b128 v[170:173], v178 offset:1024
	ds_read_b128 v[174:177], v178 offset:2048
	ds_read_b128 v[178:181], v178 offset:3072
	s_add_u32 s28, s36, 0xb0000
	s_addc_u32 s29, s37, 0
	s_mov_b32 m0, s40
	v_lshl_add_u64 v[224:225], s[28:29], 0, v[128:129]
	ds_read_b128 v[182:185], v149 offset:32768
	ds_read_b128 v[186:189], v149 offset:33792
	ds_read_b128 v[190:193], v149 offset:34816
	ds_read_b128 v[194:197], v149 offset:35840
	ds_read_b128 v[198:201], v149 offset:36864
	ds_read_b128 v[202:205], v149 offset:37888
	ds_read_b128 v[210:213], v149 offset:38912
	ds_read_b128 v[214:217], v149 offset:39936
	global_load_lds_dwordx4 v[224:225], off
	v_lshl_add_u64 v[224:225], s[28:29], 0, v[132:133]
	s_mov_b32 m0, s41
	s_nop 0
	global_load_lds_dwordx4 v[224:225], off
	s_waitcnt vmcnt(8)
	s_waitcnt lgkmcnt(0)
	v_mfma_f32_16x16x32_bf16 v[124:127], v[150:153], v[182:185], v[124:127]
	v_mfma_f32_16x16x32_bf16 v[120:123], v[158:161], v[182:185], v[120:123]
	v_mfma_f32_16x16x32_bf16 v[116:119], v[150:153], v[190:193], v[116:119]
	v_mfma_f32_16x16x32_bf16 v[112:115], v[158:161], v[190:193], v[112:115]
	s_barrier
	s_setprio 1
	s_waitcnt lgkmcnt(0)
	v_mfma_f32_16x16x32_bf16 v[100:103], v[150:153], v[198:201], v[100:103]
	v_mfma_f32_16x16x32_bf16 v[96:99], v[158:161], v[198:201], v[96:99]
	v_mfma_f32_16x16x32_bf16 v[84:87], v[150:153], v[210:213], v[84:87]
	v_mfma_f32_16x16x32_bf16 v[80:83], v[158:161], v[210:213], v[80:83]
	v_mfma_f32_16x16x32_bf16 v[124:127], v[154:157], v[186:189], v[124:127]
	v_mfma_f32_16x16x32_bf16 v[120:123], v[162:165], v[186:189], v[120:123]
	v_mfma_f32_16x16x32_bf16 v[116:119], v[154:157], v[194:197], v[116:119]
	v_mfma_f32_16x16x32_bf16 v[112:115], v[162:165], v[194:197], v[112:115]
	v_mfma_f32_16x16x32_bf16 v[100:103], v[154:157], v[202:205], v[100:103]
	v_mfma_f32_16x16x32_bf16 v[96:99], v[162:165], v[202:205], v[96:99]
	v_mfma_f32_16x16x32_bf16 v[84:87], v[154:157], v[214:217], v[84:87]
	v_mfma_f32_16x16x32_bf16 v[80:83], v[162:165], v[214:217], v[80:83]
	s_setprio 0
	s_setprio 1
	v_mfma_f32_16x16x32_bf16 v[108:111], v[166:169], v[182:185], v[108:111]
	v_mfma_f32_16x16x32_bf16 v[104:107], v[174:177], v[182:185], v[104:107]
	v_mfma_f32_16x16x32_bf16 v[92:95], v[166:169], v[190:193], v[92:95]
	v_mfma_f32_16x16x32_bf16 v[88:91], v[174:177], v[190:193], v[88:91]
	v_mfma_f32_16x16x32_bf16 v[76:79], v[166:169], v[198:201], v[76:79]
	v_mfma_f32_16x16x32_bf16 v[72:75], v[174:177], v[198:201], v[72:75]
	v_mfma_f32_16x16x32_bf16 v[68:71], v[166:169], v[210:213], v[68:71]
	v_mfma_f32_16x16x32_bf16 v[64:67], v[174:177], v[210:213], v[64:67]
	v_mfma_f32_16x16x32_bf16 v[108:111], v[170:173], v[186:189], v[108:111]
	v_mfma_f32_16x16x32_bf16 v[104:107], v[178:181], v[186:189], v[104:107]
	v_mfma_f32_16x16x32_bf16 v[92:95], v[170:173], v[194:197], v[92:95]
	v_mfma_f32_16x16x32_bf16 v[88:91], v[178:181], v[194:197], v[88:91]
	v_mfma_f32_16x16x32_bf16 v[76:79], v[170:173], v[202:205], v[76:79]
	v_mfma_f32_16x16x32_bf16 v[72:75], v[178:181], v[202:205], v[72:75]
	v_mfma_f32_16x16x32_bf16 v[68:71], v[170:173], v[214:217], v[68:71]
	v_mfma_f32_16x16x32_bf16 v[64:67], v[178:181], v[214:217], v[64:67]
	s_setprio 0
	s_barrier
; #define PG8_STAGE(bufoff, gbase, voff) do { _Pragma("unroll") for (int _i = 0; _i < 2; ++_i) \
;         __builtin_amdgcn_global_load_lds((const unsigned*)((const char*)(gbase) + (voff)[_i]), (PG8_LAS unsigned*)(lds + (bufoff) + ldsw + _i * 8192), 16, 0, 0); } while (0)
; #define PG8_LDA(dst, b, h) do { _Pragma("unroll") for (int m = 0; m < 4; ++m) _Pragma("unroll") for (int k = 0; k < 2; ++k) dst[m][k] = *(const PG8_LAS bf16x8*)(lds + PG8_SA(b, h) + aoff + m * 2048 + k * 1024); } while (0)
; #define PG8_MMA(ai, bj, At, Bt) do { __builtin_amdgcn_s_setprio(1); _Pragma("unroll") for (int m = 0; m < 4; ++m) _Pragma("unroll") for (int n = 0; n < 2; ++n) _Pragma("unroll") for (int k = 0; k < 2; ++k) \
;         acc[ai][bj][m][n] = __builtin_amdgcn_mfma_f32_16x16x32_bf16(Bt[n][k], At[m][k], acc[ai][bj][m][n], 0, 0, 0); __builtin_amdgcn_s_setprio(0); } while (0)
; #define PG8_WAIT_V(n) asm volatile("s_waitcnt vmcnt(" #n ")" ::: "memory")
; #define PG8_WAIT_L(n) asm volatile("s_waitcnt lgkmcnt(" #n ")" ::: "memory")
; #define PG8_BAR __builtin_amdgcn_s_barrier()
; #define PG8_SCHED __builtin_amdgcn_sched_barrier(0)
; template <class Epi, class Sched, bool ALIGN_EPI = false, bool SP2 = false>
; __device__ __forceinline__ void gemm_phase(PG8_LAS unsigned char* lds, const Gemm g, const Sched& S, const Epi& E, const int tid) {
;     ...
;             PG8_LDA(At, 1, 1); PG8_STAGE(PG8_SB(1, 0), b3, voffB); PG8_STAGE(PG8_SB(1, 1), b3 + hstepB, voffB); PG8_STAGE(PG8_SA(1, 0), a3, voffA);
;             PG8_WAIT_V(8); PG8_WAIT_L(0); PG8_BAR; PG8_MMA(1, 0, At, B0); PG8_MMA(1, 1, At, B1); PG8_BAR; PG8_SCHED;
	s_add_i32 s28, s63, s33
	v_lshl_add_u64 v[206:207], v[206:207], 0, s[14:15]
	s_mov_b32 m0, s28
	ds_read_b128 v[182:185], v149 offset:49152
	ds_read_b128 v[186:189], v149 offset:50176
	ds_read_b128 v[190:193], v149 offset:51200
	ds_read_b128 v[194:197], v149 offset:52224
	ds_read_b128 v[198:201], v149 offset:53248
	ds_read_b128 v[202:205], v149 offset:54272
	ds_read_b128 v[210:213], v149 offset:55296
	ds_read_b128 v[214:217], v149 offset:56320
	global_load_lds_dwordx4 v[206:207], off
	s_add_i32 m0, s28, 0x2000
	s_add_u32 s28, s34, 0xb0080
	v_lshl_add_u64 v[206:207], v[218:219], 0, s[14:15]
	s_addc_u32 s29, s35, 0
	s_add_i32 s34, s64, s33
	global_load_lds_dwordx4 v[206:207], off
	v_lshl_add_u64 v[206:207], s[28:29], 0, v[130:131]
	s_mov_b32 m0, s34
	s_nop 0
	global_load_lds_dwordx4 v[206:207], off
	v_lshl_add_u64 v[206:207], s[28:29], 0, v[134:135]
	s_add_i32 m0, s34, 0x2000
	s_nop 0
	global_load_lds_dwordx4 v[206:207], off
	v_lshl_add_u64 v[206:207], v[220:221], 0, s[14:15]
	s_mov_b32 m0, s43
	s_nop 0
	global_load_lds_dwordx4 v[206:207], off
	v_lshl_add_u64 v[206:207], v[222:223], 0, s[14:15]
	s_mov_b32 m0, s44
	s_nop 0
	global_load_lds_dwordx4 v[206:207], off
	s_waitcnt vmcnt(8)
	s_waitcnt lgkmcnt(0)
	v_mfma_f32_16x16x32_bf16 v[60:63], v[150:153], v[182:185], v[60:63]
	v_mfma_f32_16x16x32_bf16 v[56:59], v[158:161], v[182:185], v[56:59]
	v_mfma_f32_16x16x32_bf16 v[52:55], v[150:153], v[190:193], v[52:55]
	v_mfma_f32_16x16x32_bf16 v[48:51], v[158:161], v[190:193], v[48:51]
	s_barrier
	s_setprio 1
	s_waitcnt lgkmcnt(0)
	v_mfma_f32_16x16x32_bf16 v[36:39], v[150:153], v[198:201], v[36:39]
	v_mfma_f32_16x16x32_bf16 v[32:35], v[158:161], v[198:201], v[32:35]
	v_mfma_f32_16x16x32_bf16 v[20:23], v[150:153], v[210:213], v[20:23]
	v_mfma_f32_16x16x32_bf16 v[16:19], v[158:161], v[210:213], v[16:19]
	v_mfma_f32_16x16x32_bf16 v[60:63], v[154:157], v[186:189], v[60:63]
	v_mfma_f32_16x16x32_bf16 v[56:59], v[162:165], v[186:189], v[56:59]
	v_mfma_f32_16x16x32_bf16 v[52:55], v[154:157], v[194:197], v[52:55]
	v_mfma_f32_16x16x32_bf16 v[48:51], v[162:165], v[194:197], v[48:51]
	v_mfma_f32_16x16x32_bf16 v[36:39], v[154:157], v[202:205], v[36:39]
	v_mfma_f32_16x16x32_bf16 v[32:35], v[162:165], v[202:205], v[32:35]
	v_mfma_f32_16x16x32_bf16 v[20:23], v[154:157], v[214:217], v[20:23]
	v_mfma_f32_16x16x32_bf16 v[16:19], v[162:165], v[214:217], v[16:19]
	s_setprio 0
	s_setprio 1
	v_mfma_f32_16x16x32_bf16 v[44:47], v[166:169], v[182:185], v[44:47]
	v_mfma_f32_16x16x32_bf16 v[40:43], v[174:177], v[182:185], v[40:43]
	v_mfma_f32_16x16x32_bf16 v[28:31], v[166:169], v[190:193], v[28:31]
	v_mfma_f32_16x16x32_bf16 v[24:27], v[174:177], v[190:193], v[24:27]
	v_mfma_f32_16x16x32_bf16 v[12:15], v[166:169], v[198:201], v[12:15]
	v_mfma_f32_16x16x32_bf16 v[8:11], v[174:177], v[198:201], v[8:11]
	v_mfma_f32_16x16x32_bf16 v[4:7], v[166:169], v[210:213], v[4:7]
	v_mfma_f32_16x16x32_bf16 v[0:3], v[174:177], v[210:213], v[0:3]
	v_mfma_f32_16x16x32_bf16 v[44:47], v[170:173], v[186:189], v[44:47]
	v_mfma_f32_16x16x32_bf16 v[40:43], v[178:181], v[186:189], v[40:43]
	v_mfma_f32_16x16x32_bf16 v[28:31], v[170:173], v[194:197], v[28:31]
	v_mfma_f32_16x16x32_bf16 v[24:27], v[178:181], v[194:197], v[24:27]
	v_mfma_f32_16x16x32_bf16 v[12:15], v[170:173], v[202:205], v[12:15]
	v_mfma_f32_16x16x32_bf16 v[8:11], v[178:181], v[202:205], v[8:11]
	v_mfma_f32_16x16x32_bf16 v[4:7], v[170:173], v[214:217], v[4:7]
	v_mfma_f32_16x16x32_bf16 v[0:3], v[178:181], v[214:217], v[0:3]
	s_setprio 0
	s_barrier
	s_add_i32 s62, s62, 2
	s_add_u32 s60, s60, 0x100
	s_addc_u32 s61, s61, 0
	s_cmp_gt_u32 s62, 41
	s_mov_b64 s[28:29], s[30:31]
	s_cbranch_scc0 .LBB0_2016
	s_and_b64 vcc, exec, s[16:17]
	s_cbranch_vccz .LBB0_2019
	s_barrier
